# repeat: MFMA blocks at byte phase 0 mod 8, redundant post-barrier lgkmcnt waits and mid-block setprio flips removed
# speedup vs baseline: 1.0054x; 1.0054x over previous
; #define PG8_STAGE(bufoff, gbase, voff) do { _Pragma("unroll") for (int _i = 0; _i < 2; ++_i) \
;         __builtin_amdgcn_global_load_lds((const unsigned*)((const char*)(gbase) + (voff)[_i]), (PG8_LAS unsigned*)(lds + (bufoff) + ldsw + _i * 8192), 16, 0, 0); } while (0)
; #define PG8_LDA(dst, b, h) do { _Pragma("unroll") for (int m = 0; m < 4; ++m) _Pragma("unroll") for (int k = 0; k < 2; ++k) dst[m][k] = *(const PG8_LAS bf16x8*)(lds + PG8_SA(b, h) + aoff + m * 2048 + k * 1024); } while (0)
; #define PG8_LDB(dst, b, h) do { _Pragma("unroll") for (int n = 0; n < 2; ++n) _Pragma("unroll") for (int k = 0; k < 2; ++k) dst[n][k] = *(const PG8_LAS bf16x8*)(lds + PG8_SB(b, h) + boff + n * 2048 + k * 1024); } while (0)
; #define PG8_MMA(ai, bj, At, Bt) do { __builtin_amdgcn_s_setprio(1); _Pragma("unroll") for (int m = 0; m < 4; ++m) _Pragma("unroll") for (int n = 0; n < 2; ++n) _Pragma("unroll") for (int k = 0; k < 2; ++k) \
;         acc[ai][bj][m][n] = __builtin_amdgcn_mfma_f32_16x16x32_bf16(Bt[n][k], At[m][k], acc[ai][bj][m][n], 0, 0, 0); __builtin_amdgcn_s_setprio(0); } while (0)
; #define PG8_WAIT_V(n) asm volatile("s_waitcnt vmcnt(" #n ")" ::: "memory")
; #define PG8_WAIT_L(n) asm volatile("s_waitcnt lgkmcnt(" #n ")" ::: "memory")
; #define PG8_BAR __builtin_amdgcn_s_barrier()
; #define PG8_SCHED __builtin_amdgcn_sched_barrier(0)
; template <class Epi, class Sched, bool ALIGN_EPI = false, bool SP2 = false>
; __device__ __forceinline__ void gemm_phase(PG8_LAS unsigned char* lds, const Gemm g, const Sched& S, const Epi& E) {
;     ...
;             const bool last = (t == nt - 2);
;             const char* a1 = cA + (size_t)(t + 1) * kstep;
;             const char* a2 = last ? nA : cA + (size_t)(t + 2) * kstep; const char* b2 = last ? nB : cB + (size_t)(t + 2) * kstep;
;             const char* a3 = a2 + kstep; const char* b3 = b2 + kstep;
;             if (last && has_next) S.a_ready(nxt);
;             if constexpr (SP2) {
;             PG8_LDB(B0, 0, 0); PG8_LDB(B1, 0, 1); PG8_SCHED; PG8_LDA(At, 0, 0); PG8_STAGE(PG8_SA(1, 1), a1 + hstep, voffA);
;             PG8_WAIT_V(8); PG8_WAIT_L(0); PG8_BAR; PG8_MMA(0, 0, At, B0); PG8_MMA(0, 1, At, B1); PG8_BAR; PG8_SCHED;
;             PG8_LDA(At, 0, 1); PG8_STAGE(PG8_SB(0, 0), b2, voffB); PG8_STAGE(PG8_SB(0, 1), b2 + hstep, voffB); PG8_STAGE(PG8_SA(0, 0), a2, voffA);
.LBB0_148:
	s_add_u32 s8, s6, 0xfff80080
	s_addc_u32 s9, s7, -1
	s_add_i32 s39, 0, 0x10000
	s_cmp_eq_u32 s38, 28
	s_cselect_b32 s31, s25, s9
	s_cselect_b32 s30, s34, s8
	s_cselect_b32 s9, s23, s37
	s_cselect_b32 s8, s35, s36
	s_add_i32 s58, 0, 0x14000
	v_add_u32_e32 v140, s39, v181
	v_add_u32_e32 v178, s58, v181
	ds_read_b128 v[128:131], v140
	ds_read_b128 v[132:135], v140 offset:1024
	ds_read_b128 v[136:139], v140 offset:2048
	ds_read_b128 v[140:143], v140 offset:3072
	ds_read_b128 v[174:177], v178
	ds_read_b128 v[184:187], v178 offset:1024
	ds_read_b128 v[198:201], v178 offset:2048
	ds_read_b128 v[202:205], v178 offset:3072
	v_lshl_add_u64 v[246:247], s[6:7], 0, v[154:155]
	s_add_i32 m0, s63, 0xc000
	ds_read_b128 v[206:209], v183
	ds_read_b128 v[210:213], v183 offset:1024
	ds_read_b128 v[214:217], v183 offset:2048
	ds_read_b128 v[218:221], v183 offset:3072
	ds_read_b128 v[222:225], v183 offset:4096
	ds_read_b128 v[226:229], v183 offset:5120
	ds_read_b128 v[238:241], v183 offset:6144
	ds_read_b128 v[242:245], v183 offset:7168
	global_load_lds_dwordx4 v[246:247], off
	v_lshl_add_u64 v[246:247], s[6:7], 0, v[156:157]
	s_add_i32 m0, s63, 0xe000
	s_nop 0
	global_load_lds_dwordx4 v[246:247], off
	s_waitcnt vmcnt(8)
	s_waitcnt lgkmcnt(0)
	s_barrier
	s_setprio 1
	v_mfma_f32_16x16x32_bf16 v[124:127], v[128:131], v[206:209], v[124:127]
	v_mfma_f32_16x16x32_bf16 v[120:123], v[136:139], v[206:209], v[120:123]
	v_mfma_f32_16x16x32_bf16 v[108:111], v[128:131], v[214:217], v[108:111]
	v_mfma_f32_16x16x32_bf16 v[104:107], v[136:139], v[214:217], v[104:107]
	v_mfma_f32_16x16x32_bf16 v[92:95], v[128:131], v[222:225], v[92:95]
	v_mfma_f32_16x16x32_bf16 v[88:91], v[136:139], v[222:225], v[88:91]
	v_mfma_f32_16x16x32_bf16 v[76:79], v[128:131], v[238:241], v[76:79]
	v_mfma_f32_16x16x32_bf16 v[72:75], v[136:139], v[238:241], v[72:75]
	v_mfma_f32_16x16x32_bf16 v[124:127], v[132:135], v[210:213], v[124:127]
	v_mfma_f32_16x16x32_bf16 v[120:123], v[140:143], v[210:213], v[120:123]
	v_mfma_f32_16x16x32_bf16 v[108:111], v[132:135], v[218:221], v[108:111]
	v_mfma_f32_16x16x32_bf16 v[104:107], v[140:143], v[218:221], v[104:107]
	v_mfma_f32_16x16x32_bf16 v[92:95], v[132:135], v[226:229], v[92:95]
	v_mfma_f32_16x16x32_bf16 v[88:91], v[140:143], v[226:229], v[88:91]
	v_mfma_f32_16x16x32_bf16 v[76:79], v[132:135], v[242:245], v[76:79]
	v_mfma_f32_16x16x32_bf16 v[72:75], v[140:143], v[242:245], v[72:75]
	v_mfma_f32_16x16x32_bf16 v[116:119], v[174:177], v[206:209], v[116:119]
	v_mfma_f32_16x16x32_bf16 v[112:115], v[198:201], v[206:209], v[112:115]
	v_mfma_f32_16x16x32_bf16 v[100:103], v[174:177], v[214:217], v[100:103]
	v_mfma_f32_16x16x32_bf16 v[96:99], v[198:201], v[214:217], v[96:99]
	v_mfma_f32_16x16x32_bf16 v[84:87], v[174:177], v[222:225], v[84:87]
	v_mfma_f32_16x16x32_bf16 v[80:83], v[198:201], v[222:225], v[80:83]
	v_mfma_f32_16x16x32_bf16 v[68:71], v[174:177], v[238:241], v[68:71]
	v_mfma_f32_16x16x32_bf16 v[64:67], v[198:201], v[238:241], v[64:67]
	v_mfma_f32_16x16x32_bf16 v[116:119], v[184:187], v[210:213], v[116:119]
	v_mfma_f32_16x16x32_bf16 v[112:115], v[202:205], v[210:213], v[112:115]
	v_mfma_f32_16x16x32_bf16 v[100:103], v[184:187], v[218:221], v[100:103]
	v_mfma_f32_16x16x32_bf16 v[96:99], v[202:205], v[218:221], v[96:99]
	v_mfma_f32_16x16x32_bf16 v[84:87], v[184:187], v[226:229], v[84:87]
	v_mfma_f32_16x16x32_bf16 v[80:83], v[202:205], v[226:229], v[80:83]
	v_mfma_f32_16x16x32_bf16 v[68:71], v[184:187], v[242:245], v[68:71]
	v_mfma_f32_16x16x32_bf16 v[64:67], v[202:205], v[242:245], v[64:67]
	s_setprio 0
	s_barrier
	s_add_i32 s39, s39, s45
	v_lshl_add_u64 v[246:247], s[8:9], 0, v[148:149]
	s_mov_b32 m0, s39
	ds_read_b128 v[206:209], v183 offset:16384
	ds_read_b128 v[210:213], v183 offset:17408
	ds_read_b128 v[214:217], v183 offset:18432
	ds_read_b128 v[218:221], v183 offset:19456
	ds_read_b128 v[222:225], v183 offset:20480
	ds_read_b128 v[226:229], v183 offset:21504
	ds_read_b128 v[238:241], v183 offset:22528
	ds_read_b128 v[242:245], v183 offset:23552
	global_load_lds_dwordx4 v[246:247], off
	s_add_i32 m0, s39, 0x2000
	s_add_u32 s88, s8, 0x80000
	v_lshl_add_u64 v[248:249], s[8:9], 0, v[144:145]
	s_addc_u32 s89, s9, 0
	s_add_i32 s39, s58, s45
	global_load_lds_dwordx4 v[248:249], off
	v_lshl_add_u64 v[250:251], s[88:89], 0, v[148:149]
	s_mov_b32 m0, s39
	v_lshl_add_u64 v[252:253], s[30:31], 0, v[146:147]
	global_load_lds_dwordx4 v[250:251], off
	v_lshl_add_u64 v[250:251], s[88:89], 0, v[144:145]
	s_add_i32 m0, s39, 0x2000
	s_nop 0
	global_load_lds_dwordx4 v[250:251], off
	v_lshl_add_u64 v[250:251], s[30:31], 0, v[150:151]
	s_mov_b32 m0, s63
	s_nop 0
	global_load_lds_dwordx4 v[250:251], off
	s_mov_b32 m0, s66
	s_nop 0
	global_load_lds_dwordx4 v[252:253], off
	s_waitcnt vmcnt(8)
	s_waitcnt lgkmcnt(0)
	s_barrier
; #define PG8_STAGE(bufoff, gbase, voff) do { _Pragma("unroll") for (int _i = 0; _i < 2; ++_i) \
;         __builtin_amdgcn_global_load_lds((const unsigned*)((const char*)(gbase) + (voff)[_i]), (PG8_LAS unsigned*)(lds + (bufoff) + ldsw + _i * 8192), 16, 0, 0); } while (0)
; #define PG8_LDA(dst, b, h) do { _Pragma("unroll") for (int m = 0; m < 4; ++m) _Pragma("unroll") for (int k = 0; k < 2; ++k) dst[m][k] = *(const PG8_LAS bf16x8*)(lds + PG8_SA(b, h) + aoff + m * 2048 + k * 1024); } while (0)
; #define PG8_LDB(dst, b, h) do { _Pragma("unroll") for (int n = 0; n < 2; ++n) _Pragma("unroll") for (int k = 0; k < 2; ++k) dst[n][k] = *(const PG8_LAS bf16x8*)(lds + PG8_SB(b, h) + boff + n * 2048 + k * 1024); } while (0)
; #define PG8_MMA(ai, bj, At, Bt) do { __builtin_amdgcn_s_setprio(1); _Pragma("unroll") for (int m = 0; m < 4; ++m) _Pragma("unroll") for (int n = 0; n < 2; ++n) _Pragma("unroll") for (int k = 0; k < 2; ++k) \
;         acc[ai][bj][m][n] = __builtin_amdgcn_mfma_f32_16x16x32_bf16(Bt[n][k], At[m][k], acc[ai][bj][m][n], 0, 0, 0); __builtin_amdgcn_s_setprio(0); } while (0)
; #define PG8_WAIT_V(n) asm volatile("s_waitcnt vmcnt(" #n ")" ::: "memory")
; #define PG8_WAIT_L(n) asm volatile("s_waitcnt lgkmcnt(" #n ")" ::: "memory")
; #define PG8_BAR __builtin_amdgcn_s_barrier()
; #define PG8_SCHED __builtin_amdgcn_sched_barrier(0)
; template <class Epi, class Sched, bool ALIGN_EPI = false, bool SP2 = false>
; __device__ __forceinline__ void gemm_phase(PG8_LAS unsigned char* lds, const Gemm g, const Sched& S, const Epi& E) {
;     ...
;             PG8_WAIT_V(8); PG8_WAIT_L(0); PG8_BAR; PG8_MMA(1, 0, At, B0); PG8_MMA(1, 1, At, B1); PG8_BAR; PG8_SCHED;
;             PG8_LDB(B0, 1, 0); PG8_LDB(B1, 1, 1); PG8_SCHED; PG8_LDA(At, 1, 0); PG8_STAGE(PG8_SA(0, 1), a2 + hstep, voffA);
;             PG8_WAIT_V(8); PG8_WAIT_L(0); PG8_BAR; PG8_MMA(0, 0, At, B0); PG8_MMA(0, 1, At, B1); PG8_BAR; PG8_SCHED;
	s_setprio 1
	v_mfma_f32_16x16x32_bf16 v[60:63], v[128:131], v[206:209], v[60:63]
	v_mfma_f32_16x16x32_bf16 v[56:59], v[136:139], v[206:209], v[56:59]
	v_mfma_f32_16x16x32_bf16 v[44:47], v[128:131], v[214:217], v[44:47]
	v_mfma_f32_16x16x32_bf16 v[40:43], v[136:139], v[214:217], v[40:43]
	v_mfma_f32_16x16x32_bf16 v[28:31], v[128:131], v[222:225], v[28:31]
	v_mfma_f32_16x16x32_bf16 v[24:27], v[136:139], v[222:225], v[24:27]
	v_mfma_f32_16x16x32_bf16 v[12:15], v[128:131], v[238:241], v[12:15]
	v_mfma_f32_16x16x32_bf16 v[8:11], v[136:139], v[238:241], v[8:11]
	v_mfma_f32_16x16x32_bf16 v[60:63], v[132:135], v[210:213], v[60:63]
	v_mfma_f32_16x16x32_bf16 v[56:59], v[140:143], v[210:213], v[56:59]
	v_mfma_f32_16x16x32_bf16 v[44:47], v[132:135], v[218:221], v[44:47]
	v_mfma_f32_16x16x32_bf16 v[40:43], v[140:143], v[218:221], v[40:43]
	v_mfma_f32_16x16x32_bf16 v[28:31], v[132:135], v[226:229], v[28:31]
	v_mfma_f32_16x16x32_bf16 v[24:27], v[140:143], v[226:229], v[24:27]
	v_mfma_f32_16x16x32_bf16 v[12:15], v[132:135], v[242:245], v[12:15]
	v_mfma_f32_16x16x32_bf16 v[8:11], v[140:143], v[242:245], v[8:11]
	v_mfma_f32_16x16x32_bf16 v[52:55], v[174:177], v[206:209], v[52:55]
	v_mfma_f32_16x16x32_bf16 v[48:51], v[198:201], v[206:209], v[48:51]
	v_mfma_f32_16x16x32_bf16 v[36:39], v[174:177], v[214:217], v[36:39]
	v_mfma_f32_16x16x32_bf16 v[32:35], v[198:201], v[214:217], v[32:35]
	v_mfma_f32_16x16x32_bf16 v[20:23], v[174:177], v[222:225], v[20:23]
	v_mfma_f32_16x16x32_bf16 v[16:19], v[198:201], v[222:225], v[16:19]
	v_mfma_f32_16x16x32_bf16 v[4:7], v[174:177], v[238:241], v[4:7]
	v_mfma_f32_16x16x32_bf16 v[0:3], v[198:201], v[238:241], v[0:3]
	v_mfma_f32_16x16x32_bf16 v[52:55], v[184:187], v[210:213], v[52:55]
	v_mfma_f32_16x16x32_bf16 v[48:51], v[202:205], v[210:213], v[48:51]
	v_mfma_f32_16x16x32_bf16 v[36:39], v[184:187], v[218:221], v[36:39]
	v_mfma_f32_16x16x32_bf16 v[32:35], v[202:205], v[218:221], v[32:35]
	v_mfma_f32_16x16x32_bf16 v[20:23], v[184:187], v[226:229], v[20:23]
	v_mfma_f32_16x16x32_bf16 v[16:19], v[202:205], v[226:229], v[16:19]
	v_mfma_f32_16x16x32_bf16 v[4:7], v[184:187], v[242:245], v[4:7]
	v_mfma_f32_16x16x32_bf16 v[0:3], v[202:205], v[242:245], v[0:3]
	s_setprio 0
	s_barrier
	s_add_i32 s39, 0, 0x18000
	s_add_i32 s58, 0, 0x1c000
	v_add_u32_e32 v140, s39, v181
	v_add_u32_e32 v178, s58, v181
	ds_read_b128 v[128:131], v140
	ds_read_b128 v[132:135], v140 offset:1024
	ds_read_b128 v[136:139], v140 offset:2048
	ds_read_b128 v[140:143], v140 offset:3072
	ds_read_b128 v[174:177], v178
	ds_read_b128 v[184:187], v178 offset:1024
	ds_read_b128 v[198:201], v178 offset:2048
	ds_read_b128 v[202:205], v178 offset:3072
	s_add_u32 s30, s30, 0x80000
	s_addc_u32 s31, s31, 0
	s_mov_b32 m0, s67
	v_lshl_add_u64 v[232:233], s[30:31], 0, v[150:151]
	ds_read_b128 v[206:209], v183 offset:32768
	ds_read_b128 v[210:213], v183 offset:33792
	ds_read_b128 v[214:217], v183 offset:34816
	ds_read_b128 v[218:221], v183 offset:35840
	ds_read_b128 v[222:225], v183 offset:36864
	ds_read_b128 v[226:229], v183 offset:37888
	ds_read_b128 v[238:241], v183 offset:38912
	ds_read_b128 v[242:245], v183 offset:39936
	global_load_lds_dwordx4 v[232:233], off
	v_lshl_add_u64 v[232:233], s[30:31], 0, v[146:147]
	s_mov_b32 m0, s72
	s_nop 0
	global_load_lds_dwordx4 v[232:233], off
	s_waitcnt vmcnt(8)
	s_waitcnt lgkmcnt(0)
	s_barrier
	s_setprio 1
	v_mfma_f32_16x16x32_bf16 v[124:127], v[128:131], v[206:209], v[124:127]
	v_mfma_f32_16x16x32_bf16 v[120:123], v[136:139], v[206:209], v[120:123]
	v_mfma_f32_16x16x32_bf16 v[108:111], v[128:131], v[214:217], v[108:111]
	v_mfma_f32_16x16x32_bf16 v[104:107], v[136:139], v[214:217], v[104:107]
	v_mfma_f32_16x16x32_bf16 v[92:95], v[128:131], v[222:225], v[92:95]
	v_mfma_f32_16x16x32_bf16 v[88:91], v[136:139], v[222:225], v[88:91]
	v_mfma_f32_16x16x32_bf16 v[76:79], v[128:131], v[238:241], v[76:79]
	v_mfma_f32_16x16x32_bf16 v[72:75], v[136:139], v[238:241], v[72:75]
	v_mfma_f32_16x16x32_bf16 v[124:127], v[132:135], v[210:213], v[124:127]
	v_mfma_f32_16x16x32_bf16 v[120:123], v[140:143], v[210:213], v[120:123]
	v_mfma_f32_16x16x32_bf16 v[108:111], v[132:135], v[218:221], v[108:111]
	v_mfma_f32_16x16x32_bf16 v[104:107], v[140:143], v[218:221], v[104:107]
	v_mfma_f32_16x16x32_bf16 v[92:95], v[132:135], v[226:229], v[92:95]
	v_mfma_f32_16x16x32_bf16 v[88:91], v[140:143], v[226:229], v[88:91]
	v_mfma_f32_16x16x32_bf16 v[76:79], v[132:135], v[242:245], v[76:79]
	v_mfma_f32_16x16x32_bf16 v[72:75], v[140:143], v[242:245], v[72:75]
	v_mfma_f32_16x16x32_bf16 v[116:119], v[174:177], v[206:209], v[116:119]
	v_mfma_f32_16x16x32_bf16 v[112:115], v[198:201], v[206:209], v[112:115]
	v_mfma_f32_16x16x32_bf16 v[100:103], v[174:177], v[214:217], v[100:103]
	v_mfma_f32_16x16x32_bf16 v[96:99], v[198:201], v[214:217], v[96:99]
	v_mfma_f32_16x16x32_bf16 v[84:87], v[174:177], v[222:225], v[84:87]
	v_mfma_f32_16x16x32_bf16 v[80:83], v[198:201], v[222:225], v[80:83]
	v_mfma_f32_16x16x32_bf16 v[68:71], v[174:177], v[238:241], v[68:71]
	v_mfma_f32_16x16x32_bf16 v[64:67], v[198:201], v[238:241], v[64:67]
	v_mfma_f32_16x16x32_bf16 v[116:119], v[184:187], v[210:213], v[116:119]
	v_mfma_f32_16x16x32_bf16 v[112:115], v[202:205], v[210:213], v[112:115]
	v_mfma_f32_16x16x32_bf16 v[100:103], v[184:187], v[218:221], v[100:103]
	v_mfma_f32_16x16x32_bf16 v[96:99], v[202:205], v[218:221], v[96:99]
	v_mfma_f32_16x16x32_bf16 v[84:87], v[184:187], v[226:229], v[84:87]
	v_mfma_f32_16x16x32_bf16 v[80:83], v[202:205], v[226:229], v[80:83]
	v_mfma_f32_16x16x32_bf16 v[68:71], v[184:187], v[242:245], v[68:71]
	v_mfma_f32_16x16x32_bf16 v[64:67], v[202:205], v[242:245], v[64:67]
	s_setprio 0
	s_barrier
; #define PG8_STAGE(bufoff, gbase, voff) do { _Pragma("unroll") for (int _i = 0; _i < 2; ++_i) \
;         __builtin_amdgcn_global_load_lds((const unsigned*)((const char*)(gbase) + (voff)[_i]), (PG8_LAS unsigned*)(lds + (bufoff) + ldsw + _i * 8192), 16, 0, 0); } while (0)
; #define PG8_LDA(dst, b, h) do { _Pragma("unroll") for (int m = 0; m < 4; ++m) _Pragma("unroll") for (int k = 0; k < 2; ++k) dst[m][k] = *(const PG8_LAS bf16x8*)(lds + PG8_SA(b, h) + aoff + m * 2048 + k * 1024); } while (0)
; #define PG8_MMA(ai, bj, At, Bt) do { __builtin_amdgcn_s_setprio(1); _Pragma("unroll") for (int m = 0; m < 4; ++m) _Pragma("unroll") for (int n = 0; n < 2; ++n) _Pragma("unroll") for (int k = 0; k < 2; ++k) \
;         acc[ai][bj][m][n] = __builtin_amdgcn_mfma_f32_16x16x32_bf16(Bt[n][k], At[m][k], acc[ai][bj][m][n], 0, 0, 0); __builtin_amdgcn_s_setprio(0); } while (0)
; #define PG8_WAIT_V(n) asm volatile("s_waitcnt vmcnt(" #n ")" ::: "memory")
; #define PG8_WAIT_L(n) asm volatile("s_waitcnt lgkmcnt(" #n ")" ::: "memory")
; #define PG8_BAR __builtin_amdgcn_s_barrier()
; #define PG8_SCHED __builtin_amdgcn_sched_barrier(0)
; template <class Epi, class Sched, bool ALIGN_EPI = false, bool SP2 = false>
; __device__ __forceinline__ void gemm_phase(PG8_LAS unsigned char* lds, const Gemm g, const Sched& S, const Epi& E) {
;     ...
;             PG8_LDA(At, 1, 1); PG8_STAGE(PG8_SB(1, 0), b3, voffB); PG8_STAGE(PG8_SB(1, 1), b3 + hstep, voffB); PG8_STAGE(PG8_SA(1, 0), a3, voffA);
;             PG8_WAIT_V(8); PG8_WAIT_L(0); PG8_BAR; PG8_MMA(1, 0, At, B0); PG8_MMA(1, 1, At, B1); PG8_BAR; PG8_SCHED;
	s_add_i32 s30, s39, s45
	v_lshl_add_u64 v[232:233], v[246:247], 0, s[78:79]
	s_mov_b32 m0, s30
	ds_read_b128 v[206:209], v183 offset:49152
	ds_read_b128 v[210:213], v183 offset:50176
	ds_read_b128 v[214:217], v183 offset:51200
	ds_read_b128 v[218:221], v183 offset:52224
	ds_read_b128 v[222:225], v183 offset:53248
	ds_read_b128 v[226:229], v183 offset:54272
	ds_read_b128 v[238:241], v183 offset:55296
	ds_read_b128 v[242:245], v183 offset:56320
	global_load_lds_dwordx4 v[232:233], off
	s_add_i32 m0, s30, 0x2000
	s_add_u32 s8, s8, 0x80080
	v_lshl_add_u64 v[232:233], v[248:249], 0, s[78:79]
	s_addc_u32 s9, s9, 0
	s_add_i32 s30, s58, s45
	global_load_lds_dwordx4 v[232:233], off
	v_lshl_add_u64 v[232:233], s[8:9], 0, v[148:149]
	s_mov_b32 m0, s30
	s_nop 0
	global_load_lds_dwordx4 v[232:233], off
	v_lshl_add_u64 v[232:233], s[8:9], 0, v[144:145]
	s_add_i32 m0, s30, 0x2000
	s_nop 0
	global_load_lds_dwordx4 v[232:233], off
	v_lshl_add_u64 v[232:233], v[250:251], 0, s[78:79]
	s_mov_b32 m0, s73
	s_nop 0
	global_load_lds_dwordx4 v[232:233], off
	v_lshl_add_u64 v[232:233], v[252:253], 0, s[78:79]
	s_mov_b32 m0, s74
	s_nop 0
	global_load_lds_dwordx4 v[232:233], off
	s_nop 0
	s_waitcnt vmcnt(8)
	s_waitcnt lgkmcnt(0)
	s_barrier
	s_setprio 1
	v_mfma_f32_16x16x32_bf16 v[60:63], v[128:131], v[206:209], v[60:63]
	v_mfma_f32_16x16x32_bf16 v[56:59], v[136:139], v[206:209], v[56:59]
	v_mfma_f32_16x16x32_bf16 v[44:47], v[128:131], v[214:217], v[44:47]
	v_mfma_f32_16x16x32_bf16 v[40:43], v[136:139], v[214:217], v[40:43]
	v_mfma_f32_16x16x32_bf16 v[28:31], v[128:131], v[222:225], v[28:31]
	v_mfma_f32_16x16x32_bf16 v[24:27], v[136:139], v[222:225], v[24:27]
	v_mfma_f32_16x16x32_bf16 v[12:15], v[128:131], v[238:241], v[12:15]
	v_mfma_f32_16x16x32_bf16 v[8:11], v[136:139], v[238:241], v[8:11]
	v_mfma_f32_16x16x32_bf16 v[60:63], v[132:135], v[210:213], v[60:63]
	v_mfma_f32_16x16x32_bf16 v[56:59], v[140:143], v[210:213], v[56:59]
	v_mfma_f32_16x16x32_bf16 v[44:47], v[132:135], v[218:221], v[44:47]
	v_mfma_f32_16x16x32_bf16 v[40:43], v[140:143], v[218:221], v[40:43]
	v_mfma_f32_16x16x32_bf16 v[28:31], v[132:135], v[226:229], v[28:31]
	v_mfma_f32_16x16x32_bf16 v[24:27], v[140:143], v[226:229], v[24:27]
	v_mfma_f32_16x16x32_bf16 v[12:15], v[132:135], v[242:245], v[12:15]
	v_mfma_f32_16x16x32_bf16 v[8:11], v[140:143], v[242:245], v[8:11]
	v_mfma_f32_16x16x32_bf16 v[52:55], v[174:177], v[206:209], v[52:55]
	v_mfma_f32_16x16x32_bf16 v[48:51], v[198:201], v[206:209], v[48:51]
	v_mfma_f32_16x16x32_bf16 v[36:39], v[174:177], v[214:217], v[36:39]
	v_mfma_f32_16x16x32_bf16 v[32:35], v[198:201], v[214:217], v[32:35]
	v_mfma_f32_16x16x32_bf16 v[20:23], v[174:177], v[222:225], v[20:23]
	v_mfma_f32_16x16x32_bf16 v[16:19], v[198:201], v[222:225], v[16:19]
	v_mfma_f32_16x16x32_bf16 v[4:7], v[174:177], v[238:241], v[4:7]
	v_mfma_f32_16x16x32_bf16 v[0:3], v[198:201], v[238:241], v[0:3]
	v_mfma_f32_16x16x32_bf16 v[52:55], v[184:187], v[210:213], v[52:55]
	v_mfma_f32_16x16x32_bf16 v[48:51], v[202:205], v[210:213], v[48:51]
	v_mfma_f32_16x16x32_bf16 v[36:39], v[184:187], v[218:221], v[36:39]
	v_mfma_f32_16x16x32_bf16 v[32:35], v[202:205], v[218:221], v[32:35]
	v_mfma_f32_16x16x32_bf16 v[20:23], v[184:187], v[226:229], v[20:23]
	v_mfma_f32_16x16x32_bf16 v[16:19], v[202:205], v[226:229], v[16:19]
	v_mfma_f32_16x16x32_bf16 v[4:7], v[184:187], v[242:245], v[4:7]
	v_mfma_f32_16x16x32_bf16 v[0:3], v[202:205], v[242:245], v[0:3]
	s_setprio 0
	s_barrier
	s_add_i32 s38, s38, 2
	s_add_u32 s6, s6, 0x100
	s_addc_u32 s7, s7, 0
	s_add_u32 s36, s36, 0x100
	s_addc_u32 s37, s37, 0
	s_cmp_gt_u32 s38, 29
	s_cbranch_scc0 .LBB0_148
	s_and_b64 vcc, exec, s[20:21]
	s_cbranch_vccz .LBB0_151
	s_barrier

; #define PG8_STAGE(bufoff, gbase, voff) do { _Pragma("unroll") for (int _i = 0; _i < 2; ++_i) \
;         __builtin_amdgcn_global_load_lds((const unsigned*)((const char*)(gbase) + (voff)[_i]), (PG8_LAS unsigned*)(lds + (bufoff) + ldsw + _i * 8192), 16, 0, 0); } while (0)
; #define PG8_LDA(dst, b, h) do { _Pragma("unroll") for (int m = 0; m < 4; ++m) _Pragma("unroll") for (int k = 0; k < 2; ++k) dst[m][k] = *(const PG8_LAS bf16x8*)(lds + PG8_SA(b, h) + aoff + m * 2048 + k * 1024); } while (0)
; #define PG8_LDB(dst, b, h) do { _Pragma("unroll") for (int n = 0; n < 2; ++n) _Pragma("unroll") for (int k = 0; k < 2; ++k) dst[n][k] = *(const PG8_LAS bf16x8*)(lds + PG8_SB(b, h) + boff + n * 2048 + k * 1024); } while (0)
; #define PG8_MMA(ai, bj, At, Bt) do { __builtin_amdgcn_s_setprio(1); _Pragma("unroll") for (int m = 0; m < 4; ++m) _Pragma("unroll") for (int n = 0; n < 2; ++n) _Pragma("unroll") for (int k = 0; k < 2; ++k) \
;         acc[ai][bj][m][n] = __builtin_amdgcn_mfma_f32_16x16x32_bf16(Bt[n][k], At[m][k], acc[ai][bj][m][n], 0, 0, 0); __builtin_amdgcn_s_setprio(0); } while (0)
; #define PG8_WAIT_V(n) asm volatile("s_waitcnt vmcnt(" #n ")" ::: "memory")
; #define PG8_WAIT_L(n) asm volatile("s_waitcnt lgkmcnt(" #n ")" ::: "memory")
; #define PG8_BAR __builtin_amdgcn_s_barrier()
; #define PG8_SCHED __builtin_amdgcn_sched_barrier(0)
; template <class Epi, class Sched, bool ALIGN_EPI = false, bool SP2 = false>
; __device__ __forceinline__ void gemm_phase(PG8_LAS unsigned char* lds, const Gemm g, const Sched& S, const Epi& E) {
;     ...
;             const bool last = (t == nt - 2);
;             const char* a1 = cA + (size_t)(t + 1) * kstep;
;             const char* a2 = last ? nA : cA + (size_t)(t + 2) * kstep; const char* b2 = last ? nB : cB + (size_t)(t + 2) * kstep;
;             const char* a3 = a2 + kstep; const char* b3 = b2 + kstep;
;             if (last && has_next) S.a_ready(nxt);
;             if constexpr (SP2) {
;             PG8_LDB(B0, 0, 0); PG8_LDB(B1, 0, 1); PG8_SCHED; PG8_LDA(At, 0, 0); PG8_STAGE(PG8_SA(1, 1), a1 + hstep, voffA);
;             PG8_WAIT_V(8); PG8_WAIT_L(0); PG8_BAR; PG8_MMA(0, 0, At, B0); PG8_MMA(0, 1, At, B1); PG8_BAR; PG8_SCHED;
;             PG8_LDA(At, 0, 1); PG8_STAGE(PG8_SB(0, 0), b2, voffB); PG8_STAGE(PG8_SB(0, 1), b2 + hstep, voffB); PG8_STAGE(PG8_SA(0, 0), a2, voffA);
.LBB0_424:
	s_add_u32 s8, s6, 0xfffc0080
	s_addc_u32 s9, s7, -1
	s_add_i32 s60, 0, 0x10000
	s_cmp_eq_u32 s58, 12
	s_cselect_b32 s25, s17, s9
	s_cselect_b32 s24, s38, s8
	s_cselect_b32 s9, s19, s52
	s_cselect_b32 s8, s39, s45
	s_add_i32 s62, 0, 0x14000
	v_add_u32_e32 v140, s60, v201
	v_add_u32_e32 v156, s62, v201
	ds_read_b128 v[128:131], v140
	ds_read_b128 v[132:135], v140 offset:1024
	ds_read_b128 v[136:139], v140 offset:2048
	ds_read_b128 v[140:143], v140 offset:3072
	ds_read_b128 v[144:147], v156
	ds_read_b128 v[148:151], v156 offset:1024
	ds_read_b128 v[152:155], v156 offset:2048
	ds_read_b128 v[156:159], v156 offset:3072
	v_lshl_add_u64 v[198:199], s[6:7], 0, v[168:169]
	s_add_i32 m0, s31, 0xc000
	ds_read_b128 v[172:175], v203
	ds_read_b128 v[176:179], v203 offset:1024
	ds_read_b128 v[180:183], v203 offset:2048
	ds_read_b128 v[184:187], v203 offset:3072
	ds_read_b128 v[204:207], v203 offset:4096
	ds_read_b128 v[208:211], v203 offset:5120
	ds_read_b128 v[212:215], v203 offset:6144
	ds_read_b128 v[216:219], v203 offset:7168
	global_load_lds_dwordx4 v[198:199], off
	v_lshl_add_u64 v[198:199], s[6:7], 0, v[170:171]
	s_add_i32 m0, s31, 0xe000
	s_nop 0
	global_load_lds_dwordx4 v[198:199], off
	s_waitcnt vmcnt(8)
	s_waitcnt lgkmcnt(0)
	s_barrier
	s_setprio 1
	v_mfma_f32_16x16x32_bf16 v[124:127], v[128:131], v[172:175], v[124:127]
	v_mfma_f32_16x16x32_bf16 v[120:123], v[136:139], v[172:175], v[120:123]
	v_mfma_f32_16x16x32_bf16 v[116:119], v[128:131], v[180:183], v[116:119]
	v_mfma_f32_16x16x32_bf16 v[112:115], v[136:139], v[180:183], v[112:115]
	v_mfma_f32_16x16x32_bf16 v[108:111], v[128:131], v[204:207], v[108:111]
	v_mfma_f32_16x16x32_bf16 v[104:107], v[136:139], v[204:207], v[104:107]
	v_mfma_f32_16x16x32_bf16 v[100:103], v[128:131], v[212:215], v[100:103]
	v_mfma_f32_16x16x32_bf16 v[96:99], v[136:139], v[212:215], v[96:99]
	v_mfma_f32_16x16x32_bf16 v[124:127], v[132:135], v[176:179], v[124:127]
	v_mfma_f32_16x16x32_bf16 v[120:123], v[140:143], v[176:179], v[120:123]
	v_mfma_f32_16x16x32_bf16 v[116:119], v[132:135], v[184:187], v[116:119]
	v_mfma_f32_16x16x32_bf16 v[112:115], v[140:143], v[184:187], v[112:115]
	v_mfma_f32_16x16x32_bf16 v[108:111], v[132:135], v[208:211], v[108:111]
	v_mfma_f32_16x16x32_bf16 v[104:107], v[140:143], v[208:211], v[104:107]
	v_mfma_f32_16x16x32_bf16 v[100:103], v[132:135], v[216:219], v[100:103]
	v_mfma_f32_16x16x32_bf16 v[96:99], v[140:143], v[216:219], v[96:99]
	v_mfma_f32_16x16x32_bf16 v[92:95], v[144:147], v[172:175], v[92:95]
	v_mfma_f32_16x16x32_bf16 v[88:91], v[152:155], v[172:175], v[88:91]
	v_mfma_f32_16x16x32_bf16 v[84:87], v[144:147], v[180:183], v[84:87]
	v_mfma_f32_16x16x32_bf16 v[80:83], v[152:155], v[180:183], v[80:83]
	v_mfma_f32_16x16x32_bf16 v[76:79], v[144:147], v[204:207], v[76:79]
	v_mfma_f32_16x16x32_bf16 v[72:75], v[152:155], v[204:207], v[72:75]
	v_mfma_f32_16x16x32_bf16 v[68:71], v[144:147], v[212:215], v[68:71]
	v_mfma_f32_16x16x32_bf16 v[64:67], v[152:155], v[212:215], v[64:67]
	v_mfma_f32_16x16x32_bf16 v[92:95], v[148:151], v[176:179], v[92:95]
	v_mfma_f32_16x16x32_bf16 v[88:91], v[156:159], v[176:179], v[88:91]
	v_mfma_f32_16x16x32_bf16 v[84:87], v[148:151], v[184:187], v[84:87]
	v_mfma_f32_16x16x32_bf16 v[80:83], v[156:159], v[184:187], v[80:83]
	v_mfma_f32_16x16x32_bf16 v[76:79], v[148:151], v[208:211], v[76:79]
	v_mfma_f32_16x16x32_bf16 v[72:75], v[156:159], v[208:211], v[72:75]
	v_mfma_f32_16x16x32_bf16 v[68:71], v[148:151], v[216:219], v[68:71]
	v_mfma_f32_16x16x32_bf16 v[64:67], v[156:159], v[216:219], v[64:67]
	s_setprio 0
	s_barrier
	s_add_i32 s60, s60, s30
	v_lshl_add_u64 v[198:199], s[8:9], 0, v[164:165]
	s_mov_b32 m0, s60
	ds_read_b128 v[172:175], v203 offset:16384
	ds_read_b128 v[176:179], v203 offset:17408
	ds_read_b128 v[180:183], v203 offset:18432
	ds_read_b128 v[184:187], v203 offset:19456
	ds_read_b128 v[204:207], v203 offset:20480
	ds_read_b128 v[208:211], v203 offset:21504
	ds_read_b128 v[212:215], v203 offset:22528
	ds_read_b128 v[216:219], v203 offset:23552
	global_load_lds_dwordx4 v[198:199], off
	s_add_i32 m0, s60, 0x2000
	s_add_u32 s60, s8, 0x40000
	v_lshl_add_u64 v[220:221], s[8:9], 0, v[160:161]
	s_addc_u32 s61, s9, 0
	s_add_i32 s62, s62, s30
	global_load_lds_dwordx4 v[220:221], off
	v_lshl_add_u64 v[222:223], s[60:61], 0, v[164:165]
	s_mov_b32 m0, s62
	v_lshl_add_u64 v[224:225], s[24:25], 0, v[162:163]
	global_load_lds_dwordx4 v[222:223], off
	v_lshl_add_u64 v[222:223], s[60:61], 0, v[160:161]
	s_add_i32 m0, s62, 0x2000
	s_nop 0
	global_load_lds_dwordx4 v[222:223], off
	v_lshl_add_u64 v[222:223], s[24:25], 0, v[166:167]
	s_mov_b32 m0, s31
	s_nop 0
	global_load_lds_dwordx4 v[222:223], off
	s_mov_b32 m0, s34
	s_nop 0
	global_load_lds_dwordx4 v[224:225], off
	s_waitcnt vmcnt(8)
	s_waitcnt lgkmcnt(0)
	s_barrier
; #define PG8_STAGE(bufoff, gbase, voff) do { _Pragma("unroll") for (int _i = 0; _i < 2; ++_i) \
;         __builtin_amdgcn_global_load_lds((const unsigned*)((const char*)(gbase) + (voff)[_i]), (PG8_LAS unsigned*)(lds + (bufoff) + ldsw + _i * 8192), 16, 0, 0); } while (0)
; #define PG8_LDA(dst, b, h) do { _Pragma("unroll") for (int m = 0; m < 4; ++m) _Pragma("unroll") for (int k = 0; k < 2; ++k) dst[m][k] = *(const PG8_LAS bf16x8*)(lds + PG8_SA(b, h) + aoff + m * 2048 + k * 1024); } while (0)
; #define PG8_LDB(dst, b, h) do { _Pragma("unroll") for (int n = 0; n < 2; ++n) _Pragma("unroll") for (int k = 0; k < 2; ++k) dst[n][k] = *(const PG8_LAS bf16x8*)(lds + PG8_SB(b, h) + boff + n * 2048 + k * 1024); } while (0)
; #define PG8_MMA(ai, bj, At, Bt) do { __builtin_amdgcn_s_setprio(1); _Pragma("unroll") for (int m = 0; m < 4; ++m) _Pragma("unroll") for (int n = 0; n < 2; ++n) _Pragma("unroll") for (int k = 0; k < 2; ++k) \
;         acc[ai][bj][m][n] = __builtin_amdgcn_mfma_f32_16x16x32_bf16(Bt[n][k], At[m][k], acc[ai][bj][m][n], 0, 0, 0); __builtin_amdgcn_s_setprio(0); } while (0)
; #define PG8_WAIT_V(n) asm volatile("s_waitcnt vmcnt(" #n ")" ::: "memory")
; #define PG8_WAIT_L(n) asm volatile("s_waitcnt lgkmcnt(" #n ")" ::: "memory")
; #define PG8_BAR __builtin_amdgcn_s_barrier()
; #define PG8_SCHED __builtin_amdgcn_sched_barrier(0)
; template <class Epi, class Sched, bool ALIGN_EPI = false, bool SP2 = false>
; __device__ __forceinline__ void gemm_phase(PG8_LAS unsigned char* lds, const Gemm g, const Sched& S, const Epi& E) {
;     ...
;             PG8_WAIT_V(8); PG8_WAIT_L(0); PG8_BAR; PG8_MMA(1, 0, At, B0); PG8_MMA(1, 1, At, B1); PG8_BAR; PG8_SCHED;
;             PG8_LDB(B0, 1, 0); PG8_LDB(B1, 1, 1); PG8_SCHED; PG8_LDA(At, 1, 0); PG8_STAGE(PG8_SA(0, 1), a2 + hstep, voffA);
;             PG8_WAIT_V(8); PG8_WAIT_L(0); PG8_BAR; PG8_MMA(0, 0, At, B0); PG8_MMA(0, 1, At, B1); PG8_BAR; PG8_SCHED;
	s_setprio 1
	v_mfma_f32_16x16x32_bf16 v[60:63], v[128:131], v[172:175], v[60:63]
	v_mfma_f32_16x16x32_bf16 v[56:59], v[136:139], v[172:175], v[56:59]
	v_mfma_f32_16x16x32_bf16 v[52:55], v[128:131], v[180:183], v[52:55]
	v_mfma_f32_16x16x32_bf16 v[48:51], v[136:139], v[180:183], v[48:51]
	v_mfma_f32_16x16x32_bf16 v[44:47], v[128:131], v[204:207], v[44:47]
	v_mfma_f32_16x16x32_bf16 v[40:43], v[136:139], v[204:207], v[40:43]
	v_mfma_f32_16x16x32_bf16 v[36:39], v[128:131], v[212:215], v[36:39]
	v_mfma_f32_16x16x32_bf16 v[32:35], v[136:139], v[212:215], v[32:35]
	v_mfma_f32_16x16x32_bf16 v[60:63], v[132:135], v[176:179], v[60:63]
	v_mfma_f32_16x16x32_bf16 v[56:59], v[140:143], v[176:179], v[56:59]
	v_mfma_f32_16x16x32_bf16 v[52:55], v[132:135], v[184:187], v[52:55]
	v_mfma_f32_16x16x32_bf16 v[48:51], v[140:143], v[184:187], v[48:51]
	v_mfma_f32_16x16x32_bf16 v[44:47], v[132:135], v[208:211], v[44:47]
	v_mfma_f32_16x16x32_bf16 v[40:43], v[140:143], v[208:211], v[40:43]
	v_mfma_f32_16x16x32_bf16 v[36:39], v[132:135], v[216:219], v[36:39]
	v_mfma_f32_16x16x32_bf16 v[32:35], v[140:143], v[216:219], v[32:35]
	v_mfma_f32_16x16x32_bf16 v[28:31], v[144:147], v[172:175], v[28:31]
	v_mfma_f32_16x16x32_bf16 v[24:27], v[152:155], v[172:175], v[24:27]
	v_mfma_f32_16x16x32_bf16 v[20:23], v[144:147], v[180:183], v[20:23]
	v_mfma_f32_16x16x32_bf16 v[16:19], v[152:155], v[180:183], v[16:19]
	v_mfma_f32_16x16x32_bf16 v[12:15], v[144:147], v[204:207], v[12:15]
	v_mfma_f32_16x16x32_bf16 v[8:11], v[152:155], v[204:207], v[8:11]
	v_mfma_f32_16x16x32_bf16 v[4:7], v[144:147], v[212:215], v[4:7]
	v_mfma_f32_16x16x32_bf16 v[0:3], v[152:155], v[212:215], v[0:3]
	v_mfma_f32_16x16x32_bf16 v[28:31], v[148:151], v[176:179], v[28:31]
	v_mfma_f32_16x16x32_bf16 v[24:27], v[156:159], v[176:179], v[24:27]
	v_mfma_f32_16x16x32_bf16 v[20:23], v[148:151], v[184:187], v[20:23]
	v_mfma_f32_16x16x32_bf16 v[16:19], v[156:159], v[184:187], v[16:19]
	v_mfma_f32_16x16x32_bf16 v[12:15], v[148:151], v[208:211], v[12:15]
	v_mfma_f32_16x16x32_bf16 v[8:11], v[156:159], v[208:211], v[8:11]
	v_mfma_f32_16x16x32_bf16 v[4:7], v[148:151], v[216:219], v[4:7]
	v_mfma_f32_16x16x32_bf16 v[0:3], v[156:159], v[216:219], v[0:3]
	s_setprio 0
	s_barrier
	s_add_i32 s60, 0, 0x18000
	s_add_i32 s61, 0, 0x1c000
	v_add_u32_e32 v140, s60, v201
	v_add_u32_e32 v156, s61, v201
	ds_read_b128 v[128:131], v140
	ds_read_b128 v[132:135], v140 offset:1024
	ds_read_b128 v[136:139], v140 offset:2048
	ds_read_b128 v[140:143], v140 offset:3072
	ds_read_b128 v[144:147], v156
	ds_read_b128 v[148:151], v156 offset:1024
	ds_read_b128 v[152:155], v156 offset:2048
	ds_read_b128 v[156:159], v156 offset:3072
	s_add_u32 s24, s24, 0x40000
	s_addc_u32 s25, s25, 0
	s_mov_b32 m0, s35
	v_lshl_add_u64 v[226:227], s[24:25], 0, v[166:167]
	ds_read_b128 v[172:175], v203 offset:32768
	ds_read_b128 v[176:179], v203 offset:33792
	ds_read_b128 v[180:183], v203 offset:34816
	ds_read_b128 v[184:187], v203 offset:35840
	ds_read_b128 v[204:207], v203 offset:36864
	ds_read_b128 v[208:211], v203 offset:37888
	ds_read_b128 v[212:215], v203 offset:38912
	ds_read_b128 v[216:219], v203 offset:39936
	global_load_lds_dwordx4 v[226:227], off
	v_lshl_add_u64 v[226:227], s[24:25], 0, v[162:163]
	s_mov_b32 m0, s36
	s_nop 0
	global_load_lds_dwordx4 v[226:227], off
	s_waitcnt vmcnt(8)
	s_waitcnt lgkmcnt(0)
	s_barrier
	s_setprio 1
	v_mfma_f32_16x16x32_bf16 v[124:127], v[128:131], v[172:175], v[124:127]
	v_mfma_f32_16x16x32_bf16 v[120:123], v[136:139], v[172:175], v[120:123]
	v_mfma_f32_16x16x32_bf16 v[116:119], v[128:131], v[180:183], v[116:119]
	v_mfma_f32_16x16x32_bf16 v[112:115], v[136:139], v[180:183], v[112:115]
	v_mfma_f32_16x16x32_bf16 v[108:111], v[128:131], v[204:207], v[108:111]
	v_mfma_f32_16x16x32_bf16 v[104:107], v[136:139], v[204:207], v[104:107]
	v_mfma_f32_16x16x32_bf16 v[100:103], v[128:131], v[212:215], v[100:103]
	v_mfma_f32_16x16x32_bf16 v[96:99], v[136:139], v[212:215], v[96:99]
	v_mfma_f32_16x16x32_bf16 v[124:127], v[132:135], v[176:179], v[124:127]
	v_mfma_f32_16x16x32_bf16 v[120:123], v[140:143], v[176:179], v[120:123]
	v_mfma_f32_16x16x32_bf16 v[116:119], v[132:135], v[184:187], v[116:119]
	v_mfma_f32_16x16x32_bf16 v[112:115], v[140:143], v[184:187], v[112:115]
	v_mfma_f32_16x16x32_bf16 v[108:111], v[132:135], v[208:211], v[108:111]
	v_mfma_f32_16x16x32_bf16 v[104:107], v[140:143], v[208:211], v[104:107]
	v_mfma_f32_16x16x32_bf16 v[100:103], v[132:135], v[216:219], v[100:103]
	v_mfma_f32_16x16x32_bf16 v[96:99], v[140:143], v[216:219], v[96:99]
	v_mfma_f32_16x16x32_bf16 v[92:95], v[144:147], v[172:175], v[92:95]
	v_mfma_f32_16x16x32_bf16 v[88:91], v[152:155], v[172:175], v[88:91]
	v_mfma_f32_16x16x32_bf16 v[84:87], v[144:147], v[180:183], v[84:87]
	v_mfma_f32_16x16x32_bf16 v[80:83], v[152:155], v[180:183], v[80:83]
	v_mfma_f32_16x16x32_bf16 v[76:79], v[144:147], v[204:207], v[76:79]
	v_mfma_f32_16x16x32_bf16 v[72:75], v[152:155], v[204:207], v[72:75]
	v_mfma_f32_16x16x32_bf16 v[68:71], v[144:147], v[212:215], v[68:71]
	v_mfma_f32_16x16x32_bf16 v[64:67], v[152:155], v[212:215], v[64:67]
	v_mfma_f32_16x16x32_bf16 v[92:95], v[148:151], v[176:179], v[92:95]
	v_mfma_f32_16x16x32_bf16 v[88:91], v[156:159], v[176:179], v[88:91]
	v_mfma_f32_16x16x32_bf16 v[84:87], v[148:151], v[184:187], v[84:87]
	v_mfma_f32_16x16x32_bf16 v[80:83], v[156:159], v[184:187], v[80:83]
	v_mfma_f32_16x16x32_bf16 v[76:79], v[148:151], v[208:211], v[76:79]
	v_mfma_f32_16x16x32_bf16 v[72:75], v[156:159], v[208:211], v[72:75]
	v_mfma_f32_16x16x32_bf16 v[68:71], v[148:151], v[216:219], v[68:71]
	v_mfma_f32_16x16x32_bf16 v[64:67], v[156:159], v[216:219], v[64:67]
	s_setprio 0
	s_barrier
; #define PG8_STAGE(bufoff, gbase, voff) do { _Pragma("unroll") for (int _i = 0; _i < 2; ++_i) \
;         __builtin_amdgcn_global_load_lds((const unsigned*)((const char*)(gbase) + (voff)[_i]), (PG8_LAS unsigned*)(lds + (bufoff) + ldsw + _i * 8192), 16, 0, 0); } while (0)
; #define PG8_LDA(dst, b, h) do { _Pragma("unroll") for (int m = 0; m < 4; ++m) _Pragma("unroll") for (int k = 0; k < 2; ++k) dst[m][k] = *(const PG8_LAS bf16x8*)(lds + PG8_SA(b, h) + aoff + m * 2048 + k * 1024); } while (0)
; #define PG8_MMA(ai, bj, At, Bt) do { __builtin_amdgcn_s_setprio(1); _Pragma("unroll") for (int m = 0; m < 4; ++m) _Pragma("unroll") for (int n = 0; n < 2; ++n) _Pragma("unroll") for (int k = 0; k < 2; ++k) \
;         acc[ai][bj][m][n] = __builtin_amdgcn_mfma_f32_16x16x32_bf16(Bt[n][k], At[m][k], acc[ai][bj][m][n], 0, 0, 0); __builtin_amdgcn_s_setprio(0); } while (0)
; #define PG8_WAIT_V(n) asm volatile("s_waitcnt vmcnt(" #n ")" ::: "memory")
; #define PG8_WAIT_L(n) asm volatile("s_waitcnt lgkmcnt(" #n ")" ::: "memory")
; #define PG8_BAR __builtin_amdgcn_s_barrier()
; #define PG8_SCHED __builtin_amdgcn_sched_barrier(0)
; template <class Epi, class Sched, bool ALIGN_EPI = false, bool SP2 = false>
; __device__ __forceinline__ void gemm_phase(PG8_LAS unsigned char* lds, const Gemm g, const Sched& S, const Epi& E) {
;     ...
;             PG8_LDA(At, 1, 1); PG8_STAGE(PG8_SB(1, 0), b3, voffB); PG8_STAGE(PG8_SB(1, 1), b3 + hstep, voffB); PG8_STAGE(PG8_SA(1, 0), a3, voffA);
;             PG8_WAIT_V(8); PG8_WAIT_L(0); PG8_BAR; PG8_MMA(1, 0, At, B0); PG8_MMA(1, 1, At, B1); PG8_BAR; PG8_SCHED;
	s_add_i32 s24, s60, s30
	v_lshl_add_u64 v[198:199], v[198:199], 0, s[78:79]
	s_mov_b32 m0, s24
	ds_read_b128 v[172:175], v203 offset:49152
	ds_read_b128 v[176:179], v203 offset:50176
	ds_read_b128 v[180:183], v203 offset:51200
	ds_read_b128 v[184:187], v203 offset:52224
	ds_read_b128 v[204:207], v203 offset:53248
	ds_read_b128 v[208:211], v203 offset:54272
	ds_read_b128 v[212:215], v203 offset:55296
	ds_read_b128 v[216:219], v203 offset:56320
	global_load_lds_dwordx4 v[198:199], off
	s_add_i32 m0, s24, 0x2000
	s_add_u32 s8, s8, 0x40080
	v_lshl_add_u64 v[198:199], v[220:221], 0, s[78:79]
	s_addc_u32 s9, s9, 0
	s_add_i32 s24, s61, s30
	global_load_lds_dwordx4 v[198:199], off
	v_lshl_add_u64 v[198:199], s[8:9], 0, v[164:165]
	s_mov_b32 m0, s24
	s_nop 0
	global_load_lds_dwordx4 v[198:199], off
	v_lshl_add_u64 v[198:199], s[8:9], 0, v[160:161]
	s_add_i32 m0, s24, 0x2000
	s_nop 0
	global_load_lds_dwordx4 v[198:199], off
	v_lshl_add_u64 v[198:199], v[222:223], 0, s[78:79]
	s_mov_b32 m0, s37
	s_nop 0
	global_load_lds_dwordx4 v[198:199], off
	v_lshl_add_u64 v[198:199], v[224:225], 0, s[78:79]
	s_mov_b32 m0, s40
	s_nop 0
	global_load_lds_dwordx4 v[198:199], off
	s_nop 0
	s_waitcnt vmcnt(8)
	s_waitcnt lgkmcnt(0)
	s_barrier
	s_setprio 1
	v_mfma_f32_16x16x32_bf16 v[60:63], v[128:131], v[172:175], v[60:63]
	v_mfma_f32_16x16x32_bf16 v[56:59], v[136:139], v[172:175], v[56:59]
	v_mfma_f32_16x16x32_bf16 v[52:55], v[128:131], v[180:183], v[52:55]
	v_mfma_f32_16x16x32_bf16 v[48:51], v[136:139], v[180:183], v[48:51]
	v_mfma_f32_16x16x32_bf16 v[44:47], v[128:131], v[204:207], v[44:47]
	v_mfma_f32_16x16x32_bf16 v[40:43], v[136:139], v[204:207], v[40:43]
	v_mfma_f32_16x16x32_bf16 v[36:39], v[128:131], v[212:215], v[36:39]
	v_mfma_f32_16x16x32_bf16 v[32:35], v[136:139], v[212:215], v[32:35]
	v_mfma_f32_16x16x32_bf16 v[60:63], v[132:135], v[176:179], v[60:63]
	v_mfma_f32_16x16x32_bf16 v[56:59], v[140:143], v[176:179], v[56:59]
	v_mfma_f32_16x16x32_bf16 v[52:55], v[132:135], v[184:187], v[52:55]
	v_mfma_f32_16x16x32_bf16 v[48:51], v[140:143], v[184:187], v[48:51]
	v_mfma_f32_16x16x32_bf16 v[44:47], v[132:135], v[208:211], v[44:47]
	v_mfma_f32_16x16x32_bf16 v[40:43], v[140:143], v[208:211], v[40:43]
	v_mfma_f32_16x16x32_bf16 v[36:39], v[132:135], v[216:219], v[36:39]
	v_mfma_f32_16x16x32_bf16 v[32:35], v[140:143], v[216:219], v[32:35]
	v_mfma_f32_16x16x32_bf16 v[28:31], v[144:147], v[172:175], v[28:31]
	v_mfma_f32_16x16x32_bf16 v[24:27], v[152:155], v[172:175], v[24:27]
	v_mfma_f32_16x16x32_bf16 v[20:23], v[144:147], v[180:183], v[20:23]
	v_mfma_f32_16x16x32_bf16 v[16:19], v[152:155], v[180:183], v[16:19]
	v_mfma_f32_16x16x32_bf16 v[12:15], v[144:147], v[204:207], v[12:15]
	v_mfma_f32_16x16x32_bf16 v[8:11], v[152:155], v[204:207], v[8:11]
	v_mfma_f32_16x16x32_bf16 v[4:7], v[144:147], v[212:215], v[4:7]
	v_mfma_f32_16x16x32_bf16 v[0:3], v[152:155], v[212:215], v[0:3]
	v_mfma_f32_16x16x32_bf16 v[28:31], v[148:151], v[176:179], v[28:31]
	v_mfma_f32_16x16x32_bf16 v[24:27], v[156:159], v[176:179], v[24:27]
	v_mfma_f32_16x16x32_bf16 v[20:23], v[148:151], v[184:187], v[20:23]
	v_mfma_f32_16x16x32_bf16 v[16:19], v[156:159], v[184:187], v[16:19]
	v_mfma_f32_16x16x32_bf16 v[12:15], v[148:151], v[208:211], v[12:15]
	v_mfma_f32_16x16x32_bf16 v[8:11], v[156:159], v[208:211], v[8:11]
	v_mfma_f32_16x16x32_bf16 v[4:7], v[148:151], v[216:219], v[4:7]
	v_mfma_f32_16x16x32_bf16 v[0:3], v[156:159], v[216:219], v[0:3]
	s_setprio 0
	s_barrier
	s_add_i32 s58, s58, 2
	s_add_u32 s6, s6, 0x100
	s_addc_u32 s7, s7, 0
	s_add_u32 s45, s45, 0x100
	s_addc_u32 s52, s52, 0
	s_cmp_gt_u32 s58, 13
	s_cbranch_scc0 .LBB0_424
	s_and_b64 vcc, exec, s[14:15]
	s_cbranch_vccz .LBB0_427
	s_barrier

; #define PG8_STAGE(bufoff, gbase, voff) do { _Pragma("unroll") for (int _i = 0; _i < 2; ++_i) \
;         __builtin_amdgcn_global_load_lds((const unsigned*)((const char*)(gbase) + (voff)[_i]), (PG8_LAS unsigned*)(lds + (bufoff) + ldsw + _i * 8192), 16, 0, 0); } while (0)
; #define PG8_LDA(dst, b, h) do { _Pragma("unroll") for (int m = 0; m < 4; ++m) _Pragma("unroll") for (int k = 0; k < 2; ++k) dst[m][k] = *(const PG8_LAS bf16x8*)(lds + PG8_SA(b, h) + aoff + m * 2048 + k * 1024); } while (0)
; #define PG8_LDB(dst, b, h) do { _Pragma("unroll") for (int n = 0; n < 2; ++n) _Pragma("unroll") for (int k = 0; k < 2; ++k) dst[n][k] = *(const PG8_LAS bf16x8*)(lds + PG8_SB(b, h) + boff + n * 2048 + k * 1024); } while (0)
; #define PG8_MMA(ai, bj, At, Bt) do { __builtin_amdgcn_s_setprio(1); _Pragma("unroll") for (int m = 0; m < 4; ++m) _Pragma("unroll") for (int n = 0; n < 2; ++n) _Pragma("unroll") for (int k = 0; k < 2; ++k) \
;         acc[ai][bj][m][n] = __builtin_amdgcn_mfma_f32_16x16x32_bf16(Bt[n][k], At[m][k], acc[ai][bj][m][n], 0, 0, 0); __builtin_amdgcn_s_setprio(0); } while (0)
; #define PG8_WAIT_V(n) asm volatile("s_waitcnt vmcnt(" #n ")" ::: "memory")
; #define PG8_WAIT_L(n) asm volatile("s_waitcnt lgkmcnt(" #n ")" ::: "memory")
; #define PG8_BAR __builtin_amdgcn_s_barrier()
; #define PG8_SCHED __builtin_amdgcn_sched_barrier(0)
; template <class Epi, class Sched, bool ALIGN_EPI = false, bool SP2 = false>
; __device__ __forceinline__ void gemm_phase(PG8_LAS unsigned char* lds, const Gemm g, const Sched& S, const Epi& E) {
;     ...
;             const bool last = (t == nt - 2);
;             const char* a1 = cA + (size_t)(t + 1) * kstep;
;             const char* a2 = last ? nA : cA + (size_t)(t + 2) * kstep; const char* b2 = last ? nB : cB + (size_t)(t + 2) * kstep;
;             const char* a3 = a2 + kstep; const char* b3 = b2 + kstep;
;             if (last && has_next) S.a_ready(nxt);
;             if constexpr (SP2) {
;             PG8_LDB(B0, 0, 0); PG8_LDB(B1, 0, 1); PG8_SCHED; PG8_LDA(At, 0, 0); PG8_STAGE(PG8_SA(1, 1), a1 + hstep, voffA);
;             PG8_WAIT_V(8); PG8_WAIT_L(0); PG8_BAR; PG8_MMA(0, 0, At, B0); PG8_MMA(0, 1, At, B1); PG8_BAR; PG8_SCHED;
;             PG8_LDA(At, 0, 1); PG8_STAGE(PG8_SB(0, 0), b2, voffB); PG8_STAGE(PG8_SB(0, 1), b2 + hstep, voffB); PG8_STAGE(PG8_SA(0, 0), a2, voffA);
.LBB0_596:
	s_add_u32 s26, s24, 0xfff80080
	s_addc_u32 s27, s25, -1
	s_add_i32 s60, 0, 0x10000
	s_cmp_eq_u32 s67, 28
	s_cselect_b32 s29, s19, s27
	s_cselect_b32 s28, s58, s26
	s_cselect_b32 s27, s17, s66
	s_cselect_b32 s26, s62, s63
	s_add_i32 s68, 0, 0x14000
	v_add_u32_e32 v124, s60, v239
	v_add_u32_e32 v148, s68, v239
	ds_read_b128 v[112:115], v124
	ds_read_b128 v[116:119], v124 offset:1024
	ds_read_b128 v[120:123], v124 offset:2048
	ds_read_b128 v[124:127], v124 offset:3072
	ds_read_b128 v[132:135], v148
	ds_read_b128 v[140:143], v148 offset:1024
	ds_read_b128 v[144:147], v148 offset:2048
	ds_read_b128 v[148:151], v148 offset:3072
	v_lshl_add_u64 v[212:213], s[24:25], 0, v[204:205]
	s_add_i32 m0, s36, 0xc000
	ds_read_b128 v[156:159], v241
	ds_read_b128 v[164:167], v241 offset:1024
	ds_read_b128 v[168:171], v241 offset:2048
	ds_read_b128 v[172:175], v241 offset:3072
	ds_read_b128 v[176:179], v241 offset:4096
	ds_read_b128 v[180:183], v241 offset:5120
	ds_read_b128 v[184:187], v241 offset:6144
	ds_read_b128 v[208:211], v241 offset:7168
	global_load_lds_dwordx4 v[212:213], off
	v_lshl_add_u64 v[212:213], s[24:25], 0, v[206:207]
	s_add_i32 m0, s36, 0xe000
	s_nop 0
	global_load_lds_dwordx4 v[212:213], off
	s_waitcnt vmcnt(8)
	s_waitcnt lgkmcnt(0)
	s_barrier
	s_setprio 1
	v_mfma_f32_16x16x32_bf16 v[160:163], v[112:115], v[156:159], v[160:163]
	v_mfma_f32_16x16x32_bf16 v[152:155], v[120:123], v[156:159], v[152:155]
	v_mfma_f32_16x16x32_bf16 v[108:111], v[112:115], v[168:171], v[108:111]
	v_mfma_f32_16x16x32_bf16 v[104:107], v[120:123], v[168:171], v[104:107]
	v_mfma_f32_16x16x32_bf16 v[92:95], v[112:115], v[176:179], v[92:95]
	v_mfma_f32_16x16x32_bf16 v[88:91], v[120:123], v[176:179], v[88:91]
	v_mfma_f32_16x16x32_bf16 v[76:79], v[112:115], v[184:187], v[76:79]
	v_mfma_f32_16x16x32_bf16 v[72:75], v[120:123], v[184:187], v[72:75]
	v_mfma_f32_16x16x32_bf16 v[160:163], v[116:119], v[164:167], v[160:163]
	v_mfma_f32_16x16x32_bf16 v[152:155], v[124:127], v[164:167], v[152:155]
	v_mfma_f32_16x16x32_bf16 v[108:111], v[116:119], v[172:175], v[108:111]
	v_mfma_f32_16x16x32_bf16 v[104:107], v[124:127], v[172:175], v[104:107]
	v_mfma_f32_16x16x32_bf16 v[92:95], v[116:119], v[180:183], v[92:95]
	v_mfma_f32_16x16x32_bf16 v[88:91], v[124:127], v[180:183], v[88:91]
	v_mfma_f32_16x16x32_bf16 v[76:79], v[116:119], v[208:211], v[76:79]
	v_mfma_f32_16x16x32_bf16 v[72:75], v[124:127], v[208:211], v[72:75]
	v_mfma_f32_16x16x32_bf16 v[136:139], v[132:135], v[156:159], v[136:139]
	v_mfma_f32_16x16x32_bf16 v[128:131], v[144:147], v[156:159], v[128:131]
	v_mfma_f32_16x16x32_bf16 v[100:103], v[132:135], v[168:171], v[100:103]
	v_mfma_f32_16x16x32_bf16 v[96:99], v[144:147], v[168:171], v[96:99]
	v_mfma_f32_16x16x32_bf16 v[84:87], v[132:135], v[176:179], v[84:87]
	v_mfma_f32_16x16x32_bf16 v[80:83], v[144:147], v[176:179], v[80:83]
	v_mfma_f32_16x16x32_bf16 v[68:71], v[132:135], v[184:187], v[68:71]
	v_mfma_f32_16x16x32_bf16 v[64:67], v[144:147], v[184:187], v[64:67]
	v_mfma_f32_16x16x32_bf16 v[136:139], v[140:143], v[164:167], v[136:139]
	v_mfma_f32_16x16x32_bf16 v[128:131], v[148:151], v[164:167], v[128:131]
	v_mfma_f32_16x16x32_bf16 v[100:103], v[140:143], v[172:175], v[100:103]
	v_mfma_f32_16x16x32_bf16 v[96:99], v[148:151], v[172:175], v[96:99]
	v_mfma_f32_16x16x32_bf16 v[84:87], v[140:143], v[180:183], v[84:87]
	v_mfma_f32_16x16x32_bf16 v[80:83], v[148:151], v[180:183], v[80:83]
	v_mfma_f32_16x16x32_bf16 v[68:71], v[140:143], v[208:211], v[68:71]
	v_mfma_f32_16x16x32_bf16 v[64:67], v[148:151], v[208:211], v[64:67]
	s_setprio 0
	s_barrier
	s_add_i32 s60, s60, s35
	v_lshl_add_u64 v[212:213], s[26:27], 0, v[188:189]
	s_mov_b32 m0, s60
	ds_read_b128 v[156:159], v241 offset:16384
	ds_read_b128 v[164:167], v241 offset:17408
	ds_read_b128 v[168:171], v241 offset:18432
	ds_read_b128 v[172:175], v241 offset:19456
	ds_read_b128 v[176:179], v241 offset:20480
	ds_read_b128 v[180:183], v241 offset:21504
	ds_read_b128 v[184:187], v241 offset:22528
	ds_read_b128 v[208:211], v241 offset:23552
	global_load_lds_dwordx4 v[212:213], off
	s_add_i32 m0, s60, 0x2000
	s_add_u32 s60, s26, 0x80000
	v_lshl_add_u64 v[214:215], s[26:27], 0, v[198:199]
	s_addc_u32 s61, s27, 0
	s_add_i32 s68, s68, s35
	global_load_lds_dwordx4 v[214:215], off
	v_lshl_add_u64 v[216:217], s[60:61], 0, v[188:189]
	s_mov_b32 m0, s68
	v_lshl_add_u64 v[218:219], s[28:29], 0, v[200:201]
	global_load_lds_dwordx4 v[216:217], off
	v_lshl_add_u64 v[216:217], s[60:61], 0, v[198:199]
	s_add_i32 m0, s68, 0x2000
	s_nop 0
	global_load_lds_dwordx4 v[216:217], off
	v_lshl_add_u64 v[216:217], s[28:29], 0, v[202:203]
	s_mov_b32 m0, s36
	s_nop 0
	global_load_lds_dwordx4 v[216:217], off
	s_mov_b32 m0, s37
	s_nop 0
	global_load_lds_dwordx4 v[218:219], off
	s_waitcnt vmcnt(8)
	s_waitcnt lgkmcnt(0)
	s_barrier
; #define PG8_STAGE(bufoff, gbase, voff) do { _Pragma("unroll") for (int _i = 0; _i < 2; ++_i) \
;         __builtin_amdgcn_global_load_lds((const unsigned*)((const char*)(gbase) + (voff)[_i]), (PG8_LAS unsigned*)(lds + (bufoff) + ldsw + _i * 8192), 16, 0, 0); } while (0)
; #define PG8_LDA(dst, b, h) do { _Pragma("unroll") for (int m = 0; m < 4; ++m) _Pragma("unroll") for (int k = 0; k < 2; ++k) dst[m][k] = *(const PG8_LAS bf16x8*)(lds + PG8_SA(b, h) + aoff + m * 2048 + k * 1024); } while (0)
; #define PG8_LDB(dst, b, h) do { _Pragma("unroll") for (int n = 0; n < 2; ++n) _Pragma("unroll") for (int k = 0; k < 2; ++k) dst[n][k] = *(const PG8_LAS bf16x8*)(lds + PG8_SB(b, h) + boff + n * 2048 + k * 1024); } while (0)
; #define PG8_MMA(ai, bj, At, Bt) do { __builtin_amdgcn_s_setprio(1); _Pragma("unroll") for (int m = 0; m < 4; ++m) _Pragma("unroll") for (int n = 0; n < 2; ++n) _Pragma("unroll") for (int k = 0; k < 2; ++k) \
;         acc[ai][bj][m][n] = __builtin_amdgcn_mfma_f32_16x16x32_bf16(Bt[n][k], At[m][k], acc[ai][bj][m][n], 0, 0, 0); __builtin_amdgcn_s_setprio(0); } while (0)
; #define PG8_WAIT_V(n) asm volatile("s_waitcnt vmcnt(" #n ")" ::: "memory")
; #define PG8_WAIT_L(n) asm volatile("s_waitcnt lgkmcnt(" #n ")" ::: "memory")
; #define PG8_BAR __builtin_amdgcn_s_barrier()
; #define PG8_SCHED __builtin_amdgcn_sched_barrier(0)
; template <class Epi, class Sched, bool ALIGN_EPI = false, bool SP2 = false>
; __device__ __forceinline__ void gemm_phase(PG8_LAS unsigned char* lds, const Gemm g, const Sched& S, const Epi& E) {
;     ...
;             PG8_WAIT_V(8); PG8_WAIT_L(0); PG8_BAR; PG8_MMA(1, 0, At, B0); PG8_MMA(1, 1, At, B1); PG8_BAR; PG8_SCHED;
;             PG8_LDB(B0, 1, 0); PG8_LDB(B1, 1, 1); PG8_SCHED; PG8_LDA(At, 1, 0); PG8_STAGE(PG8_SA(0, 1), a2 + hstep, voffA);
;             PG8_WAIT_V(8); PG8_WAIT_L(0); PG8_BAR; PG8_MMA(0, 0, At, B0); PG8_MMA(0, 1, At, B1); PG8_BAR; PG8_SCHED;
	s_setprio 1
	v_mfma_f32_16x16x32_bf16 v[60:63], v[112:115], v[156:159], v[60:63]
	v_mfma_f32_16x16x32_bf16 v[56:59], v[120:123], v[156:159], v[56:59]
	v_mfma_f32_16x16x32_bf16 v[44:47], v[112:115], v[168:171], v[44:47]
	v_mfma_f32_16x16x32_bf16 v[40:43], v[120:123], v[168:171], v[40:43]
	v_mfma_f32_16x16x32_bf16 v[28:31], v[112:115], v[176:179], v[28:31]
	v_mfma_f32_16x16x32_bf16 v[24:27], v[120:123], v[176:179], v[24:27]
	v_mfma_f32_16x16x32_bf16 v[12:15], v[112:115], v[184:187], v[12:15]
	v_mfma_f32_16x16x32_bf16 v[8:11], v[120:123], v[184:187], v[8:11]
	v_mfma_f32_16x16x32_bf16 v[60:63], v[116:119], v[164:167], v[60:63]
	v_mfma_f32_16x16x32_bf16 v[56:59], v[124:127], v[164:167], v[56:59]
	v_mfma_f32_16x16x32_bf16 v[44:47], v[116:119], v[172:175], v[44:47]
	v_mfma_f32_16x16x32_bf16 v[40:43], v[124:127], v[172:175], v[40:43]
	v_mfma_f32_16x16x32_bf16 v[28:31], v[116:119], v[180:183], v[28:31]
	v_mfma_f32_16x16x32_bf16 v[24:27], v[124:127], v[180:183], v[24:27]
	v_mfma_f32_16x16x32_bf16 v[12:15], v[116:119], v[208:211], v[12:15]
	v_mfma_f32_16x16x32_bf16 v[8:11], v[124:127], v[208:211], v[8:11]
	v_mfma_f32_16x16x32_bf16 v[52:55], v[132:135], v[156:159], v[52:55]
	v_mfma_f32_16x16x32_bf16 v[48:51], v[144:147], v[156:159], v[48:51]
	v_mfma_f32_16x16x32_bf16 v[36:39], v[132:135], v[168:171], v[36:39]
	v_mfma_f32_16x16x32_bf16 v[32:35], v[144:147], v[168:171], v[32:35]
	v_mfma_f32_16x16x32_bf16 v[20:23], v[132:135], v[176:179], v[20:23]
	v_mfma_f32_16x16x32_bf16 v[16:19], v[144:147], v[176:179], v[16:19]
	v_mfma_f32_16x16x32_bf16 v[4:7], v[132:135], v[184:187], v[4:7]
	v_mfma_f32_16x16x32_bf16 v[0:3], v[144:147], v[184:187], v[0:3]
	v_mfma_f32_16x16x32_bf16 v[52:55], v[140:143], v[164:167], v[52:55]
	v_mfma_f32_16x16x32_bf16 v[48:51], v[148:151], v[164:167], v[48:51]
	v_mfma_f32_16x16x32_bf16 v[36:39], v[140:143], v[172:175], v[36:39]
	v_mfma_f32_16x16x32_bf16 v[32:35], v[148:151], v[172:175], v[32:35]
	v_mfma_f32_16x16x32_bf16 v[20:23], v[140:143], v[180:183], v[20:23]
	v_mfma_f32_16x16x32_bf16 v[16:19], v[148:151], v[180:183], v[16:19]
	v_mfma_f32_16x16x32_bf16 v[4:7], v[140:143], v[208:211], v[4:7]
	v_mfma_f32_16x16x32_bf16 v[0:3], v[148:151], v[208:211], v[0:3]
	s_setprio 0
	s_barrier
	s_add_i32 s60, 0, 0x18000
	s_add_i32 s61, 0, 0x1c000
	v_add_u32_e32 v124, s60, v239
	v_add_u32_e32 v148, s61, v239
	ds_read_b128 v[112:115], v124
	ds_read_b128 v[116:119], v124 offset:1024
	ds_read_b128 v[120:123], v124 offset:2048
	ds_read_b128 v[124:127], v124 offset:3072
	ds_read_b128 v[132:135], v148
	ds_read_b128 v[140:143], v148 offset:1024
	ds_read_b128 v[144:147], v148 offset:2048
	ds_read_b128 v[148:151], v148 offset:3072
	s_add_u32 s28, s28, 0x80000
	s_addc_u32 s29, s29, 0
	s_mov_b32 m0, s38
	v_lshl_add_u64 v[220:221], s[28:29], 0, v[202:203]
	ds_read_b128 v[156:159], v241 offset:32768
	ds_read_b128 v[164:167], v241 offset:33792
	ds_read_b128 v[168:171], v241 offset:34816
	ds_read_b128 v[172:175], v241 offset:35840
	ds_read_b128 v[176:179], v241 offset:36864
	ds_read_b128 v[180:183], v241 offset:37888
	ds_read_b128 v[184:187], v241 offset:38912
	ds_read_b128 v[208:211], v241 offset:39936
	global_load_lds_dwordx4 v[220:221], off
	v_lshl_add_u64 v[220:221], s[28:29], 0, v[200:201]
	s_mov_b32 m0, s39
	s_nop 0
	global_load_lds_dwordx4 v[220:221], off
	s_waitcnt vmcnt(8)
	s_waitcnt lgkmcnt(0)
	s_barrier
	s_setprio 1
	v_mfma_f32_16x16x32_bf16 v[160:163], v[112:115], v[156:159], v[160:163]
	v_mfma_f32_16x16x32_bf16 v[152:155], v[120:123], v[156:159], v[152:155]
	v_mfma_f32_16x16x32_bf16 v[108:111], v[112:115], v[168:171], v[108:111]
	v_mfma_f32_16x16x32_bf16 v[104:107], v[120:123], v[168:171], v[104:107]
	v_mfma_f32_16x16x32_bf16 v[92:95], v[112:115], v[176:179], v[92:95]
	v_mfma_f32_16x16x32_bf16 v[88:91], v[120:123], v[176:179], v[88:91]
	v_mfma_f32_16x16x32_bf16 v[76:79], v[112:115], v[184:187], v[76:79]
	v_mfma_f32_16x16x32_bf16 v[72:75], v[120:123], v[184:187], v[72:75]
	v_mfma_f32_16x16x32_bf16 v[160:163], v[116:119], v[164:167], v[160:163]
	v_mfma_f32_16x16x32_bf16 v[152:155], v[124:127], v[164:167], v[152:155]
	v_mfma_f32_16x16x32_bf16 v[108:111], v[116:119], v[172:175], v[108:111]
	v_mfma_f32_16x16x32_bf16 v[104:107], v[124:127], v[172:175], v[104:107]
	v_mfma_f32_16x16x32_bf16 v[92:95], v[116:119], v[180:183], v[92:95]
	v_mfma_f32_16x16x32_bf16 v[88:91], v[124:127], v[180:183], v[88:91]
	v_mfma_f32_16x16x32_bf16 v[76:79], v[116:119], v[208:211], v[76:79]
	v_mfma_f32_16x16x32_bf16 v[72:75], v[124:127], v[208:211], v[72:75]
	v_mfma_f32_16x16x32_bf16 v[136:139], v[132:135], v[156:159], v[136:139]
	v_mfma_f32_16x16x32_bf16 v[128:131], v[144:147], v[156:159], v[128:131]
	v_mfma_f32_16x16x32_bf16 v[100:103], v[132:135], v[168:171], v[100:103]
	v_mfma_f32_16x16x32_bf16 v[96:99], v[144:147], v[168:171], v[96:99]
	v_mfma_f32_16x16x32_bf16 v[84:87], v[132:135], v[176:179], v[84:87]
	v_mfma_f32_16x16x32_bf16 v[80:83], v[144:147], v[176:179], v[80:83]
	v_mfma_f32_16x16x32_bf16 v[68:71], v[132:135], v[184:187], v[68:71]
	v_mfma_f32_16x16x32_bf16 v[64:67], v[144:147], v[184:187], v[64:67]
	v_mfma_f32_16x16x32_bf16 v[136:139], v[140:143], v[164:167], v[136:139]
	v_mfma_f32_16x16x32_bf16 v[128:131], v[148:151], v[164:167], v[128:131]
	v_mfma_f32_16x16x32_bf16 v[100:103], v[140:143], v[172:175], v[100:103]
	v_mfma_f32_16x16x32_bf16 v[96:99], v[148:151], v[172:175], v[96:99]
	v_mfma_f32_16x16x32_bf16 v[84:87], v[140:143], v[180:183], v[84:87]
	v_mfma_f32_16x16x32_bf16 v[80:83], v[148:151], v[180:183], v[80:83]
	v_mfma_f32_16x16x32_bf16 v[68:71], v[140:143], v[208:211], v[68:71]
	v_mfma_f32_16x16x32_bf16 v[64:67], v[148:151], v[208:211], v[64:67]
	s_setprio 0
	s_barrier
; #define PG8_STAGE(bufoff, gbase, voff) do { _Pragma("unroll") for (int _i = 0; _i < 2; ++_i) \
;         __builtin_amdgcn_global_load_lds((const unsigned*)((const char*)(gbase) + (voff)[_i]), (PG8_LAS unsigned*)(lds + (bufoff) + ldsw + _i * 8192), 16, 0, 0); } while (0)
; #define PG8_LDA(dst, b, h) do { _Pragma("unroll") for (int m = 0; m < 4; ++m) _Pragma("unroll") for (int k = 0; k < 2; ++k) dst[m][k] = *(const PG8_LAS bf16x8*)(lds + PG8_SA(b, h) + aoff + m * 2048 + k * 1024); } while (0)
; #define PG8_MMA(ai, bj, At, Bt) do { __builtin_amdgcn_s_setprio(1); _Pragma("unroll") for (int m = 0; m < 4; ++m) _Pragma("unroll") for (int n = 0; n < 2; ++n) _Pragma("unroll") for (int k = 0; k < 2; ++k) \
;         acc[ai][bj][m][n] = __builtin_amdgcn_mfma_f32_16x16x32_bf16(Bt[n][k], At[m][k], acc[ai][bj][m][n], 0, 0, 0); __builtin_amdgcn_s_setprio(0); } while (0)
; #define PG8_WAIT_V(n) asm volatile("s_waitcnt vmcnt(" #n ")" ::: "memory")
; #define PG8_WAIT_L(n) asm volatile("s_waitcnt lgkmcnt(" #n ")" ::: "memory")
; #define PG8_BAR __builtin_amdgcn_s_barrier()
; #define PG8_SCHED __builtin_amdgcn_sched_barrier(0)
; template <class Epi, class Sched, bool ALIGN_EPI = false, bool SP2 = false>
; __device__ __forceinline__ void gemm_phase(PG8_LAS unsigned char* lds, const Gemm g, const Sched& S, const Epi& E) {
;     ...
;             PG8_LDA(At, 1, 1); PG8_STAGE(PG8_SB(1, 0), b3, voffB); PG8_STAGE(PG8_SB(1, 1), b3 + hstep, voffB); PG8_STAGE(PG8_SA(1, 0), a3, voffA);
;             PG8_WAIT_V(8); PG8_WAIT_L(0); PG8_BAR; PG8_MMA(1, 0, At, B0); PG8_MMA(1, 1, At, B1); PG8_BAR; PG8_SCHED;
	s_add_i32 s28, s60, s35
	v_lshl_add_u64 v[212:213], v[212:213], 0, s[78:79]
	s_mov_b32 m0, s28
	ds_read_b128 v[156:159], v241 offset:49152
	ds_read_b128 v[164:167], v241 offset:50176
	ds_read_b128 v[168:171], v241 offset:51200
	ds_read_b128 v[172:175], v241 offset:52224
	ds_read_b128 v[176:179], v241 offset:53248
	ds_read_b128 v[180:183], v241 offset:54272
	ds_read_b128 v[184:187], v241 offset:55296
	ds_read_b128 v[208:211], v241 offset:56320
	global_load_lds_dwordx4 v[212:213], off
	s_add_i32 m0, s28, 0x2000
	s_add_u32 s26, s26, 0x80080
	v_lshl_add_u64 v[212:213], v[214:215], 0, s[78:79]
	s_addc_u32 s27, s27, 0
	s_add_i32 s28, s61, s35
	global_load_lds_dwordx4 v[212:213], off
	v_lshl_add_u64 v[212:213], s[26:27], 0, v[188:189]
	s_mov_b32 m0, s28
	s_nop 0
	global_load_lds_dwordx4 v[212:213], off
	v_lshl_add_u64 v[212:213], s[26:27], 0, v[198:199]
	s_add_i32 m0, s28, 0x2000
	s_nop 0
	global_load_lds_dwordx4 v[212:213], off
	v_lshl_add_u64 v[212:213], v[216:217], 0, s[78:79]
	s_mov_b32 m0, s40
	s_nop 0
	global_load_lds_dwordx4 v[212:213], off
	v_lshl_add_u64 v[212:213], v[218:219], 0, s[78:79]
	s_mov_b32 m0, s41
	s_nop 0
	global_load_lds_dwordx4 v[212:213], off
	s_nop 0
	s_waitcnt vmcnt(8)
	s_waitcnt lgkmcnt(0)
	s_barrier
	s_setprio 1
	v_mfma_f32_16x16x32_bf16 v[60:63], v[112:115], v[156:159], v[60:63]
	v_mfma_f32_16x16x32_bf16 v[56:59], v[120:123], v[156:159], v[56:59]
	v_mfma_f32_16x16x32_bf16 v[44:47], v[112:115], v[168:171], v[44:47]
	v_mfma_f32_16x16x32_bf16 v[40:43], v[120:123], v[168:171], v[40:43]
	v_mfma_f32_16x16x32_bf16 v[28:31], v[112:115], v[176:179], v[28:31]
	v_mfma_f32_16x16x32_bf16 v[24:27], v[120:123], v[176:179], v[24:27]
	v_mfma_f32_16x16x32_bf16 v[12:15], v[112:115], v[184:187], v[12:15]
	v_mfma_f32_16x16x32_bf16 v[8:11], v[120:123], v[184:187], v[8:11]
	v_mfma_f32_16x16x32_bf16 v[60:63], v[116:119], v[164:167], v[60:63]
	v_mfma_f32_16x16x32_bf16 v[56:59], v[124:127], v[164:167], v[56:59]
	v_mfma_f32_16x16x32_bf16 v[44:47], v[116:119], v[172:175], v[44:47]
	v_mfma_f32_16x16x32_bf16 v[40:43], v[124:127], v[172:175], v[40:43]
	v_mfma_f32_16x16x32_bf16 v[28:31], v[116:119], v[180:183], v[28:31]
	v_mfma_f32_16x16x32_bf16 v[24:27], v[124:127], v[180:183], v[24:27]
	v_mfma_f32_16x16x32_bf16 v[12:15], v[116:119], v[208:211], v[12:15]
	v_mfma_f32_16x16x32_bf16 v[8:11], v[124:127], v[208:211], v[8:11]
	v_mfma_f32_16x16x32_bf16 v[52:55], v[132:135], v[156:159], v[52:55]
	v_mfma_f32_16x16x32_bf16 v[48:51], v[144:147], v[156:159], v[48:51]
	v_mfma_f32_16x16x32_bf16 v[36:39], v[132:135], v[168:171], v[36:39]
	v_mfma_f32_16x16x32_bf16 v[32:35], v[144:147], v[168:171], v[32:35]
	v_mfma_f32_16x16x32_bf16 v[20:23], v[132:135], v[176:179], v[20:23]
	v_mfma_f32_16x16x32_bf16 v[16:19], v[144:147], v[176:179], v[16:19]
	v_mfma_f32_16x16x32_bf16 v[4:7], v[132:135], v[184:187], v[4:7]
	v_mfma_f32_16x16x32_bf16 v[0:3], v[144:147], v[184:187], v[0:3]
	v_mfma_f32_16x16x32_bf16 v[52:55], v[140:143], v[164:167], v[52:55]
	v_mfma_f32_16x16x32_bf16 v[48:51], v[148:151], v[164:167], v[48:51]
	v_mfma_f32_16x16x32_bf16 v[36:39], v[140:143], v[172:175], v[36:39]
	v_mfma_f32_16x16x32_bf16 v[32:35], v[148:151], v[172:175], v[32:35]
	v_mfma_f32_16x16x32_bf16 v[20:23], v[140:143], v[180:183], v[20:23]
	v_mfma_f32_16x16x32_bf16 v[16:19], v[148:151], v[180:183], v[16:19]
	v_mfma_f32_16x16x32_bf16 v[4:7], v[140:143], v[208:211], v[4:7]
	v_mfma_f32_16x16x32_bf16 v[0:3], v[148:151], v[208:211], v[0:3]
	s_setprio 0
	s_barrier
	s_add_i32 s67, s67, 2
	s_add_u32 s24, s24, 0x100
	s_addc_u32 s25, s25, 0
	s_add_u32 s63, s63, 0x100
	s_addc_u32 s66, s66, 0
	s_cmp_gt_u32 s67, 29
	s_cbranch_scc0 .LBB0_596
	s_and_b64 vcc, exec, s[14:15]
	s_cbranch_vccz .LBB0_599
	s_barrier

; #define PG8_STAGE(bufoff, gbase, voff) do { _Pragma("unroll") for (int _i = 0; _i < 2; ++_i) \
;         __builtin_amdgcn_global_load_lds((const unsigned*)((const char*)(gbase) + (voff)[_i]), (PG8_LAS unsigned*)(lds + (bufoff) + ldsw + _i * 8192), 16, 0, 0); } while (0)
; #define PG8_LDA(dst, b, h) do { _Pragma("unroll") for (int m = 0; m < 4; ++m) _Pragma("unroll") for (int k = 0; k < 2; ++k) dst[m][k] = *(const PG8_LAS bf16x8*)(lds + PG8_SA(b, h) + aoff + m * 2048 + k * 1024); } while (0)
; #define PG8_LDB(dst, b, h) do { _Pragma("unroll") for (int n = 0; n < 2; ++n) _Pragma("unroll") for (int k = 0; k < 2; ++k) dst[n][k] = *(const PG8_LAS bf16x8*)(lds + PG8_SB(b, h) + boff + n * 2048 + k * 1024); } while (0)
; #define PG8_MMA(ai, bj, At, Bt) do { __builtin_amdgcn_s_setprio(1); _Pragma("unroll") for (int m = 0; m < 4; ++m) _Pragma("unroll") for (int n = 0; n < 2; ++n) _Pragma("unroll") for (int k = 0; k < 2; ++k) \
;         acc[ai][bj][m][n] = __builtin_amdgcn_mfma_f32_16x16x32_bf16(Bt[n][k], At[m][k], acc[ai][bj][m][n], 0, 0, 0); __builtin_amdgcn_s_setprio(0); } while (0)
; #define PG8_WAIT_V(n) asm volatile("s_waitcnt vmcnt(" #n ")" ::: "memory")
; #define PG8_WAIT_L(n) asm volatile("s_waitcnt lgkmcnt(" #n ")" ::: "memory")
; #define PG8_BAR __builtin_amdgcn_s_barrier()
; #define PG8_SCHED __builtin_amdgcn_sched_barrier(0)
; template <class Epi, class Sched, bool ALIGN_EPI = false, bool SP2 = false>
; __device__ __forceinline__ void gemm_phase(PG8_LAS unsigned char* lds, const Gemm g, const Sched& S, const Epi& E) {
;     ...
;             const bool last = (t == nt - 2);
;             const char* a1 = cA + (size_t)(t + 1) * kstep;
;             const char* a2 = last ? nA : cA + (size_t)(t + 2) * kstep; const char* b2 = last ? nB : cB + (size_t)(t + 2) * kstep;
;             const char* a3 = a2 + kstep; const char* b3 = b2 + kstep;
;             if (last && has_next) S.a_ready(nxt);
;             if constexpr (SP2) {
;             PG8_LDB(B0, 0, 0); PG8_LDB(B1, 0, 1); PG8_SCHED; PG8_LDA(At, 0, 0); PG8_STAGE(PG8_SA(1, 1), a1 + hstep, voffA);
;             PG8_WAIT_V(8); PG8_WAIT_L(0); PG8_BAR; PG8_MMA(0, 0, At, B0); PG8_MMA(0, 1, At, B1); PG8_BAR; PG8_SCHED;
;             PG8_LDA(At, 0, 1); PG8_STAGE(PG8_SB(0, 0), b2, voffB); PG8_STAGE(PG8_SB(0, 1), b2 + hstep, voffB); PG8_STAGE(PG8_SA(0, 0), a2, voffA);
.LBB0_684:
	s_add_u32 s24, s8, 0xfff80080
	s_addc_u32 s25, s9, -1
	s_add_i32 s60, 0, 0x10000
	s_cmp_eq_u32 s63, 28
	s_cselect_b32 s27, s19, s25
	s_cselect_b32 s26, s45, s24
	v_add_u32_e32 v154, s60, v157
	s_cselect_b32 s25, s17, s62
	s_cselect_b32 s24, s52, s58
	s_add_i32 s66, 0, 0x14000
	ds_read_b128 v[160:163], v154
	ds_read_b128 v[164:167], v154 offset:1024
	ds_read_b128 v[168:171], v154 offset:2048
	ds_read_b128 v[172:175], v154 offset:3072
	v_add_u32_e32 v154, s66, v157
	ds_read_b128 v[176:179], v154
	ds_read_b128 v[180:183], v154 offset:1024
	ds_read_b128 v[184:187], v154 offset:2048
	ds_read_b128 v[198:201], v154 offset:3072
	v_lshl_add_u64 v[154:155], s[8:9], 0, v[134:135]
	s_add_i32 m0, s34, 0xc000
	ds_read_b128 v[202:205], v159
	ds_read_b128 v[206:209], v159 offset:1024
	ds_read_b128 v[210:213], v159 offset:2048
	ds_read_b128 v[214:217], v159 offset:3072
	ds_read_b128 v[218:221], v159 offset:4096
	ds_read_b128 v[222:225], v159 offset:5120
	ds_read_b128 v[226:229], v159 offset:6144
	ds_read_b128 v[238:241], v159 offset:7168
	global_load_lds_dwordx4 v[154:155], off
	v_lshl_add_u64 v[154:155], s[8:9], 0, v[136:137]
	s_add_i32 m0, s34, 0xe000
	s_nop 0
	global_load_lds_dwordx4 v[154:155], off
	s_waitcnt vmcnt(8)
	s_waitcnt lgkmcnt(0)
	s_barrier
	s_setprio 1
	v_mfma_f32_16x16x32_bf16 v[124:127], v[160:163], v[202:205], v[124:127]
	v_mfma_f32_16x16x32_bf16 v[120:123], v[168:171], v[202:205], v[120:123]
	v_mfma_f32_16x16x32_bf16 v[108:111], v[160:163], v[210:213], v[108:111]
	v_mfma_f32_16x16x32_bf16 v[104:107], v[168:171], v[210:213], v[104:107]
	v_mfma_f32_16x16x32_bf16 v[92:95], v[160:163], v[218:221], v[92:95]
	v_mfma_f32_16x16x32_bf16 v[88:91], v[168:171], v[218:221], v[88:91]
	v_mfma_f32_16x16x32_bf16 v[76:79], v[160:163], v[226:229], v[76:79]
	v_mfma_f32_16x16x32_bf16 v[72:75], v[168:171], v[226:229], v[72:75]
	v_mfma_f32_16x16x32_bf16 v[124:127], v[164:167], v[206:209], v[124:127]
	v_mfma_f32_16x16x32_bf16 v[120:123], v[172:175], v[206:209], v[120:123]
	v_mfma_f32_16x16x32_bf16 v[108:111], v[164:167], v[214:217], v[108:111]
	v_mfma_f32_16x16x32_bf16 v[104:107], v[172:175], v[214:217], v[104:107]
	v_mfma_f32_16x16x32_bf16 v[92:95], v[164:167], v[222:225], v[92:95]
	v_mfma_f32_16x16x32_bf16 v[88:91], v[172:175], v[222:225], v[88:91]
	v_mfma_f32_16x16x32_bf16 v[76:79], v[164:167], v[238:241], v[76:79]
	v_mfma_f32_16x16x32_bf16 v[72:75], v[172:175], v[238:241], v[72:75]
	v_mfma_f32_16x16x32_bf16 v[116:119], v[176:179], v[202:205], v[116:119]
	v_mfma_f32_16x16x32_bf16 v[112:115], v[184:187], v[202:205], v[112:115]
	v_mfma_f32_16x16x32_bf16 v[100:103], v[176:179], v[210:213], v[100:103]
	v_mfma_f32_16x16x32_bf16 v[96:99], v[184:187], v[210:213], v[96:99]
	v_mfma_f32_16x16x32_bf16 v[84:87], v[176:179], v[218:221], v[84:87]
	v_mfma_f32_16x16x32_bf16 v[80:83], v[184:187], v[218:221], v[80:83]
	v_mfma_f32_16x16x32_bf16 v[68:71], v[176:179], v[226:229], v[68:71]
	v_mfma_f32_16x16x32_bf16 v[64:67], v[184:187], v[226:229], v[64:67]
	v_mfma_f32_16x16x32_bf16 v[116:119], v[180:183], v[206:209], v[116:119]
	v_mfma_f32_16x16x32_bf16 v[112:115], v[198:201], v[206:209], v[112:115]
	v_mfma_f32_16x16x32_bf16 v[100:103], v[180:183], v[214:217], v[100:103]
	v_mfma_f32_16x16x32_bf16 v[96:99], v[198:201], v[214:217], v[96:99]
	v_mfma_f32_16x16x32_bf16 v[84:87], v[180:183], v[222:225], v[84:87]
	v_mfma_f32_16x16x32_bf16 v[80:83], v[198:201], v[222:225], v[80:83]
	v_mfma_f32_16x16x32_bf16 v[68:71], v[180:183], v[238:241], v[68:71]
	v_mfma_f32_16x16x32_bf16 v[64:67], v[198:201], v[238:241], v[64:67]
	s_setprio 0
	s_barrier
	s_add_i32 s60, s60, s31
	v_lshl_add_u64 v[154:155], s[24:25], 0, v[188:189]
	s_mov_b32 m0, s60
	ds_read_b128 v[202:205], v159 offset:16384
	ds_read_b128 v[206:209], v159 offset:17408
	ds_read_b128 v[210:213], v159 offset:18432
	ds_read_b128 v[214:217], v159 offset:19456
	ds_read_b128 v[218:221], v159 offset:20480
	ds_read_b128 v[222:225], v159 offset:21504
	ds_read_b128 v[226:229], v159 offset:22528
	ds_read_b128 v[238:241], v159 offset:23552
	global_load_lds_dwordx4 v[154:155], off
	s_add_i32 m0, s60, 0x2000
	s_add_u32 s60, s24, 0x80000
	v_lshl_add_u64 v[232:233], s[24:25], 0, v[128:129]
	s_addc_u32 s61, s25, 0
	s_add_i32 s66, s66, s31
	global_load_lds_dwordx4 v[232:233], off
	v_lshl_add_u64 v[242:243], s[60:61], 0, v[188:189]
	s_mov_b32 m0, s66
	v_lshl_add_u64 v[244:245], s[26:27], 0, v[130:131]
	global_load_lds_dwordx4 v[242:243], off
	v_lshl_add_u64 v[242:243], s[60:61], 0, v[128:129]
	s_add_i32 m0, s66, 0x2000
	s_nop 0
	global_load_lds_dwordx4 v[242:243], off
	v_lshl_add_u64 v[242:243], s[26:27], 0, v[132:133]
	s_mov_b32 m0, s34
	s_nop 0
	global_load_lds_dwordx4 v[242:243], off
	s_mov_b32 m0, s35
	s_nop 0
	global_load_lds_dwordx4 v[244:245], off
	s_waitcnt vmcnt(8)
	s_waitcnt lgkmcnt(0)
	s_barrier
; #define PG8_STAGE(bufoff, gbase, voff) do { _Pragma("unroll") for (int _i = 0; _i < 2; ++_i) \
;         __builtin_amdgcn_global_load_lds((const unsigned*)((const char*)(gbase) + (voff)[_i]), (PG8_LAS unsigned*)(lds + (bufoff) + ldsw + _i * 8192), 16, 0, 0); } while (0)
; #define PG8_LDA(dst, b, h) do { _Pragma("unroll") for (int m = 0; m < 4; ++m) _Pragma("unroll") for (int k = 0; k < 2; ++k) dst[m][k] = *(const PG8_LAS bf16x8*)(lds + PG8_SA(b, h) + aoff + m * 2048 + k * 1024); } while (0)
; #define PG8_LDB(dst, b, h) do { _Pragma("unroll") for (int n = 0; n < 2; ++n) _Pragma("unroll") for (int k = 0; k < 2; ++k) dst[n][k] = *(const PG8_LAS bf16x8*)(lds + PG8_SB(b, h) + boff + n * 2048 + k * 1024); } while (0)
; #define PG8_MMA(ai, bj, At, Bt) do { __builtin_amdgcn_s_setprio(1); _Pragma("unroll") for (int m = 0; m < 4; ++m) _Pragma("unroll") for (int n = 0; n < 2; ++n) _Pragma("unroll") for (int k = 0; k < 2; ++k) \
;         acc[ai][bj][m][n] = __builtin_amdgcn_mfma_f32_16x16x32_bf16(Bt[n][k], At[m][k], acc[ai][bj][m][n], 0, 0, 0); __builtin_amdgcn_s_setprio(0); } while (0)
; #define PG8_WAIT_V(n) asm volatile("s_waitcnt vmcnt(" #n ")" ::: "memory")
; #define PG8_WAIT_L(n) asm volatile("s_waitcnt lgkmcnt(" #n ")" ::: "memory")
; #define PG8_BAR __builtin_amdgcn_s_barrier()
; #define PG8_SCHED __builtin_amdgcn_sched_barrier(0)
; template <class Epi, class Sched, bool ALIGN_EPI = false, bool SP2 = false>
; __device__ __forceinline__ void gemm_phase(PG8_LAS unsigned char* lds, const Gemm g, const Sched& S, const Epi& E) {
;     ...
;             PG8_WAIT_V(8); PG8_WAIT_L(0); PG8_BAR; PG8_MMA(1, 0, At, B0); PG8_MMA(1, 1, At, B1); PG8_BAR; PG8_SCHED;
;             PG8_LDB(B0, 1, 0); PG8_LDB(B1, 1, 1); PG8_SCHED; PG8_LDA(At, 1, 0); PG8_STAGE(PG8_SA(0, 1), a2 + hstep, voffA);
;             PG8_WAIT_V(8); PG8_WAIT_L(0); PG8_BAR; PG8_MMA(0, 0, At, B0); PG8_MMA(0, 1, At, B1); PG8_BAR; PG8_SCHED;
	s_setprio 1
	v_mfma_f32_16x16x32_bf16 v[60:63], v[160:163], v[202:205], v[60:63]
	v_mfma_f32_16x16x32_bf16 v[56:59], v[168:171], v[202:205], v[56:59]
	v_mfma_f32_16x16x32_bf16 v[44:47], v[160:163], v[210:213], v[44:47]
	v_mfma_f32_16x16x32_bf16 v[40:43], v[168:171], v[210:213], v[40:43]
	v_mfma_f32_16x16x32_bf16 v[28:31], v[160:163], v[218:221], v[28:31]
	v_mfma_f32_16x16x32_bf16 v[24:27], v[168:171], v[218:221], v[24:27]
	v_mfma_f32_16x16x32_bf16 v[12:15], v[160:163], v[226:229], v[12:15]
	v_mfma_f32_16x16x32_bf16 v[8:11], v[168:171], v[226:229], v[8:11]
	v_mfma_f32_16x16x32_bf16 v[60:63], v[164:167], v[206:209], v[60:63]
	v_mfma_f32_16x16x32_bf16 v[56:59], v[172:175], v[206:209], v[56:59]
	v_mfma_f32_16x16x32_bf16 v[44:47], v[164:167], v[214:217], v[44:47]
	v_mfma_f32_16x16x32_bf16 v[40:43], v[172:175], v[214:217], v[40:43]
	v_mfma_f32_16x16x32_bf16 v[28:31], v[164:167], v[222:225], v[28:31]
	v_mfma_f32_16x16x32_bf16 v[24:27], v[172:175], v[222:225], v[24:27]
	v_mfma_f32_16x16x32_bf16 v[12:15], v[164:167], v[238:241], v[12:15]
	v_mfma_f32_16x16x32_bf16 v[8:11], v[172:175], v[238:241], v[8:11]
	v_mfma_f32_16x16x32_bf16 v[52:55], v[176:179], v[202:205], v[52:55]
	v_mfma_f32_16x16x32_bf16 v[48:51], v[184:187], v[202:205], v[48:51]
	v_mfma_f32_16x16x32_bf16 v[36:39], v[176:179], v[210:213], v[36:39]
	v_mfma_f32_16x16x32_bf16 v[32:35], v[184:187], v[210:213], v[32:35]
	v_mfma_f32_16x16x32_bf16 v[20:23], v[176:179], v[218:221], v[20:23]
	v_mfma_f32_16x16x32_bf16 v[16:19], v[184:187], v[218:221], v[16:19]
	v_mfma_f32_16x16x32_bf16 v[4:7], v[176:179], v[226:229], v[4:7]
	v_mfma_f32_16x16x32_bf16 v[0:3], v[184:187], v[226:229], v[0:3]
	v_mfma_f32_16x16x32_bf16 v[52:55], v[180:183], v[206:209], v[52:55]
	v_mfma_f32_16x16x32_bf16 v[48:51], v[198:201], v[206:209], v[48:51]
	v_mfma_f32_16x16x32_bf16 v[36:39], v[180:183], v[214:217], v[36:39]
	v_mfma_f32_16x16x32_bf16 v[32:35], v[198:201], v[214:217], v[32:35]
	v_mfma_f32_16x16x32_bf16 v[20:23], v[180:183], v[222:225], v[20:23]
	v_mfma_f32_16x16x32_bf16 v[16:19], v[198:201], v[222:225], v[16:19]
	v_mfma_f32_16x16x32_bf16 v[4:7], v[180:183], v[238:241], v[4:7]
	v_mfma_f32_16x16x32_bf16 v[0:3], v[198:201], v[238:241], v[0:3]
	s_setprio 0
	s_barrier
	s_add_i32 s60, 0, 0x18000
	s_add_i32 s61, 0, 0x1c000
	v_add_u32_e32 v172, s60, v157
	v_add_u32_e32 v194, s61, v157
	ds_read_b128 v[160:163], v172
	ds_read_b128 v[164:167], v172 offset:1024
	ds_read_b128 v[168:171], v172 offset:2048
	ds_read_b128 v[172:175], v172 offset:3072
	ds_read_b128 v[176:179], v194
	ds_read_b128 v[180:183], v194 offset:1024
	ds_read_b128 v[184:187], v194 offset:2048
	ds_read_b128 v[198:201], v194 offset:3072
	s_add_u32 s26, s26, 0x80000
	s_addc_u32 s27, s27, 0
	s_mov_b32 m0, s36
	v_lshl_add_u64 v[246:247], s[26:27], 0, v[132:133]
	ds_read_b128 v[202:205], v159 offset:32768
	ds_read_b128 v[206:209], v159 offset:33792
	ds_read_b128 v[210:213], v159 offset:34816
	ds_read_b128 v[214:217], v159 offset:35840
	ds_read_b128 v[218:221], v159 offset:36864
	ds_read_b128 v[222:225], v159 offset:37888
	ds_read_b128 v[226:229], v159 offset:38912
	ds_read_b128 v[238:241], v159 offset:39936
	global_load_lds_dwordx4 v[246:247], off
	v_lshl_add_u64 v[246:247], s[26:27], 0, v[130:131]
	s_mov_b32 m0, s37
	s_nop 0
	global_load_lds_dwordx4 v[246:247], off
	s_waitcnt vmcnt(8)
	s_waitcnt lgkmcnt(0)
	s_barrier
	s_setprio 1
	v_mfma_f32_16x16x32_bf16 v[124:127], v[160:163], v[202:205], v[124:127]
	v_mfma_f32_16x16x32_bf16 v[120:123], v[168:171], v[202:205], v[120:123]
	v_mfma_f32_16x16x32_bf16 v[108:111], v[160:163], v[210:213], v[108:111]
	v_mfma_f32_16x16x32_bf16 v[104:107], v[168:171], v[210:213], v[104:107]
	v_mfma_f32_16x16x32_bf16 v[92:95], v[160:163], v[218:221], v[92:95]
	v_mfma_f32_16x16x32_bf16 v[88:91], v[168:171], v[218:221], v[88:91]
	v_mfma_f32_16x16x32_bf16 v[76:79], v[160:163], v[226:229], v[76:79]
	v_mfma_f32_16x16x32_bf16 v[72:75], v[168:171], v[226:229], v[72:75]
	v_mfma_f32_16x16x32_bf16 v[124:127], v[164:167], v[206:209], v[124:127]
	v_mfma_f32_16x16x32_bf16 v[120:123], v[172:175], v[206:209], v[120:123]
	v_mfma_f32_16x16x32_bf16 v[108:111], v[164:167], v[214:217], v[108:111]
	v_mfma_f32_16x16x32_bf16 v[104:107], v[172:175], v[214:217], v[104:107]
	v_mfma_f32_16x16x32_bf16 v[92:95], v[164:167], v[222:225], v[92:95]
	v_mfma_f32_16x16x32_bf16 v[88:91], v[172:175], v[222:225], v[88:91]
	v_mfma_f32_16x16x32_bf16 v[76:79], v[164:167], v[238:241], v[76:79]
	v_mfma_f32_16x16x32_bf16 v[72:75], v[172:175], v[238:241], v[72:75]
	v_mfma_f32_16x16x32_bf16 v[116:119], v[176:179], v[202:205], v[116:119]
	v_mfma_f32_16x16x32_bf16 v[112:115], v[184:187], v[202:205], v[112:115]
	v_mfma_f32_16x16x32_bf16 v[100:103], v[176:179], v[210:213], v[100:103]
	v_mfma_f32_16x16x32_bf16 v[96:99], v[184:187], v[210:213], v[96:99]
	v_mfma_f32_16x16x32_bf16 v[84:87], v[176:179], v[218:221], v[84:87]
	v_mfma_f32_16x16x32_bf16 v[80:83], v[184:187], v[218:221], v[80:83]
	v_mfma_f32_16x16x32_bf16 v[68:71], v[176:179], v[226:229], v[68:71]
	v_mfma_f32_16x16x32_bf16 v[64:67], v[184:187], v[226:229], v[64:67]
	v_mfma_f32_16x16x32_bf16 v[116:119], v[180:183], v[206:209], v[116:119]
	v_mfma_f32_16x16x32_bf16 v[112:115], v[198:201], v[206:209], v[112:115]
	v_mfma_f32_16x16x32_bf16 v[100:103], v[180:183], v[214:217], v[100:103]
	v_mfma_f32_16x16x32_bf16 v[96:99], v[198:201], v[214:217], v[96:99]
	v_mfma_f32_16x16x32_bf16 v[84:87], v[180:183], v[222:225], v[84:87]
	v_mfma_f32_16x16x32_bf16 v[80:83], v[198:201], v[222:225], v[80:83]
	v_mfma_f32_16x16x32_bf16 v[68:71], v[180:183], v[238:241], v[68:71]
	v_mfma_f32_16x16x32_bf16 v[64:67], v[198:201], v[238:241], v[64:67]
	s_setprio 0
	s_barrier
; #define PG8_STAGE(bufoff, gbase, voff) do { _Pragma("unroll") for (int _i = 0; _i < 2; ++_i) \
;         __builtin_amdgcn_global_load_lds((const unsigned*)((const char*)(gbase) + (voff)[_i]), (PG8_LAS unsigned*)(lds + (bufoff) + ldsw + _i * 8192), 16, 0, 0); } while (0)
; #define PG8_LDA(dst, b, h) do { _Pragma("unroll") for (int m = 0; m < 4; ++m) _Pragma("unroll") for (int k = 0; k < 2; ++k) dst[m][k] = *(const PG8_LAS bf16x8*)(lds + PG8_SA(b, h) + aoff + m * 2048 + k * 1024); } while (0)
; #define PG8_MMA(ai, bj, At, Bt) do { __builtin_amdgcn_s_setprio(1); _Pragma("unroll") for (int m = 0; m < 4; ++m) _Pragma("unroll") for (int n = 0; n < 2; ++n) _Pragma("unroll") for (int k = 0; k < 2; ++k) \
;         acc[ai][bj][m][n] = __builtin_amdgcn_mfma_f32_16x16x32_bf16(Bt[n][k], At[m][k], acc[ai][bj][m][n], 0, 0, 0); __builtin_amdgcn_s_setprio(0); } while (0)
; #define PG8_WAIT_V(n) asm volatile("s_waitcnt vmcnt(" #n ")" ::: "memory")
; #define PG8_WAIT_L(n) asm volatile("s_waitcnt lgkmcnt(" #n ")" ::: "memory")
; #define PG8_BAR __builtin_amdgcn_s_barrier()
; #define PG8_SCHED __builtin_amdgcn_sched_barrier(0)
; template <class Epi, class Sched, bool ALIGN_EPI = false, bool SP2 = false>
; __device__ __forceinline__ void gemm_phase(PG8_LAS unsigned char* lds, const Gemm g, const Sched& S, const Epi& E) {
;     ...
;             PG8_LDA(At, 1, 1); PG8_STAGE(PG8_SB(1, 0), b3, voffB); PG8_STAGE(PG8_SB(1, 1), b3 + hstep, voffB); PG8_STAGE(PG8_SA(1, 0), a3, voffA);
;             PG8_WAIT_V(8); PG8_WAIT_L(0); PG8_BAR; PG8_MMA(1, 0, At, B0); PG8_MMA(1, 1, At, B1); PG8_BAR; PG8_SCHED;
	s_add_i32 s26, s60, s31
	v_lshl_add_u64 v[154:155], v[154:155], 0, s[78:79]
	s_mov_b32 m0, s26
	ds_read_b128 v[202:205], v159 offset:49152
	ds_read_b128 v[206:209], v159 offset:50176
	ds_read_b128 v[210:213], v159 offset:51200
	ds_read_b128 v[214:217], v159 offset:52224
	ds_read_b128 v[218:221], v159 offset:53248
	ds_read_b128 v[222:225], v159 offset:54272
	ds_read_b128 v[226:229], v159 offset:55296
	ds_read_b128 v[238:241], v159 offset:56320
	global_load_lds_dwordx4 v[154:155], off
	s_add_i32 m0, s26, 0x2000
	s_add_u32 s24, s24, 0x80080
	v_lshl_add_u64 v[154:155], v[232:233], 0, s[78:79]
	s_addc_u32 s25, s25, 0
	s_add_i32 s26, s61, s31
	global_load_lds_dwordx4 v[154:155], off
	v_lshl_add_u64 v[154:155], s[24:25], 0, v[188:189]
	s_mov_b32 m0, s26
	s_nop 0
	global_load_lds_dwordx4 v[154:155], off
	v_lshl_add_u64 v[154:155], s[24:25], 0, v[128:129]
	s_add_i32 m0, s26, 0x2000
	s_nop 0
	global_load_lds_dwordx4 v[154:155], off
	v_lshl_add_u64 v[154:155], v[242:243], 0, s[78:79]
	s_mov_b32 m0, s38
	s_nop 0
	global_load_lds_dwordx4 v[154:155], off
	v_lshl_add_u64 v[154:155], v[244:245], 0, s[78:79]
	s_mov_b32 m0, s39
	s_nop 0
	global_load_lds_dwordx4 v[154:155], off
	s_nop 0
	s_waitcnt vmcnt(8)
	s_waitcnt lgkmcnt(0)
	s_barrier
	s_setprio 1
	v_mfma_f32_16x16x32_bf16 v[60:63], v[160:163], v[202:205], v[60:63]
	v_mfma_f32_16x16x32_bf16 v[56:59], v[168:171], v[202:205], v[56:59]
	v_mfma_f32_16x16x32_bf16 v[44:47], v[160:163], v[210:213], v[44:47]
	v_mfma_f32_16x16x32_bf16 v[40:43], v[168:171], v[210:213], v[40:43]
	v_mfma_f32_16x16x32_bf16 v[28:31], v[160:163], v[218:221], v[28:31]
	v_mfma_f32_16x16x32_bf16 v[24:27], v[168:171], v[218:221], v[24:27]
	v_mfma_f32_16x16x32_bf16 v[12:15], v[160:163], v[226:229], v[12:15]
	v_mfma_f32_16x16x32_bf16 v[8:11], v[168:171], v[226:229], v[8:11]
	v_mfma_f32_16x16x32_bf16 v[60:63], v[164:167], v[206:209], v[60:63]
	v_mfma_f32_16x16x32_bf16 v[56:59], v[172:175], v[206:209], v[56:59]
	v_mfma_f32_16x16x32_bf16 v[44:47], v[164:167], v[214:217], v[44:47]
	v_mfma_f32_16x16x32_bf16 v[40:43], v[172:175], v[214:217], v[40:43]
	v_mfma_f32_16x16x32_bf16 v[28:31], v[164:167], v[222:225], v[28:31]
	v_mfma_f32_16x16x32_bf16 v[24:27], v[172:175], v[222:225], v[24:27]
	v_mfma_f32_16x16x32_bf16 v[12:15], v[164:167], v[238:241], v[12:15]
	v_mfma_f32_16x16x32_bf16 v[8:11], v[172:175], v[238:241], v[8:11]
	v_mfma_f32_16x16x32_bf16 v[52:55], v[176:179], v[202:205], v[52:55]
	v_mfma_f32_16x16x32_bf16 v[48:51], v[184:187], v[202:205], v[48:51]
	v_mfma_f32_16x16x32_bf16 v[36:39], v[176:179], v[210:213], v[36:39]
	v_mfma_f32_16x16x32_bf16 v[32:35], v[184:187], v[210:213], v[32:35]
	v_mfma_f32_16x16x32_bf16 v[20:23], v[176:179], v[218:221], v[20:23]
	v_mfma_f32_16x16x32_bf16 v[16:19], v[184:187], v[218:221], v[16:19]
	v_mfma_f32_16x16x32_bf16 v[4:7], v[176:179], v[226:229], v[4:7]
	v_mfma_f32_16x16x32_bf16 v[0:3], v[184:187], v[226:229], v[0:3]
	v_mfma_f32_16x16x32_bf16 v[52:55], v[180:183], v[206:209], v[52:55]
	v_mfma_f32_16x16x32_bf16 v[48:51], v[198:201], v[206:209], v[48:51]
	v_mfma_f32_16x16x32_bf16 v[36:39], v[180:183], v[214:217], v[36:39]
	v_mfma_f32_16x16x32_bf16 v[32:35], v[198:201], v[214:217], v[32:35]
	v_mfma_f32_16x16x32_bf16 v[20:23], v[180:183], v[222:225], v[20:23]
	v_mfma_f32_16x16x32_bf16 v[16:19], v[198:201], v[222:225], v[16:19]
	v_mfma_f32_16x16x32_bf16 v[4:7], v[180:183], v[238:241], v[4:7]
	v_mfma_f32_16x16x32_bf16 v[0:3], v[198:201], v[238:241], v[0:3]
	s_setprio 0
	s_barrier
	s_add_i32 s63, s63, 2
	s_add_u32 s8, s8, 0x100
	s_addc_u32 s9, s9, 0
	s_add_u32 s58, s58, 0x100
	s_addc_u32 s62, s62, 0
	s_cmp_gt_u32 s63, 29
	s_cbranch_scc0 .LBB0_684
	s_and_b64 vcc, exec, s[14:15]
	s_cbranch_vccz .LBB0_687
	s_barrier

; #define PG8_STAGE(bufoff, gbase, voff) do { _Pragma("unroll") for (int _i = 0; _i < 2; ++_i) \
;         __builtin_amdgcn_global_load_lds((const unsigned*)((const char*)(gbase) + (voff)[_i]), (PG8_LAS unsigned*)(lds + (bufoff) + ldsw + _i * 8192), 16, 0, 0); } while (0)
; #define PG8_LDA(dst, b, h) do { _Pragma("unroll") for (int m = 0; m < 4; ++m) _Pragma("unroll") for (int k = 0; k < 2; ++k) dst[m][k] = *(const PG8_LAS bf16x8*)(lds + PG8_SA(b, h) + aoff + m * 2048 + k * 1024); } while (0)
; #define PG8_LDB(dst, b, h) do { _Pragma("unroll") for (int n = 0; n < 2; ++n) _Pragma("unroll") for (int k = 0; k < 2; ++k) dst[n][k] = *(const PG8_LAS bf16x8*)(lds + PG8_SB(b, h) + boff + n * 2048 + k * 1024); } while (0)
; #define PG8_MMA(ai, bj, At, Bt) do { __builtin_amdgcn_s_setprio(1); _Pragma("unroll") for (int m = 0; m < 4; ++m) _Pragma("unroll") for (int n = 0; n < 2; ++n) _Pragma("unroll") for (int k = 0; k < 2; ++k) \
;         acc[ai][bj][m][n] = __builtin_amdgcn_mfma_f32_16x16x32_bf16(Bt[n][k], At[m][k], acc[ai][bj][m][n], 0, 0, 0); __builtin_amdgcn_s_setprio(0); } while (0)
; #define PG8_WAIT_V(n) asm volatile("s_waitcnt vmcnt(" #n ")" ::: "memory")
; #define PG8_WAIT_L(n) asm volatile("s_waitcnt lgkmcnt(" #n ")" ::: "memory")
; #define PG8_BAR __builtin_amdgcn_s_barrier()
; #define PG8_SCHED __builtin_amdgcn_sched_barrier(0)
; template <class Epi, class Sched, bool ALIGN_EPI = false, bool SP2 = false>
; __device__ __forceinline__ void gemm_phase(PG8_LAS unsigned char* lds, const Gemm g, const Sched& S, const Epi& E) {
;     ...
;             const bool last = (t == nt - 2);
;             const char* a1 = cA + (size_t)(t + 1) * kstep;
;             const char* a2 = last ? nA : cA + (size_t)(t + 2) * kstep; const char* b2 = last ? nB : cB + (size_t)(t + 2) * kstep;
;             const char* a3 = a2 + kstep; const char* b3 = b2 + kstep;
;             if (last && has_next) S.a_ready(nxt);
;             if constexpr (SP2) {
;             PG8_LDB(B0, 0, 0); PG8_LDB(B1, 0, 1); PG8_SCHED; PG8_LDA(At, 0, 0); PG8_STAGE(PG8_SA(1, 1), a1 + hstep, voffA);
;             PG8_WAIT_V(8); PG8_WAIT_L(0); PG8_BAR; PG8_MMA(0, 0, At, B0); PG8_MMA(0, 1, At, B1); PG8_BAR; PG8_SCHED;
;             PG8_LDA(At, 0, 1); PG8_STAGE(PG8_SB(0, 0), b2, voffB); PG8_STAGE(PG8_SB(0, 1), b2 + hstep, voffB); PG8_STAGE(PG8_SA(0, 0), a2, voffA);
.LBB0_757:
	s_add_u32 s28, s26, 0xffe00080
	s_addc_u32 s29, s27, -1
	s_add_i32 s60, 0, 0x10000
	s_cmpk_eq_i32 s72, 0x7c
	s_cselect_b32 s31, s21, s29
	s_cselect_b32 s30, s63, s28
	s_cselect_b32 s29, s19, s68
	s_cselect_b32 s28, s66, s67
	s_add_i32 s73, 0, 0x14000
	v_add_u32_e32 v124, s60, v239
	v_add_u32_e32 v148, s73, v239
	ds_read_b128 v[112:115], v124
	ds_read_b128 v[116:119], v124 offset:1024
	ds_read_b128 v[120:123], v124 offset:2048
	ds_read_b128 v[124:127], v124 offset:3072
	ds_read_b128 v[132:135], v148
	ds_read_b128 v[140:143], v148 offset:1024
	ds_read_b128 v[144:147], v148 offset:2048
	ds_read_b128 v[148:151], v148 offset:3072
	v_lshl_add_u64 v[212:213], s[26:27], 0, v[204:205]
	s_add_i32 m0, s38, 0xc000
	ds_read_b128 v[152:155], v241
	ds_read_b128 v[164:167], v241 offset:1024
	ds_read_b128 v[168:171], v241 offset:2048
	ds_read_b128 v[172:175], v241 offset:3072
	ds_read_b128 v[176:179], v241 offset:4096
	ds_read_b128 v[180:183], v241 offset:5120
	ds_read_b128 v[184:187], v241 offset:6144
	ds_read_b128 v[208:211], v241 offset:7168
	global_load_lds_dwordx4 v[212:213], off
	v_lshl_add_u64 v[212:213], s[26:27], 0, v[206:207]
	s_add_i32 m0, s38, 0xe000
	s_nop 0
	global_load_lds_dwordx4 v[212:213], off
	s_nop 0
	s_waitcnt vmcnt(8)
	s_waitcnt lgkmcnt(0)
	s_barrier
	s_setprio 1
	v_mfma_f32_16x16x32_bf16 v[160:163], v[112:115], v[152:155], v[160:163]
	v_mfma_f32_16x16x32_bf16 v[156:159], v[120:123], v[152:155], v[156:159]
	v_mfma_f32_16x16x32_bf16 v[108:111], v[112:115], v[168:171], v[108:111]
	v_mfma_f32_16x16x32_bf16 v[104:107], v[120:123], v[168:171], v[104:107]
	v_mfma_f32_16x16x32_bf16 v[92:95], v[112:115], v[176:179], v[92:95]
	v_mfma_f32_16x16x32_bf16 v[88:91], v[120:123], v[176:179], v[88:91]
	v_mfma_f32_16x16x32_bf16 v[76:79], v[112:115], v[184:187], v[76:79]
	v_mfma_f32_16x16x32_bf16 v[72:75], v[120:123], v[184:187], v[72:75]
	v_mfma_f32_16x16x32_bf16 v[160:163], v[116:119], v[164:167], v[160:163]
	v_mfma_f32_16x16x32_bf16 v[156:159], v[124:127], v[164:167], v[156:159]
	v_mfma_f32_16x16x32_bf16 v[108:111], v[116:119], v[172:175], v[108:111]
	v_mfma_f32_16x16x32_bf16 v[104:107], v[124:127], v[172:175], v[104:107]
	v_mfma_f32_16x16x32_bf16 v[92:95], v[116:119], v[180:183], v[92:95]
	v_mfma_f32_16x16x32_bf16 v[88:91], v[124:127], v[180:183], v[88:91]
	v_mfma_f32_16x16x32_bf16 v[76:79], v[116:119], v[208:211], v[76:79]
	v_mfma_f32_16x16x32_bf16 v[72:75], v[124:127], v[208:211], v[72:75]
	v_mfma_f32_16x16x32_bf16 v[136:139], v[132:135], v[152:155], v[136:139]
	v_mfma_f32_16x16x32_bf16 v[128:131], v[144:147], v[152:155], v[128:131]
	v_mfma_f32_16x16x32_bf16 v[100:103], v[132:135], v[168:171], v[100:103]
	v_mfma_f32_16x16x32_bf16 v[96:99], v[144:147], v[168:171], v[96:99]
	v_mfma_f32_16x16x32_bf16 v[84:87], v[132:135], v[176:179], v[84:87]
	v_mfma_f32_16x16x32_bf16 v[80:83], v[144:147], v[176:179], v[80:83]
	v_mfma_f32_16x16x32_bf16 v[68:71], v[132:135], v[184:187], v[68:71]
	v_mfma_f32_16x16x32_bf16 v[64:67], v[144:147], v[184:187], v[64:67]
	v_mfma_f32_16x16x32_bf16 v[136:139], v[140:143], v[164:167], v[136:139]
	v_mfma_f32_16x16x32_bf16 v[128:131], v[148:151], v[164:167], v[128:131]
	v_mfma_f32_16x16x32_bf16 v[100:103], v[140:143], v[172:175], v[100:103]
	v_mfma_f32_16x16x32_bf16 v[96:99], v[148:151], v[172:175], v[96:99]
	v_mfma_f32_16x16x32_bf16 v[84:87], v[140:143], v[180:183], v[84:87]
	v_mfma_f32_16x16x32_bf16 v[80:83], v[148:151], v[180:183], v[80:83]
	v_mfma_f32_16x16x32_bf16 v[68:71], v[140:143], v[208:211], v[68:71]
	v_mfma_f32_16x16x32_bf16 v[64:67], v[148:151], v[208:211], v[64:67]
	s_setprio 0
	s_barrier
	s_add_i32 s60, s60, s37
	v_lshl_add_u64 v[212:213], s[28:29], 0, v[188:189]
	s_mov_b32 m0, s60
	ds_read_b128 v[152:155], v241 offset:16384
	ds_read_b128 v[164:167], v241 offset:17408
	ds_read_b128 v[168:171], v241 offset:18432
	ds_read_b128 v[172:175], v241 offset:19456
	ds_read_b128 v[176:179], v241 offset:20480
	ds_read_b128 v[180:183], v241 offset:21504
	ds_read_b128 v[184:187], v241 offset:22528
	ds_read_b128 v[208:211], v241 offset:23552
	global_load_lds_dwordx4 v[212:213], off
	s_add_i32 m0, s60, 0x2000
	s_add_u32 s60, s28, 0x200000
	v_lshl_add_u64 v[214:215], s[28:29], 0, v[198:199]
	s_addc_u32 s61, s29, 0
	s_add_i32 s73, s73, s37
	global_load_lds_dwordx4 v[214:215], off
	v_lshl_add_u64 v[216:217], s[60:61], 0, v[188:189]
	s_mov_b32 m0, s73
	v_lshl_add_u64 v[218:219], s[30:31], 0, v[200:201]
	global_load_lds_dwordx4 v[216:217], off
	v_lshl_add_u64 v[216:217], s[60:61], 0, v[198:199]
	s_add_i32 m0, s73, 0x2000
	s_nop 0
	global_load_lds_dwordx4 v[216:217], off
	v_lshl_add_u64 v[216:217], s[30:31], 0, v[202:203]
	s_mov_b32 m0, s38
	s_nop 0
	global_load_lds_dwordx4 v[216:217], off
	s_mov_b32 m0, s39
	s_nop 0
	global_load_lds_dwordx4 v[218:219], off
	s_waitcnt vmcnt(8)
	s_waitcnt lgkmcnt(0)
	s_barrier
; #define PG8_STAGE(bufoff, gbase, voff) do { _Pragma("unroll") for (int _i = 0; _i < 2; ++_i) \
;         __builtin_amdgcn_global_load_lds((const unsigned*)((const char*)(gbase) + (voff)[_i]), (PG8_LAS unsigned*)(lds + (bufoff) + ldsw + _i * 8192), 16, 0, 0); } while (0)
; #define PG8_LDA(dst, b, h) do { _Pragma("unroll") for (int m = 0; m < 4; ++m) _Pragma("unroll") for (int k = 0; k < 2; ++k) dst[m][k] = *(const PG8_LAS bf16x8*)(lds + PG8_SA(b, h) + aoff + m * 2048 + k * 1024); } while (0)
; #define PG8_LDB(dst, b, h) do { _Pragma("unroll") for (int n = 0; n < 2; ++n) _Pragma("unroll") for (int k = 0; k < 2; ++k) dst[n][k] = *(const PG8_LAS bf16x8*)(lds + PG8_SB(b, h) + boff + n * 2048 + k * 1024); } while (0)
; #define PG8_MMA(ai, bj, At, Bt) do { __builtin_amdgcn_s_setprio(1); _Pragma("unroll") for (int m = 0; m < 4; ++m) _Pragma("unroll") for (int n = 0; n < 2; ++n) _Pragma("unroll") for (int k = 0; k < 2; ++k) \
;         acc[ai][bj][m][n] = __builtin_amdgcn_mfma_f32_16x16x32_bf16(Bt[n][k], At[m][k], acc[ai][bj][m][n], 0, 0, 0); __builtin_amdgcn_s_setprio(0); } while (0)
; #define PG8_WAIT_V(n) asm volatile("s_waitcnt vmcnt(" #n ")" ::: "memory")
; #define PG8_WAIT_L(n) asm volatile("s_waitcnt lgkmcnt(" #n ")" ::: "memory")
; #define PG8_BAR __builtin_amdgcn_s_barrier()
; #define PG8_SCHED __builtin_amdgcn_sched_barrier(0)
; template <class Epi, class Sched, bool ALIGN_EPI = false, bool SP2 = false>
; __device__ __forceinline__ void gemm_phase(PG8_LAS unsigned char* lds, const Gemm g, const Sched& S, const Epi& E) {
;     ...
;             PG8_WAIT_V(8); PG8_WAIT_L(0); PG8_BAR; PG8_MMA(1, 0, At, B0); PG8_MMA(1, 1, At, B1); PG8_BAR; PG8_SCHED;
;             PG8_LDB(B0, 1, 0); PG8_LDB(B1, 1, 1); PG8_SCHED; PG8_LDA(At, 1, 0); PG8_STAGE(PG8_SA(0, 1), a2 + hstep, voffA);
;             PG8_WAIT_V(8); PG8_WAIT_L(0); PG8_BAR; PG8_MMA(0, 0, At, B0); PG8_MMA(0, 1, At, B1); PG8_BAR; PG8_SCHED;
	s_setprio 1
	v_mfma_f32_16x16x32_bf16 v[60:63], v[112:115], v[152:155], v[60:63]
	v_mfma_f32_16x16x32_bf16 v[56:59], v[120:123], v[152:155], v[56:59]
	v_mfma_f32_16x16x32_bf16 v[44:47], v[112:115], v[168:171], v[44:47]
	v_mfma_f32_16x16x32_bf16 v[40:43], v[120:123], v[168:171], v[40:43]
	v_mfma_f32_16x16x32_bf16 v[28:31], v[112:115], v[176:179], v[28:31]
	v_mfma_f32_16x16x32_bf16 v[24:27], v[120:123], v[176:179], v[24:27]
	v_mfma_f32_16x16x32_bf16 v[12:15], v[112:115], v[184:187], v[12:15]
	v_mfma_f32_16x16x32_bf16 v[8:11], v[120:123], v[184:187], v[8:11]
	v_mfma_f32_16x16x32_bf16 v[60:63], v[116:119], v[164:167], v[60:63]
	v_mfma_f32_16x16x32_bf16 v[56:59], v[124:127], v[164:167], v[56:59]
	v_mfma_f32_16x16x32_bf16 v[44:47], v[116:119], v[172:175], v[44:47]
	v_mfma_f32_16x16x32_bf16 v[40:43], v[124:127], v[172:175], v[40:43]
	v_mfma_f32_16x16x32_bf16 v[28:31], v[116:119], v[180:183], v[28:31]
	v_mfma_f32_16x16x32_bf16 v[24:27], v[124:127], v[180:183], v[24:27]
	v_mfma_f32_16x16x32_bf16 v[12:15], v[116:119], v[208:211], v[12:15]
	v_mfma_f32_16x16x32_bf16 v[8:11], v[124:127], v[208:211], v[8:11]
	v_mfma_f32_16x16x32_bf16 v[52:55], v[132:135], v[152:155], v[52:55]
	v_mfma_f32_16x16x32_bf16 v[48:51], v[144:147], v[152:155], v[48:51]
	v_mfma_f32_16x16x32_bf16 v[36:39], v[132:135], v[168:171], v[36:39]
	v_mfma_f32_16x16x32_bf16 v[32:35], v[144:147], v[168:171], v[32:35]
	v_mfma_f32_16x16x32_bf16 v[20:23], v[132:135], v[176:179], v[20:23]
	v_mfma_f32_16x16x32_bf16 v[16:19], v[144:147], v[176:179], v[16:19]
	v_mfma_f32_16x16x32_bf16 v[4:7], v[132:135], v[184:187], v[4:7]
	v_mfma_f32_16x16x32_bf16 v[0:3], v[144:147], v[184:187], v[0:3]
	v_mfma_f32_16x16x32_bf16 v[52:55], v[140:143], v[164:167], v[52:55]
	v_mfma_f32_16x16x32_bf16 v[48:51], v[148:151], v[164:167], v[48:51]
	v_mfma_f32_16x16x32_bf16 v[36:39], v[140:143], v[172:175], v[36:39]
	v_mfma_f32_16x16x32_bf16 v[32:35], v[148:151], v[172:175], v[32:35]
	v_mfma_f32_16x16x32_bf16 v[20:23], v[140:143], v[180:183], v[20:23]
	v_mfma_f32_16x16x32_bf16 v[16:19], v[148:151], v[180:183], v[16:19]
	v_mfma_f32_16x16x32_bf16 v[4:7], v[140:143], v[208:211], v[4:7]
	v_mfma_f32_16x16x32_bf16 v[0:3], v[148:151], v[208:211], v[0:3]
	s_setprio 0
	s_barrier
	s_add_i32 s60, 0, 0x18000
	s_add_i32 s61, 0, 0x1c000
	v_add_u32_e32 v124, s60, v239
	v_add_u32_e32 v148, s61, v239
	ds_read_b128 v[112:115], v124
	ds_read_b128 v[116:119], v124 offset:1024
	ds_read_b128 v[120:123], v124 offset:2048
	ds_read_b128 v[124:127], v124 offset:3072
	ds_read_b128 v[132:135], v148
	ds_read_b128 v[140:143], v148 offset:1024
	ds_read_b128 v[144:147], v148 offset:2048
	ds_read_b128 v[148:151], v148 offset:3072
	s_add_u32 s30, s30, 0x200000
	s_addc_u32 s31, s31, 0
	s_mov_b32 m0, s40
	v_lshl_add_u64 v[220:221], s[30:31], 0, v[202:203]
	ds_read_b128 v[152:155], v241 offset:32768
	ds_read_b128 v[164:167], v241 offset:33792
	ds_read_b128 v[168:171], v241 offset:34816
	ds_read_b128 v[172:175], v241 offset:35840
	ds_read_b128 v[176:179], v241 offset:36864
	ds_read_b128 v[180:183], v241 offset:37888
	ds_read_b128 v[184:187], v241 offset:38912
	ds_read_b128 v[208:211], v241 offset:39936
	global_load_lds_dwordx4 v[220:221], off
	v_lshl_add_u64 v[220:221], s[30:31], 0, v[200:201]
	s_mov_b32 m0, s41
	s_nop 0
	global_load_lds_dwordx4 v[220:221], off
	s_waitcnt vmcnt(8)
	s_waitcnt lgkmcnt(0)
	s_barrier
	s_setprio 1
	v_mfma_f32_16x16x32_bf16 v[160:163], v[112:115], v[152:155], v[160:163]
	v_mfma_f32_16x16x32_bf16 v[156:159], v[120:123], v[152:155], v[156:159]
	v_mfma_f32_16x16x32_bf16 v[108:111], v[112:115], v[168:171], v[108:111]
	v_mfma_f32_16x16x32_bf16 v[104:107], v[120:123], v[168:171], v[104:107]
	v_mfma_f32_16x16x32_bf16 v[92:95], v[112:115], v[176:179], v[92:95]
	v_mfma_f32_16x16x32_bf16 v[88:91], v[120:123], v[176:179], v[88:91]
	v_mfma_f32_16x16x32_bf16 v[76:79], v[112:115], v[184:187], v[76:79]
	v_mfma_f32_16x16x32_bf16 v[72:75], v[120:123], v[184:187], v[72:75]
	v_mfma_f32_16x16x32_bf16 v[160:163], v[116:119], v[164:167], v[160:163]
	v_mfma_f32_16x16x32_bf16 v[156:159], v[124:127], v[164:167], v[156:159]
	v_mfma_f32_16x16x32_bf16 v[108:111], v[116:119], v[172:175], v[108:111]
	v_mfma_f32_16x16x32_bf16 v[104:107], v[124:127], v[172:175], v[104:107]
	v_mfma_f32_16x16x32_bf16 v[92:95], v[116:119], v[180:183], v[92:95]
	v_mfma_f32_16x16x32_bf16 v[88:91], v[124:127], v[180:183], v[88:91]
	v_mfma_f32_16x16x32_bf16 v[76:79], v[116:119], v[208:211], v[76:79]
	v_mfma_f32_16x16x32_bf16 v[72:75], v[124:127], v[208:211], v[72:75]
	v_mfma_f32_16x16x32_bf16 v[136:139], v[132:135], v[152:155], v[136:139]
	v_mfma_f32_16x16x32_bf16 v[128:131], v[144:147], v[152:155], v[128:131]
	v_mfma_f32_16x16x32_bf16 v[100:103], v[132:135], v[168:171], v[100:103]
	v_mfma_f32_16x16x32_bf16 v[96:99], v[144:147], v[168:171], v[96:99]
	v_mfma_f32_16x16x32_bf16 v[84:87], v[132:135], v[176:179], v[84:87]
	v_mfma_f32_16x16x32_bf16 v[80:83], v[144:147], v[176:179], v[80:83]
	v_mfma_f32_16x16x32_bf16 v[68:71], v[132:135], v[184:187], v[68:71]
	v_mfma_f32_16x16x32_bf16 v[64:67], v[144:147], v[184:187], v[64:67]
	v_mfma_f32_16x16x32_bf16 v[136:139], v[140:143], v[164:167], v[136:139]
	v_mfma_f32_16x16x32_bf16 v[128:131], v[148:151], v[164:167], v[128:131]
	v_mfma_f32_16x16x32_bf16 v[100:103], v[140:143], v[172:175], v[100:103]
	v_mfma_f32_16x16x32_bf16 v[96:99], v[148:151], v[172:175], v[96:99]
	v_mfma_f32_16x16x32_bf16 v[84:87], v[140:143], v[180:183], v[84:87]
	v_mfma_f32_16x16x32_bf16 v[80:83], v[148:151], v[180:183], v[80:83]
	v_mfma_f32_16x16x32_bf16 v[68:71], v[140:143], v[208:211], v[68:71]
	v_mfma_f32_16x16x32_bf16 v[64:67], v[148:151], v[208:211], v[64:67]
	s_setprio 0
	s_barrier
; #define PG8_STAGE(bufoff, gbase, voff) do { _Pragma("unroll") for (int _i = 0; _i < 2; ++_i) \
;         __builtin_amdgcn_global_load_lds((const unsigned*)((const char*)(gbase) + (voff)[_i]), (PG8_LAS unsigned*)(lds + (bufoff) + ldsw + _i * 8192), 16, 0, 0); } while (0)
; #define PG8_LDA(dst, b, h) do { _Pragma("unroll") for (int m = 0; m < 4; ++m) _Pragma("unroll") for (int k = 0; k < 2; ++k) dst[m][k] = *(const PG8_LAS bf16x8*)(lds + PG8_SA(b, h) + aoff + m * 2048 + k * 1024); } while (0)
; #define PG8_MMA(ai, bj, At, Bt) do { __builtin_amdgcn_s_setprio(1); _Pragma("unroll") for (int m = 0; m < 4; ++m) _Pragma("unroll") for (int n = 0; n < 2; ++n) _Pragma("unroll") for (int k = 0; k < 2; ++k) \
;         acc[ai][bj][m][n] = __builtin_amdgcn_mfma_f32_16x16x32_bf16(Bt[n][k], At[m][k], acc[ai][bj][m][n], 0, 0, 0); __builtin_amdgcn_s_setprio(0); } while (0)
; #define PG8_WAIT_V(n) asm volatile("s_waitcnt vmcnt(" #n ")" ::: "memory")
; #define PG8_WAIT_L(n) asm volatile("s_waitcnt lgkmcnt(" #n ")" ::: "memory")
; #define PG8_BAR __builtin_amdgcn_s_barrier()
; #define PG8_SCHED __builtin_amdgcn_sched_barrier(0)
; template <class Epi, class Sched, bool ALIGN_EPI = false, bool SP2 = false>
; __device__ __forceinline__ void gemm_phase(PG8_LAS unsigned char* lds, const Gemm g, const Sched& S, const Epi& E) {
;     ...
;             PG8_LDA(At, 1, 1); PG8_STAGE(PG8_SB(1, 0), b3, voffB); PG8_STAGE(PG8_SB(1, 1), b3 + hstep, voffB); PG8_STAGE(PG8_SA(1, 0), a3, voffA);
;             PG8_WAIT_V(8); PG8_WAIT_L(0); PG8_BAR; PG8_MMA(1, 0, At, B0); PG8_MMA(1, 1, At, B1); PG8_BAR; PG8_SCHED;
	s_add_i32 s30, s60, s37
	v_lshl_add_u64 v[212:213], v[212:213], 0, s[78:79]
	s_mov_b32 m0, s30
	ds_read_b128 v[152:155], v241 offset:49152
	ds_read_b128 v[164:167], v241 offset:50176
	ds_read_b128 v[168:171], v241 offset:51200
	ds_read_b128 v[172:175], v241 offset:52224
	ds_read_b128 v[176:179], v241 offset:53248
	ds_read_b128 v[180:183], v241 offset:54272
	ds_read_b128 v[184:187], v241 offset:55296
	ds_read_b128 v[208:211], v241 offset:56320
	global_load_lds_dwordx4 v[212:213], off
	s_add_i32 m0, s30, 0x2000
	s_add_u32 s28, s28, 0x200080
	v_lshl_add_u64 v[212:213], v[214:215], 0, s[78:79]
	s_addc_u32 s29, s29, 0
	s_add_i32 s30, s61, s37
	global_load_lds_dwordx4 v[212:213], off
	v_lshl_add_u64 v[212:213], s[28:29], 0, v[188:189]
	s_mov_b32 m0, s30
	s_nop 0
	global_load_lds_dwordx4 v[212:213], off
	v_lshl_add_u64 v[212:213], s[28:29], 0, v[198:199]
	s_add_i32 m0, s30, 0x2000
	s_nop 0
	global_load_lds_dwordx4 v[212:213], off
	v_lshl_add_u64 v[212:213], v[216:217], 0, s[78:79]
	s_mov_b32 m0, s44
	s_nop 0
	global_load_lds_dwordx4 v[212:213], off
	v_lshl_add_u64 v[212:213], v[218:219], 0, s[78:79]
	s_mov_b32 m0, s45
	s_nop 0
	global_load_lds_dwordx4 v[212:213], off
	s_nop 0
	s_waitcnt vmcnt(8)
	s_waitcnt lgkmcnt(0)
	s_barrier
	s_setprio 1
	v_mfma_f32_16x16x32_bf16 v[60:63], v[112:115], v[152:155], v[60:63]
	v_mfma_f32_16x16x32_bf16 v[56:59], v[120:123], v[152:155], v[56:59]
	v_mfma_f32_16x16x32_bf16 v[44:47], v[112:115], v[168:171], v[44:47]
	v_mfma_f32_16x16x32_bf16 v[40:43], v[120:123], v[168:171], v[40:43]
	v_mfma_f32_16x16x32_bf16 v[28:31], v[112:115], v[176:179], v[28:31]
	v_mfma_f32_16x16x32_bf16 v[24:27], v[120:123], v[176:179], v[24:27]
	v_mfma_f32_16x16x32_bf16 v[12:15], v[112:115], v[184:187], v[12:15]
	v_mfma_f32_16x16x32_bf16 v[8:11], v[120:123], v[184:187], v[8:11]
	v_mfma_f32_16x16x32_bf16 v[60:63], v[116:119], v[164:167], v[60:63]
	v_mfma_f32_16x16x32_bf16 v[56:59], v[124:127], v[164:167], v[56:59]
	v_mfma_f32_16x16x32_bf16 v[44:47], v[116:119], v[172:175], v[44:47]
	v_mfma_f32_16x16x32_bf16 v[40:43], v[124:127], v[172:175], v[40:43]
	v_mfma_f32_16x16x32_bf16 v[28:31], v[116:119], v[180:183], v[28:31]
	v_mfma_f32_16x16x32_bf16 v[24:27], v[124:127], v[180:183], v[24:27]
	v_mfma_f32_16x16x32_bf16 v[12:15], v[116:119], v[208:211], v[12:15]
	v_mfma_f32_16x16x32_bf16 v[8:11], v[124:127], v[208:211], v[8:11]
	v_mfma_f32_16x16x32_bf16 v[52:55], v[132:135], v[152:155], v[52:55]
	v_mfma_f32_16x16x32_bf16 v[48:51], v[144:147], v[152:155], v[48:51]
	v_mfma_f32_16x16x32_bf16 v[36:39], v[132:135], v[168:171], v[36:39]
	v_mfma_f32_16x16x32_bf16 v[32:35], v[144:147], v[168:171], v[32:35]
	v_mfma_f32_16x16x32_bf16 v[20:23], v[132:135], v[176:179], v[20:23]
	v_mfma_f32_16x16x32_bf16 v[16:19], v[144:147], v[176:179], v[16:19]
	v_mfma_f32_16x16x32_bf16 v[4:7], v[132:135], v[184:187], v[4:7]
	v_mfma_f32_16x16x32_bf16 v[0:3], v[144:147], v[184:187], v[0:3]
	v_mfma_f32_16x16x32_bf16 v[52:55], v[140:143], v[164:167], v[52:55]
	v_mfma_f32_16x16x32_bf16 v[48:51], v[148:151], v[164:167], v[48:51]
	v_mfma_f32_16x16x32_bf16 v[36:39], v[140:143], v[172:175], v[36:39]
	v_mfma_f32_16x16x32_bf16 v[32:35], v[148:151], v[172:175], v[32:35]
	v_mfma_f32_16x16x32_bf16 v[20:23], v[140:143], v[180:183], v[20:23]
	v_mfma_f32_16x16x32_bf16 v[16:19], v[148:151], v[180:183], v[16:19]
	v_mfma_f32_16x16x32_bf16 v[4:7], v[140:143], v[208:211], v[4:7]
	v_mfma_f32_16x16x32_bf16 v[0:3], v[148:151], v[208:211], v[0:3]
	s_setprio 0
	s_barrier
	s_add_i32 s72, s72, 2
	s_add_u32 s26, s26, 0x100
	s_addc_u32 s27, s27, 0
	s_add_u32 s67, s67, 0x100
	s_addc_u32 s68, s68, 0
	s_cmpk_gt_u32 s72, 0x7d
	s_cbranch_scc0 .LBB0_757
	s_and_b64 vcc, exec, s[16:17]
	s_cbranch_vccz .LBB0_760
	s_barrier

; #define PG8_STAGE(bufoff, gbase, voff) do { _Pragma("unroll") for (int _i = 0; _i < 2; ++_i) \
;         __builtin_amdgcn_global_load_lds((const unsigned*)((const char*)(gbase) + (voff)[_i]), (PG8_LAS unsigned*)(lds + (bufoff) + ldsw + _i * 8192), 16, 0, 0); } while (0)
; #define PG8_LDA(dst, b, h) do { _Pragma("unroll") for (int m = 0; m < 4; ++m) _Pragma("unroll") for (int k = 0; k < 2; ++k) dst[m][k] = *(const PG8_LAS bf16x8*)(lds + PG8_SA(b, h) + aoff + m * 2048 + k * 1024); } while (0)
; #define PG8_LDB(dst, b, h) do { _Pragma("unroll") for (int n = 0; n < 2; ++n) _Pragma("unroll") for (int k = 0; k < 2; ++k) dst[n][k] = *(const PG8_LAS bf16x8*)(lds + PG8_SB(b, h) + boff + n * 2048 + k * 1024); } while (0)
; #define PG8_MMA(ai, bj, At, Bt) do { __builtin_amdgcn_s_setprio(1); _Pragma("unroll") for (int m = 0; m < 4; ++m) _Pragma("unroll") for (int n = 0; n < 2; ++n) _Pragma("unroll") for (int k = 0; k < 2; ++k) \
;         acc[ai][bj][m][n] = __builtin_amdgcn_mfma_f32_16x16x32_bf16(Bt[n][k], At[m][k], acc[ai][bj][m][n], 0, 0, 0); __builtin_amdgcn_s_setprio(0); } while (0)
; #define PG8_WAIT_V(n) asm volatile("s_waitcnt vmcnt(" #n ")" ::: "memory")
; #define PG8_WAIT_L(n) asm volatile("s_waitcnt lgkmcnt(" #n ")" ::: "memory")
; #define PG8_BAR __builtin_amdgcn_s_barrier()
; #define PG8_SCHED __builtin_amdgcn_sched_barrier(0)
; template <class Epi, class Sched, bool ALIGN_EPI = false, bool SP2 = false>
; __device__ __forceinline__ void gemm_phase(PG8_LAS unsigned char* lds, const Gemm g, const Sched& S, const Epi& E) {
;     ...
;             const bool last = (t == nt - 2);
;             const char* a1 = cA + (size_t)(t + 1) * kstep;
;             const char* a2 = last ? nA : cA + (size_t)(t + 2) * kstep; const char* b2 = last ? nB : cB + (size_t)(t + 2) * kstep;
;             const char* a3 = a2 + kstep; const char* b3 = b2 + kstep;
;             if (last && has_next) S.a_ready(nxt);
;             if constexpr (SP2) {
;             PG8_LDB(B0, 0, 0); PG8_LDB(B1, 0, 1); PG8_SCHED; PG8_LDA(At, 0, 0); PG8_STAGE(PG8_SA(1, 1), a1 + hstep, voffA);
;             PG8_WAIT_V(8); PG8_WAIT_L(0); PG8_BAR; PG8_MMA(0, 0, At, B0); PG8_MMA(0, 1, At, B1); PG8_BAR; PG8_SCHED;
;             PG8_LDA(At, 0, 1); PG8_STAGE(PG8_SB(0, 0), b2, voffB); PG8_STAGE(PG8_SB(0, 1), b2 + hstep, voffB); PG8_STAGE(PG8_SA(0, 0), a2, voffA);
.LBB0_851:
	s_add_i32 s63, s24, 2
	s_add_u32 s60, s22, 0x80
	s_addc_u32 s25, s23, 0
	s_add_i32 s66, 0, 0x10000
	s_cmp_eq_u32 s39, s24
	s_cselect_b32 s25, s7, s25
	s_cselect_b32 s24, s6, s60
	s_cselect_b32 s61, s21, s62
	s_cselect_b32 s60, s20, s58
	s_add_i32 s67, 0, 0x14000
	v_add_u32_e32 v154, s66, v139
	v_add_u32_e32 v170, s67, v139
	ds_read_b128 v[142:145], v154
	ds_read_b128 v[146:149], v154 offset:1024
	ds_read_b128 v[150:153], v154 offset:2048
	ds_read_b128 v[154:157], v154 offset:3072
	ds_read_b128 v[158:161], v170
	ds_read_b128 v[162:165], v170 offset:1024
	ds_read_b128 v[166:169], v170 offset:2048
	ds_read_b128 v[170:173], v170 offset:3072
	v_lshl_add_u64 v[186:187], s[22:23], 0, v[134:135]
	s_add_i32 m0, s30, 0xc000
	ds_read_b128 v[174:177], v141
	ds_read_b128 v[178:181], v141 offset:1024
	ds_read_b128 v[182:185], v141 offset:2048
	ds_read_b128 v[198:201], v141 offset:3072
	ds_read_b128 v[202:205], v141 offset:4096
	ds_read_b128 v[206:209], v141 offset:5120
	ds_read_b128 v[210:213], v141 offset:6144
	ds_read_b128 v[214:217], v141 offset:7168
	global_load_lds_dwordx4 v[186:187], off
	v_lshl_add_u64 v[186:187], s[22:23], 0, v[136:137]
	s_add_i32 m0, s30, 0xe000
	s_nop 0
	global_load_lds_dwordx4 v[186:187], off
	s_waitcnt vmcnt(8)
	s_waitcnt lgkmcnt(0)
	s_barrier
	s_setprio 1
	v_mfma_f32_16x16x32_bf16 v[120:123], v[142:145], v[174:177], v[120:123]
	v_mfma_f32_16x16x32_bf16 v[124:127], v[150:153], v[174:177], v[124:127]
	v_mfma_f32_16x16x32_bf16 v[108:111], v[142:145], v[182:185], v[108:111]
	v_mfma_f32_16x16x32_bf16 v[104:107], v[150:153], v[182:185], v[104:107]
	v_mfma_f32_16x16x32_bf16 v[92:95], v[142:145], v[202:205], v[92:95]
	v_mfma_f32_16x16x32_bf16 v[88:91], v[150:153], v[202:205], v[88:91]
	v_mfma_f32_16x16x32_bf16 v[76:79], v[142:145], v[210:213], v[76:79]
	v_mfma_f32_16x16x32_bf16 v[72:75], v[150:153], v[210:213], v[72:75]
	v_mfma_f32_16x16x32_bf16 v[120:123], v[146:149], v[178:181], v[120:123]
	v_mfma_f32_16x16x32_bf16 v[124:127], v[154:157], v[178:181], v[124:127]
	v_mfma_f32_16x16x32_bf16 v[108:111], v[146:149], v[198:201], v[108:111]
	v_mfma_f32_16x16x32_bf16 v[104:107], v[154:157], v[198:201], v[104:107]
	v_mfma_f32_16x16x32_bf16 v[92:95], v[146:149], v[206:209], v[92:95]
	v_mfma_f32_16x16x32_bf16 v[88:91], v[154:157], v[206:209], v[88:91]
	v_mfma_f32_16x16x32_bf16 v[76:79], v[146:149], v[214:217], v[76:79]
	v_mfma_f32_16x16x32_bf16 v[72:75], v[154:157], v[214:217], v[72:75]
	v_mfma_f32_16x16x32_bf16 v[116:119], v[158:161], v[174:177], v[116:119]
	v_mfma_f32_16x16x32_bf16 v[112:115], v[166:169], v[174:177], v[112:115]
	v_mfma_f32_16x16x32_bf16 v[100:103], v[158:161], v[182:185], v[100:103]
	v_mfma_f32_16x16x32_bf16 v[96:99], v[166:169], v[182:185], v[96:99]
	v_mfma_f32_16x16x32_bf16 v[84:87], v[158:161], v[202:205], v[84:87]
	v_mfma_f32_16x16x32_bf16 v[80:83], v[166:169], v[202:205], v[80:83]
	v_mfma_f32_16x16x32_bf16 v[68:71], v[158:161], v[210:213], v[68:71]
	v_mfma_f32_16x16x32_bf16 v[64:67], v[166:169], v[210:213], v[64:67]
	v_mfma_f32_16x16x32_bf16 v[116:119], v[162:165], v[178:181], v[116:119]
	v_mfma_f32_16x16x32_bf16 v[112:115], v[170:173], v[178:181], v[112:115]
	v_mfma_f32_16x16x32_bf16 v[100:103], v[162:165], v[198:201], v[100:103]
	v_mfma_f32_16x16x32_bf16 v[96:99], v[170:173], v[198:201], v[96:99]
	v_mfma_f32_16x16x32_bf16 v[84:87], v[162:165], v[206:209], v[84:87]
	v_mfma_f32_16x16x32_bf16 v[80:83], v[170:173], v[206:209], v[80:83]
	v_mfma_f32_16x16x32_bf16 v[68:71], v[162:165], v[214:217], v[68:71]
	v_mfma_f32_16x16x32_bf16 v[64:67], v[170:173], v[214:217], v[64:67]
	s_setprio 0
	s_barrier
	s_add_i32 s66, s66, s29
	v_lshl_add_u64 v[186:187], s[60:61], 0, v[188:189]
	s_mov_b32 m0, s66
	ds_read_b128 v[174:177], v141 offset:16384
	ds_read_b128 v[178:181], v141 offset:17408
	ds_read_b128 v[182:185], v141 offset:18432
	ds_read_b128 v[198:201], v141 offset:19456
	ds_read_b128 v[202:205], v141 offset:20480
	ds_read_b128 v[206:209], v141 offset:21504
	ds_read_b128 v[210:213], v141 offset:22528
	ds_read_b128 v[214:217], v141 offset:23552
	global_load_lds_dwordx4 v[186:187], off
	s_add_i32 m0, s66, 0x2000
	v_lshl_add_u64 v[218:219], s[60:61], 0, v[128:129]
	s_add_u32 s60, s60, s0
	s_addc_u32 s61, s61, s1
	s_add_i32 s66, s67, s29
	global_load_lds_dwordx4 v[218:219], off
	v_lshl_add_u64 v[220:221], s[60:61], 0, v[188:189]
	s_mov_b32 m0, s66
	v_lshl_add_u64 v[222:223], s[60:61], 0, v[128:129]
	global_load_lds_dwordx4 v[220:221], off
	s_add_i32 m0, s66, 0x2000
	v_lshl_add_u64 v[224:225], s[24:25], 0, v[132:133]
	global_load_lds_dwordx4 v[222:223], off
	s_mov_b32 m0, s30
	v_lshl_add_u64 v[226:227], s[24:25], 0, v[130:131]
	global_load_lds_dwordx4 v[224:225], off
	s_mov_b32 m0, s31
	s_nop 0
	global_load_lds_dwordx4 v[226:227], off
	s_nop 0
	s_waitcnt vmcnt(8)
	s_waitcnt lgkmcnt(0)
	s_barrier
; #define PG8_STAGE(bufoff, gbase, voff) do { _Pragma("unroll") for (int _i = 0; _i < 2; ++_i) \
;         __builtin_amdgcn_global_load_lds((const unsigned*)((const char*)(gbase) + (voff)[_i]), (PG8_LAS unsigned*)(lds + (bufoff) + ldsw + _i * 8192), 16, 0, 0); } while (0)
; #define PG8_LDA(dst, b, h) do { _Pragma("unroll") for (int m = 0; m < 4; ++m) _Pragma("unroll") for (int k = 0; k < 2; ++k) dst[m][k] = *(const PG8_LAS bf16x8*)(lds + PG8_SA(b, h) + aoff + m * 2048 + k * 1024); } while (0)
; #define PG8_LDB(dst, b, h) do { _Pragma("unroll") for (int n = 0; n < 2; ++n) _Pragma("unroll") for (int k = 0; k < 2; ++k) dst[n][k] = *(const PG8_LAS bf16x8*)(lds + PG8_SB(b, h) + boff + n * 2048 + k * 1024); } while (0)
; #define PG8_MMA(ai, bj, At, Bt) do { __builtin_amdgcn_s_setprio(1); _Pragma("unroll") for (int m = 0; m < 4; ++m) _Pragma("unroll") for (int n = 0; n < 2; ++n) _Pragma("unroll") for (int k = 0; k < 2; ++k) \
;         acc[ai][bj][m][n] = __builtin_amdgcn_mfma_f32_16x16x32_bf16(Bt[n][k], At[m][k], acc[ai][bj][m][n], 0, 0, 0); __builtin_amdgcn_s_setprio(0); } while (0)
; #define PG8_WAIT_V(n) asm volatile("s_waitcnt vmcnt(" #n ")" ::: "memory")
; #define PG8_WAIT_L(n) asm volatile("s_waitcnt lgkmcnt(" #n ")" ::: "memory")
; #define PG8_BAR __builtin_amdgcn_s_barrier()
; #define PG8_SCHED __builtin_amdgcn_sched_barrier(0)
; template <class Epi, class Sched, bool ALIGN_EPI = false, bool SP2 = false>
; __device__ __forceinline__ void gemm_phase(PG8_LAS unsigned char* lds, const Gemm g, const Sched& S, const Epi& E) {
;     ...
;             PG8_WAIT_V(8); PG8_WAIT_L(0); PG8_BAR; PG8_MMA(1, 0, At, B0); PG8_MMA(1, 1, At, B1); PG8_BAR; PG8_SCHED;
;             PG8_LDB(B0, 1, 0); PG8_LDB(B1, 1, 1); PG8_SCHED; PG8_LDA(At, 1, 0); PG8_STAGE(PG8_SA(0, 1), a2 + hstep, voffA);
;             PG8_WAIT_V(8); PG8_WAIT_L(0); PG8_BAR; PG8_MMA(0, 0, At, B0); PG8_MMA(0, 1, At, B1); PG8_BAR; PG8_SCHED;
	s_setprio 1
	v_mfma_f32_16x16x32_bf16 v[60:63], v[142:145], v[174:177], v[60:63]
	v_mfma_f32_16x16x32_bf16 v[56:59], v[150:153], v[174:177], v[56:59]
	v_mfma_f32_16x16x32_bf16 v[44:47], v[142:145], v[182:185], v[44:47]
	v_mfma_f32_16x16x32_bf16 v[40:43], v[150:153], v[182:185], v[40:43]
	v_mfma_f32_16x16x32_bf16 v[28:31], v[142:145], v[202:205], v[28:31]
	v_mfma_f32_16x16x32_bf16 v[24:27], v[150:153], v[202:205], v[24:27]
	v_mfma_f32_16x16x32_bf16 v[12:15], v[142:145], v[210:213], v[12:15]
	v_mfma_f32_16x16x32_bf16 v[8:11], v[150:153], v[210:213], v[8:11]
	v_mfma_f32_16x16x32_bf16 v[60:63], v[146:149], v[178:181], v[60:63]
	v_mfma_f32_16x16x32_bf16 v[56:59], v[154:157], v[178:181], v[56:59]
	v_mfma_f32_16x16x32_bf16 v[44:47], v[146:149], v[198:201], v[44:47]
	v_mfma_f32_16x16x32_bf16 v[40:43], v[154:157], v[198:201], v[40:43]
	v_mfma_f32_16x16x32_bf16 v[28:31], v[146:149], v[206:209], v[28:31]
	v_mfma_f32_16x16x32_bf16 v[24:27], v[154:157], v[206:209], v[24:27]
	v_mfma_f32_16x16x32_bf16 v[12:15], v[146:149], v[214:217], v[12:15]
	v_mfma_f32_16x16x32_bf16 v[8:11], v[154:157], v[214:217], v[8:11]
	v_mfma_f32_16x16x32_bf16 v[52:55], v[158:161], v[174:177], v[52:55]
	v_mfma_f32_16x16x32_bf16 v[48:51], v[166:169], v[174:177], v[48:51]
	v_mfma_f32_16x16x32_bf16 v[36:39], v[158:161], v[182:185], v[36:39]
	v_mfma_f32_16x16x32_bf16 v[32:35], v[166:169], v[182:185], v[32:35]
	v_mfma_f32_16x16x32_bf16 v[20:23], v[158:161], v[202:205], v[20:23]
	v_mfma_f32_16x16x32_bf16 v[16:19], v[166:169], v[202:205], v[16:19]
	v_mfma_f32_16x16x32_bf16 v[4:7], v[158:161], v[210:213], v[4:7]
	v_mfma_f32_16x16x32_bf16 v[0:3], v[166:169], v[210:213], v[0:3]
	v_mfma_f32_16x16x32_bf16 v[52:55], v[162:165], v[178:181], v[52:55]
	v_mfma_f32_16x16x32_bf16 v[48:51], v[170:173], v[178:181], v[48:51]
	v_mfma_f32_16x16x32_bf16 v[36:39], v[162:165], v[198:201], v[36:39]
	v_mfma_f32_16x16x32_bf16 v[32:35], v[170:173], v[198:201], v[32:35]
	v_mfma_f32_16x16x32_bf16 v[20:23], v[162:165], v[206:209], v[20:23]
	v_mfma_f32_16x16x32_bf16 v[16:19], v[170:173], v[206:209], v[16:19]
	v_mfma_f32_16x16x32_bf16 v[4:7], v[162:165], v[214:217], v[4:7]
	v_mfma_f32_16x16x32_bf16 v[0:3], v[170:173], v[214:217], v[0:3]
	s_setprio 0
	s_barrier
	s_add_i32 s60, 0, 0x18000
	s_add_i32 s61, 0, 0x1c000
	v_add_u32_e32 v154, s60, v139
	v_add_u32_e32 v170, s61, v139
	ds_read_b128 v[142:145], v154
	ds_read_b128 v[146:149], v154 offset:1024
	ds_read_b128 v[150:153], v154 offset:2048
	ds_read_b128 v[154:157], v154 offset:3072
	ds_read_b128 v[158:161], v170
	ds_read_b128 v[162:165], v170 offset:1024
	ds_read_b128 v[166:169], v170 offset:2048
	ds_read_b128 v[170:173], v170 offset:3072
	s_add_u32 s24, s24, s0
	s_addc_u32 s25, s25, s1
	s_mov_b32 m0, s34
	v_lshl_add_u64 v[228:229], s[24:25], 0, v[132:133]
	ds_read_b128 v[174:177], v141 offset:32768
	ds_read_b128 v[178:181], v141 offset:33792
	ds_read_b128 v[182:185], v141 offset:34816
	ds_read_b128 v[198:201], v141 offset:35840
	ds_read_b128 v[202:205], v141 offset:36864
	ds_read_b128 v[206:209], v141 offset:37888
	ds_read_b128 v[210:213], v141 offset:38912
	ds_read_b128 v[214:217], v141 offset:39936
	global_load_lds_dwordx4 v[228:229], off
	v_lshl_add_u64 v[228:229], s[24:25], 0, v[130:131]
	s_mov_b32 m0, s35
	s_nop 0
	global_load_lds_dwordx4 v[228:229], off
	s_nop 0
	s_waitcnt vmcnt(8)
	s_waitcnt lgkmcnt(0)
	s_barrier
	s_setprio 1
	v_mfma_f32_16x16x32_bf16 v[120:123], v[142:145], v[174:177], v[120:123]
	v_mfma_f32_16x16x32_bf16 v[124:127], v[150:153], v[174:177], v[124:127]
	v_mfma_f32_16x16x32_bf16 v[108:111], v[142:145], v[182:185], v[108:111]
	v_mfma_f32_16x16x32_bf16 v[104:107], v[150:153], v[182:185], v[104:107]
	v_mfma_f32_16x16x32_bf16 v[92:95], v[142:145], v[202:205], v[92:95]
	v_mfma_f32_16x16x32_bf16 v[88:91], v[150:153], v[202:205], v[88:91]
	v_mfma_f32_16x16x32_bf16 v[76:79], v[142:145], v[210:213], v[76:79]
	v_mfma_f32_16x16x32_bf16 v[72:75], v[150:153], v[210:213], v[72:75]
	v_mfma_f32_16x16x32_bf16 v[120:123], v[146:149], v[178:181], v[120:123]
	v_mfma_f32_16x16x32_bf16 v[124:127], v[154:157], v[178:181], v[124:127]
	v_mfma_f32_16x16x32_bf16 v[108:111], v[146:149], v[198:201], v[108:111]
	v_mfma_f32_16x16x32_bf16 v[104:107], v[154:157], v[198:201], v[104:107]
	v_mfma_f32_16x16x32_bf16 v[92:95], v[146:149], v[206:209], v[92:95]
	v_mfma_f32_16x16x32_bf16 v[88:91], v[154:157], v[206:209], v[88:91]
	v_mfma_f32_16x16x32_bf16 v[76:79], v[146:149], v[214:217], v[76:79]
	v_mfma_f32_16x16x32_bf16 v[72:75], v[154:157], v[214:217], v[72:75]
	v_mfma_f32_16x16x32_bf16 v[116:119], v[158:161], v[174:177], v[116:119]
	v_mfma_f32_16x16x32_bf16 v[112:115], v[166:169], v[174:177], v[112:115]
	v_mfma_f32_16x16x32_bf16 v[100:103], v[158:161], v[182:185], v[100:103]
	v_mfma_f32_16x16x32_bf16 v[96:99], v[166:169], v[182:185], v[96:99]
	v_mfma_f32_16x16x32_bf16 v[84:87], v[158:161], v[202:205], v[84:87]
	v_mfma_f32_16x16x32_bf16 v[80:83], v[166:169], v[202:205], v[80:83]
	v_mfma_f32_16x16x32_bf16 v[68:71], v[158:161], v[210:213], v[68:71]
	v_mfma_f32_16x16x32_bf16 v[64:67], v[166:169], v[210:213], v[64:67]
	v_mfma_f32_16x16x32_bf16 v[116:119], v[162:165], v[178:181], v[116:119]
	v_mfma_f32_16x16x32_bf16 v[112:115], v[170:173], v[178:181], v[112:115]
	v_mfma_f32_16x16x32_bf16 v[100:103], v[162:165], v[198:201], v[100:103]
	v_mfma_f32_16x16x32_bf16 v[96:99], v[170:173], v[198:201], v[96:99]
	v_mfma_f32_16x16x32_bf16 v[84:87], v[162:165], v[206:209], v[84:87]
	v_mfma_f32_16x16x32_bf16 v[80:83], v[170:173], v[206:209], v[80:83]
	v_mfma_f32_16x16x32_bf16 v[68:71], v[162:165], v[214:217], v[68:71]
	v_mfma_f32_16x16x32_bf16 v[64:67], v[170:173], v[214:217], v[64:67]
	s_setprio 0
	s_barrier
; #define PG8_STAGE(bufoff, gbase, voff) do { _Pragma("unroll") for (int _i = 0; _i < 2; ++_i) \
;         __builtin_amdgcn_global_load_lds((const unsigned*)((const char*)(gbase) + (voff)[_i]), (PG8_LAS unsigned*)(lds + (bufoff) + ldsw + _i * 8192), 16, 0, 0); } while (0)
; #define PG8_LDA(dst, b, h) do { _Pragma("unroll") for (int m = 0; m < 4; ++m) _Pragma("unroll") for (int k = 0; k < 2; ++k) dst[m][k] = *(const PG8_LAS bf16x8*)(lds + PG8_SA(b, h) + aoff + m * 2048 + k * 1024); } while (0)
; #define PG8_MMA(ai, bj, At, Bt) do { __builtin_amdgcn_s_setprio(1); _Pragma("unroll") for (int m = 0; m < 4; ++m) _Pragma("unroll") for (int n = 0; n < 2; ++n) _Pragma("unroll") for (int k = 0; k < 2; ++k) \
;         acc[ai][bj][m][n] = __builtin_amdgcn_mfma_f32_16x16x32_bf16(Bt[n][k], At[m][k], acc[ai][bj][m][n], 0, 0, 0); __builtin_amdgcn_s_setprio(0); } while (0)
; #define PG8_WAIT_V(n) asm volatile("s_waitcnt vmcnt(" #n ")" ::: "memory")
; #define PG8_WAIT_L(n) asm volatile("s_waitcnt lgkmcnt(" #n ")" ::: "memory")
; #define PG8_BAR __builtin_amdgcn_s_barrier()
; #define PG8_SCHED __builtin_amdgcn_sched_barrier(0)
; template <class Epi, class Sched, bool ALIGN_EPI = false, bool SP2 = false>
; __device__ __forceinline__ void gemm_phase(PG8_LAS unsigned char* lds, const Gemm g, const Sched& S, const Epi& E) {
;     ...
;             PG8_LDA(At, 1, 1); PG8_STAGE(PG8_SB(1, 0), b3, voffB); PG8_STAGE(PG8_SB(1, 1), b3 + hstep, voffB); PG8_STAGE(PG8_SA(1, 0), a3, voffA);
;             PG8_WAIT_V(8); PG8_WAIT_L(0); PG8_BAR; PG8_MMA(1, 0, At, B0); PG8_MMA(1, 1, At, B1); PG8_BAR; PG8_SCHED;
	s_add_i32 s24, s60, s29
	v_lshl_add_u64 v[186:187], v[186:187], 0, s[78:79]
	s_mov_b32 m0, s24
	ds_read_b128 v[174:177], v141 offset:49152
	ds_read_b128 v[178:181], v141 offset:50176
	ds_read_b128 v[182:185], v141 offset:51200
	ds_read_b128 v[198:201], v141 offset:52224
	ds_read_b128 v[202:205], v141 offset:53248
	ds_read_b128 v[206:209], v141 offset:54272
	ds_read_b128 v[210:213], v141 offset:55296
	ds_read_b128 v[214:217], v141 offset:56320
	global_load_lds_dwordx4 v[186:187], off
	v_lshl_add_u64 v[186:187], v[218:219], 0, s[78:79]
	s_add_i32 m0, s24, 0x2000
	s_add_i32 s24, s61, s29
	global_load_lds_dwordx4 v[186:187], off
	v_lshl_add_u64 v[186:187], v[220:221], 0, s[78:79]
	s_mov_b32 m0, s24
	s_nop 0
	global_load_lds_dwordx4 v[186:187], off
	v_lshl_add_u64 v[186:187], v[222:223], 0, s[78:79]
	s_add_i32 m0, s24, 0x2000
	s_nop 0
	global_load_lds_dwordx4 v[186:187], off
	v_lshl_add_u64 v[186:187], v[224:225], 0, s[78:79]
	s_mov_b32 m0, s37
	s_nop 0
	global_load_lds_dwordx4 v[186:187], off
	v_lshl_add_u64 v[186:187], v[226:227], 0, s[78:79]
	s_mov_b32 m0, s38
	s_nop 0
	global_load_lds_dwordx4 v[186:187], off
	s_waitcnt vmcnt(8)
	s_waitcnt lgkmcnt(0)
	s_barrier
	s_setprio 1
	v_mfma_f32_16x16x32_bf16 v[60:63], v[142:145], v[174:177], v[60:63]
	v_mfma_f32_16x16x32_bf16 v[56:59], v[150:153], v[174:177], v[56:59]
	v_mfma_f32_16x16x32_bf16 v[44:47], v[142:145], v[182:185], v[44:47]
	v_mfma_f32_16x16x32_bf16 v[40:43], v[150:153], v[182:185], v[40:43]
	v_mfma_f32_16x16x32_bf16 v[28:31], v[142:145], v[202:205], v[28:31]
	v_mfma_f32_16x16x32_bf16 v[24:27], v[150:153], v[202:205], v[24:27]
	v_mfma_f32_16x16x32_bf16 v[12:15], v[142:145], v[210:213], v[12:15]
	v_mfma_f32_16x16x32_bf16 v[8:11], v[150:153], v[210:213], v[8:11]
	v_mfma_f32_16x16x32_bf16 v[60:63], v[146:149], v[178:181], v[60:63]
	v_mfma_f32_16x16x32_bf16 v[56:59], v[154:157], v[178:181], v[56:59]
	v_mfma_f32_16x16x32_bf16 v[44:47], v[146:149], v[198:201], v[44:47]
	v_mfma_f32_16x16x32_bf16 v[40:43], v[154:157], v[198:201], v[40:43]
	v_mfma_f32_16x16x32_bf16 v[28:31], v[146:149], v[206:209], v[28:31]
	v_mfma_f32_16x16x32_bf16 v[24:27], v[154:157], v[206:209], v[24:27]
	v_mfma_f32_16x16x32_bf16 v[12:15], v[146:149], v[214:217], v[12:15]
	v_mfma_f32_16x16x32_bf16 v[8:11], v[154:157], v[214:217], v[8:11]
	v_mfma_f32_16x16x32_bf16 v[52:55], v[158:161], v[174:177], v[52:55]
	v_mfma_f32_16x16x32_bf16 v[48:51], v[166:169], v[174:177], v[48:51]
	v_mfma_f32_16x16x32_bf16 v[36:39], v[158:161], v[182:185], v[36:39]
	v_mfma_f32_16x16x32_bf16 v[32:35], v[166:169], v[182:185], v[32:35]
	v_mfma_f32_16x16x32_bf16 v[20:23], v[158:161], v[202:205], v[20:23]
	v_mfma_f32_16x16x32_bf16 v[16:19], v[166:169], v[202:205], v[16:19]
	v_mfma_f32_16x16x32_bf16 v[4:7], v[158:161], v[210:213], v[4:7]
	v_mfma_f32_16x16x32_bf16 v[0:3], v[166:169], v[210:213], v[0:3]
	v_mfma_f32_16x16x32_bf16 v[52:55], v[162:165], v[178:181], v[52:55]
	v_mfma_f32_16x16x32_bf16 v[48:51], v[170:173], v[178:181], v[48:51]
	v_mfma_f32_16x16x32_bf16 v[36:39], v[162:165], v[198:201], v[36:39]
	v_mfma_f32_16x16x32_bf16 v[32:35], v[170:173], v[198:201], v[32:35]
	v_mfma_f32_16x16x32_bf16 v[20:23], v[162:165], v[206:209], v[20:23]
	v_mfma_f32_16x16x32_bf16 v[16:19], v[170:173], v[206:209], v[16:19]
	v_mfma_f32_16x16x32_bf16 v[4:7], v[162:165], v[214:217], v[4:7]
	v_mfma_f32_16x16x32_bf16 v[0:3], v[170:173], v[214:217], v[0:3]
	s_setprio 0
	s_barrier
	s_add_u32 s22, s22, 0x100
	s_addc_u32 s23, s23, 0
	s_add_u32 s58, s58, 0x100
	s_addc_u32 s62, s62, 0
	s_cmp_ge_i32 s63, s36
	s_mov_b32 s24, s63
	s_cbranch_scc0 .LBB0_851
	s_mov_b32 s67, 0x20000
	s_mov_b32 s66, 0x30000

; #define PG8_STAGE(bufoff, gbase, voff) do { _Pragma("unroll") for (int _i = 0; _i < 2; ++_i) \
;         __builtin_amdgcn_global_load_lds((const unsigned*)((const char*)(gbase) + (voff)[_i]), (PG8_LAS unsigned*)(lds + (bufoff) + ldsw + _i * 8192), 16, 0, 0); } while (0)
; #define PG8_LDA(dst, b, h) do { _Pragma("unroll") for (int m = 0; m < 4; ++m) _Pragma("unroll") for (int k = 0; k < 2; ++k) dst[m][k] = *(const PG8_LAS bf16x8*)(lds + PG8_SA(b, h) + aoff + m * 2048 + k * 1024); } while (0)
; #define PG8_LDB(dst, b, h) do { _Pragma("unroll") for (int n = 0; n < 2; ++n) _Pragma("unroll") for (int k = 0; k < 2; ++k) dst[n][k] = *(const PG8_LAS bf16x8*)(lds + PG8_SB(b, h) + boff + n * 2048 + k * 1024); } while (0)
; #define PG8_MMA(ai, bj, At, Bt) do { __builtin_amdgcn_s_setprio(1); _Pragma("unroll") for (int m = 0; m < 4; ++m) _Pragma("unroll") for (int n = 0; n < 2; ++n) _Pragma("unroll") for (int k = 0; k < 2; ++k) \
;         acc[ai][bj][m][n] = __builtin_amdgcn_mfma_f32_16x16x32_bf16(Bt[n][k], At[m][k], acc[ai][bj][m][n], 0, 0, 0); __builtin_amdgcn_s_setprio(0); } while (0)
; #define PG8_WAIT_V(n) asm volatile("s_waitcnt vmcnt(" #n ")" ::: "memory")
; #define PG8_WAIT_L(n) asm volatile("s_waitcnt lgkmcnt(" #n ")" ::: "memory")
; #define PG8_BAR __builtin_amdgcn_s_barrier()
; #define PG8_SCHED __builtin_amdgcn_sched_barrier(0)
; template <class Epi, class Sched, bool ALIGN_EPI = false, bool SP2 = false>
; __device__ __forceinline__ void gemm_phase(PG8_LAS unsigned char* lds, const Gemm g, const Sched& S, const Epi& E) {
;     ...
;             const bool last = (t == nt - 2);
;             const char* a1 = cA + (size_t)(t + 1) * kstep;
;             const char* a2 = last ? nA : cA + (size_t)(t + 2) * kstep; const char* b2 = last ? nB : cB + (size_t)(t + 2) * kstep;
;             const char* a3 = a2 + kstep; const char* b3 = b2 + kstep;
;             if (last && has_next) S.a_ready(nxt);
;             if constexpr (SP2) {
;             PG8_LDB(B0, 0, 0); PG8_LDB(B1, 0, 1); PG8_SCHED; PG8_LDA(At, 0, 0); PG8_STAGE(PG8_SA(1, 1), a1 + hstep, voffA);
;             PG8_WAIT_V(8); PG8_WAIT_L(0); PG8_BAR; PG8_MMA(0, 0, At, B0); PG8_MMA(0, 1, At, B1); PG8_BAR; PG8_SCHED;
;             PG8_LDA(At, 0, 1); PG8_STAGE(PG8_SB(0, 0), b2, voffB); PG8_STAGE(PG8_SB(0, 1), b2 + hstep, voffB); PG8_STAGE(PG8_SA(0, 0), a2, voffA);
.LBB0_872:
	s_add_u32 s36, s34, 0xfff80080
	s_addc_u32 s37, s35, -1
	s_add_i32 s60, 0, 0x10000
	s_cmp_eq_u32 s72, 28
	s_cselect_b32 s39, s23, s37
	s_cselect_b32 s38, s29, s36
	s_cselect_b32 s37, s21, s68
	s_cselect_b32 s36, s66, s67
	s_add_i32 s73, 0, 0x14000
	v_add_u32_e32 v132, s60, v225
	v_add_u32_e32 v156, s73, v225
	ds_read_b128 v[112:115], v132
	ds_read_b128 v[116:119], v132 offset:1024
	ds_read_b128 v[120:123], v132 offset:2048
	ds_read_b128 v[132:135], v132 offset:3072
	ds_read_b128 v[140:143], v156
	ds_read_b128 v[148:151], v156 offset:1024
	ds_read_b128 v[152:155], v156 offset:2048
	ds_read_b128 v[156:159], v156 offset:3072
	v_lshl_add_u64 v[212:213], s[34:35], 0, v[186:187]
	s_add_i32 m0, s2, 0xc000
	ds_read_b128 v[160:163], v227
	ds_read_b128 v[164:167], v227 offset:1024
	ds_read_b128 v[168:171], v227 offset:2048
	ds_read_b128 v[172:175], v227 offset:3072
	ds_read_b128 v[176:179], v227 offset:4096
	ds_read_b128 v[200:203], v227 offset:5120
	ds_read_b128 v[204:207], v227 offset:6144
	ds_read_b128 v[208:211], v227 offset:7168
	global_load_lds_dwordx4 v[212:213], off
	v_lshl_add_u64 v[212:213], s[34:35], 0, v[198:199]
	s_add_i32 m0, s2, 0xe000
	s_nop 0
	global_load_lds_dwordx4 v[212:213], off
	s_nop 0
	s_waitcnt vmcnt(8)
	s_waitcnt lgkmcnt(0)
	s_barrier
	s_setprio 1
	v_mfma_f32_16x16x32_bf16 v[144:147], v[112:115], v[160:163], v[144:147]
	v_mfma_f32_16x16x32_bf16 v[136:139], v[120:123], v[160:163], v[136:139]
	v_mfma_f32_16x16x32_bf16 v[108:111], v[112:115], v[168:171], v[108:111]
	v_mfma_f32_16x16x32_bf16 v[104:107], v[120:123], v[168:171], v[104:107]
	v_mfma_f32_16x16x32_bf16 v[92:95], v[112:115], v[176:179], v[92:95]
	v_mfma_f32_16x16x32_bf16 v[88:91], v[120:123], v[176:179], v[88:91]
	v_mfma_f32_16x16x32_bf16 v[76:79], v[112:115], v[204:207], v[76:79]
	v_mfma_f32_16x16x32_bf16 v[72:75], v[120:123], v[204:207], v[72:75]
	v_mfma_f32_16x16x32_bf16 v[144:147], v[116:119], v[164:167], v[144:147]
	v_mfma_f32_16x16x32_bf16 v[136:139], v[132:135], v[164:167], v[136:139]
	v_mfma_f32_16x16x32_bf16 v[108:111], v[116:119], v[172:175], v[108:111]
	v_mfma_f32_16x16x32_bf16 v[104:107], v[132:135], v[172:175], v[104:107]
	v_mfma_f32_16x16x32_bf16 v[92:95], v[116:119], v[200:203], v[92:95]
	v_mfma_f32_16x16x32_bf16 v[88:91], v[132:135], v[200:203], v[88:91]
	v_mfma_f32_16x16x32_bf16 v[76:79], v[116:119], v[208:211], v[76:79]
	v_mfma_f32_16x16x32_bf16 v[72:75], v[132:135], v[208:211], v[72:75]
	v_mfma_f32_16x16x32_bf16 v[128:131], v[140:143], v[160:163], v[128:131]
	v_mfma_f32_16x16x32_bf16 v[124:127], v[152:155], v[160:163], v[124:127]
	v_mfma_f32_16x16x32_bf16 v[100:103], v[140:143], v[168:171], v[100:103]
	v_mfma_f32_16x16x32_bf16 v[96:99], v[152:155], v[168:171], v[96:99]
	v_mfma_f32_16x16x32_bf16 v[84:87], v[140:143], v[176:179], v[84:87]
	v_mfma_f32_16x16x32_bf16 v[80:83], v[152:155], v[176:179], v[80:83]
	v_mfma_f32_16x16x32_bf16 v[68:71], v[140:143], v[204:207], v[68:71]
	v_mfma_f32_16x16x32_bf16 v[64:67], v[152:155], v[204:207], v[64:67]
	v_mfma_f32_16x16x32_bf16 v[128:131], v[148:151], v[164:167], v[128:131]
	v_mfma_f32_16x16x32_bf16 v[124:127], v[156:159], v[164:167], v[124:127]
	v_mfma_f32_16x16x32_bf16 v[100:103], v[148:151], v[172:175], v[100:103]
	v_mfma_f32_16x16x32_bf16 v[96:99], v[156:159], v[172:175], v[96:99]
	v_mfma_f32_16x16x32_bf16 v[84:87], v[148:151], v[200:203], v[84:87]
	v_mfma_f32_16x16x32_bf16 v[80:83], v[156:159], v[200:203], v[80:83]
	v_mfma_f32_16x16x32_bf16 v[68:71], v[148:151], v[208:211], v[68:71]
	v_mfma_f32_16x16x32_bf16 v[64:67], v[156:159], v[208:211], v[64:67]
	s_setprio 0
	s_barrier
	s_add_i32 s60, s60, s44
	v_lshl_add_u64 v[212:213], s[36:37], 0, v[188:189]
	s_mov_b32 m0, s60
	ds_read_b128 v[160:163], v227 offset:16384
	ds_read_b128 v[164:167], v227 offset:17408
	ds_read_b128 v[168:171], v227 offset:18432
	ds_read_b128 v[172:175], v227 offset:19456
	ds_read_b128 v[176:179], v227 offset:20480
	ds_read_b128 v[200:203], v227 offset:21504
	ds_read_b128 v[204:207], v227 offset:22528
	ds_read_b128 v[208:211], v227 offset:23552
	global_load_lds_dwordx4 v[212:213], off
	s_add_i32 m0, s60, 0x2000
	s_add_u32 s60, s36, 0x80000
	v_lshl_add_u64 v[214:215], s[36:37], 0, v[180:181]
	s_addc_u32 s61, s37, 0
	s_add_i32 s73, s73, s44
	global_load_lds_dwordx4 v[214:215], off
	v_lshl_add_u64 v[216:217], s[60:61], 0, v[188:189]
	s_mov_b32 m0, s73
	v_lshl_add_u64 v[218:219], s[38:39], 0, v[182:183]
	global_load_lds_dwordx4 v[216:217], off
	v_lshl_add_u64 v[216:217], s[60:61], 0, v[180:181]
	s_add_i32 m0, s73, 0x2000
	s_nop 0
	global_load_lds_dwordx4 v[216:217], off
	v_lshl_add_u64 v[216:217], s[38:39], 0, v[184:185]
	s_mov_b32 m0, s2
	s_nop 0
	global_load_lds_dwordx4 v[216:217], off
	s_mov_b32 m0, s31
	s_nop 0
	global_load_lds_dwordx4 v[218:219], off
	s_waitcnt vmcnt(8)
	s_waitcnt lgkmcnt(0)
	s_barrier
; #define PG8_STAGE(bufoff, gbase, voff) do { _Pragma("unroll") for (int _i = 0; _i < 2; ++_i) \
;         __builtin_amdgcn_global_load_lds((const unsigned*)((const char*)(gbase) + (voff)[_i]), (PG8_LAS unsigned*)(lds + (bufoff) + ldsw + _i * 8192), 16, 0, 0); } while (0)
; #define PG8_LDA(dst, b, h) do { _Pragma("unroll") for (int m = 0; m < 4; ++m) _Pragma("unroll") for (int k = 0; k < 2; ++k) dst[m][k] = *(const PG8_LAS bf16x8*)(lds + PG8_SA(b, h) + aoff + m * 2048 + k * 1024); } while (0)
; #define PG8_LDB(dst, b, h) do { _Pragma("unroll") for (int n = 0; n < 2; ++n) _Pragma("unroll") for (int k = 0; k < 2; ++k) dst[n][k] = *(const PG8_LAS bf16x8*)(lds + PG8_SB(b, h) + boff + n * 2048 + k * 1024); } while (0)
; #define PG8_MMA(ai, bj, At, Bt) do { __builtin_amdgcn_s_setprio(1); _Pragma("unroll") for (int m = 0; m < 4; ++m) _Pragma("unroll") for (int n = 0; n < 2; ++n) _Pragma("unroll") for (int k = 0; k < 2; ++k) \
;         acc[ai][bj][m][n] = __builtin_amdgcn_mfma_f32_16x16x32_bf16(Bt[n][k], At[m][k], acc[ai][bj][m][n], 0, 0, 0); __builtin_amdgcn_s_setprio(0); } while (0)
; #define PG8_WAIT_V(n) asm volatile("s_waitcnt vmcnt(" #n ")" ::: "memory")
; #define PG8_WAIT_L(n) asm volatile("s_waitcnt lgkmcnt(" #n ")" ::: "memory")
; #define PG8_BAR __builtin_amdgcn_s_barrier()
; #define PG8_SCHED __builtin_amdgcn_sched_barrier(0)
; template <class Epi, class Sched, bool ALIGN_EPI = false, bool SP2 = false>
; __device__ __forceinline__ void gemm_phase(PG8_LAS unsigned char* lds, const Gemm g, const Sched& S, const Epi& E) {
;     ...
;             PG8_WAIT_V(8); PG8_WAIT_L(0); PG8_BAR; PG8_MMA(1, 0, At, B0); PG8_MMA(1, 1, At, B1); PG8_BAR; PG8_SCHED;
;             PG8_LDB(B0, 1, 0); PG8_LDB(B1, 1, 1); PG8_SCHED; PG8_LDA(At, 1, 0); PG8_STAGE(PG8_SA(0, 1), a2 + hstep, voffA);
;             PG8_WAIT_V(8); PG8_WAIT_L(0); PG8_BAR; PG8_MMA(0, 0, At, B0); PG8_MMA(0, 1, At, B1); PG8_BAR; PG8_SCHED;
	s_setprio 1
	v_mfma_f32_16x16x32_bf16 v[60:63], v[112:115], v[160:163], v[60:63]
	v_mfma_f32_16x16x32_bf16 v[56:59], v[120:123], v[160:163], v[56:59]
	v_mfma_f32_16x16x32_bf16 v[44:47], v[112:115], v[168:171], v[44:47]
	v_mfma_f32_16x16x32_bf16 v[40:43], v[120:123], v[168:171], v[40:43]
	v_mfma_f32_16x16x32_bf16 v[28:31], v[112:115], v[176:179], v[28:31]
	v_mfma_f32_16x16x32_bf16 v[24:27], v[120:123], v[176:179], v[24:27]
	v_mfma_f32_16x16x32_bf16 v[12:15], v[112:115], v[204:207], v[12:15]
	v_mfma_f32_16x16x32_bf16 v[8:11], v[120:123], v[204:207], v[8:11]
	v_mfma_f32_16x16x32_bf16 v[60:63], v[116:119], v[164:167], v[60:63]
	v_mfma_f32_16x16x32_bf16 v[56:59], v[132:135], v[164:167], v[56:59]
	v_mfma_f32_16x16x32_bf16 v[44:47], v[116:119], v[172:175], v[44:47]
	v_mfma_f32_16x16x32_bf16 v[40:43], v[132:135], v[172:175], v[40:43]
	v_mfma_f32_16x16x32_bf16 v[28:31], v[116:119], v[200:203], v[28:31]
	v_mfma_f32_16x16x32_bf16 v[24:27], v[132:135], v[200:203], v[24:27]
	v_mfma_f32_16x16x32_bf16 v[12:15], v[116:119], v[208:211], v[12:15]
	v_mfma_f32_16x16x32_bf16 v[8:11], v[132:135], v[208:211], v[8:11]
	v_mfma_f32_16x16x32_bf16 v[52:55], v[140:143], v[160:163], v[52:55]
	v_mfma_f32_16x16x32_bf16 v[48:51], v[152:155], v[160:163], v[48:51]
	v_mfma_f32_16x16x32_bf16 v[36:39], v[140:143], v[168:171], v[36:39]
	v_mfma_f32_16x16x32_bf16 v[32:35], v[152:155], v[168:171], v[32:35]
	v_mfma_f32_16x16x32_bf16 v[20:23], v[140:143], v[176:179], v[20:23]
	v_mfma_f32_16x16x32_bf16 v[16:19], v[152:155], v[176:179], v[16:19]
	v_mfma_f32_16x16x32_bf16 v[4:7], v[140:143], v[204:207], v[4:7]
	v_mfma_f32_16x16x32_bf16 v[0:3], v[152:155], v[204:207], v[0:3]
	v_mfma_f32_16x16x32_bf16 v[52:55], v[148:151], v[164:167], v[52:55]
	v_mfma_f32_16x16x32_bf16 v[48:51], v[156:159], v[164:167], v[48:51]
	v_mfma_f32_16x16x32_bf16 v[36:39], v[148:151], v[172:175], v[36:39]
	v_mfma_f32_16x16x32_bf16 v[32:35], v[156:159], v[172:175], v[32:35]
	v_mfma_f32_16x16x32_bf16 v[20:23], v[148:151], v[200:203], v[20:23]
	v_mfma_f32_16x16x32_bf16 v[16:19], v[156:159], v[200:203], v[16:19]
	v_mfma_f32_16x16x32_bf16 v[4:7], v[148:151], v[208:211], v[4:7]
	v_mfma_f32_16x16x32_bf16 v[0:3], v[156:159], v[208:211], v[0:3]
	s_setprio 0
	s_barrier
	s_add_i32 s60, 0, 0x18000
	s_add_i32 s61, 0, 0x1c000
	v_add_u32_e32 v132, s60, v225
	v_add_u32_e32 v156, s61, v225
	ds_read_b128 v[112:115], v132
	ds_read_b128 v[116:119], v132 offset:1024
	ds_read_b128 v[120:123], v132 offset:2048
	ds_read_b128 v[132:135], v132 offset:3072
	ds_read_b128 v[140:143], v156
	ds_read_b128 v[148:151], v156 offset:1024
	ds_read_b128 v[152:155], v156 offset:2048
	ds_read_b128 v[156:159], v156 offset:3072
	s_add_u32 s38, s38, 0x80000
	s_addc_u32 s39, s39, 0
	s_mov_b32 m0, s45
	v_lshl_add_u64 v[220:221], s[38:39], 0, v[184:185]
	ds_read_b128 v[160:163], v227 offset:32768
	ds_read_b128 v[164:167], v227 offset:33792
	ds_read_b128 v[168:171], v227 offset:34816
	ds_read_b128 v[172:175], v227 offset:35840
	ds_read_b128 v[176:179], v227 offset:36864
	ds_read_b128 v[200:203], v227 offset:37888
	ds_read_b128 v[204:207], v227 offset:38912
	ds_read_b128 v[208:211], v227 offset:39936
	global_load_lds_dwordx4 v[220:221], off
	v_lshl_add_u64 v[220:221], s[38:39], 0, v[182:183]
	s_mov_b32 m0, s52
	s_nop 0
	global_load_lds_dwordx4 v[220:221], off
	s_waitcnt vmcnt(8)
	s_waitcnt lgkmcnt(0)
	s_barrier
	s_setprio 1
	v_mfma_f32_16x16x32_bf16 v[144:147], v[112:115], v[160:163], v[144:147]
	v_mfma_f32_16x16x32_bf16 v[136:139], v[120:123], v[160:163], v[136:139]
	v_mfma_f32_16x16x32_bf16 v[108:111], v[112:115], v[168:171], v[108:111]
	v_mfma_f32_16x16x32_bf16 v[104:107], v[120:123], v[168:171], v[104:107]
	v_mfma_f32_16x16x32_bf16 v[92:95], v[112:115], v[176:179], v[92:95]
	v_mfma_f32_16x16x32_bf16 v[88:91], v[120:123], v[176:179], v[88:91]
	v_mfma_f32_16x16x32_bf16 v[76:79], v[112:115], v[204:207], v[76:79]
	v_mfma_f32_16x16x32_bf16 v[72:75], v[120:123], v[204:207], v[72:75]
	v_mfma_f32_16x16x32_bf16 v[144:147], v[116:119], v[164:167], v[144:147]
	v_mfma_f32_16x16x32_bf16 v[136:139], v[132:135], v[164:167], v[136:139]
	v_mfma_f32_16x16x32_bf16 v[108:111], v[116:119], v[172:175], v[108:111]
	v_mfma_f32_16x16x32_bf16 v[104:107], v[132:135], v[172:175], v[104:107]
	v_mfma_f32_16x16x32_bf16 v[92:95], v[116:119], v[200:203], v[92:95]
	v_mfma_f32_16x16x32_bf16 v[88:91], v[132:135], v[200:203], v[88:91]
	v_mfma_f32_16x16x32_bf16 v[76:79], v[116:119], v[208:211], v[76:79]
	v_mfma_f32_16x16x32_bf16 v[72:75], v[132:135], v[208:211], v[72:75]
	v_mfma_f32_16x16x32_bf16 v[128:131], v[140:143], v[160:163], v[128:131]
	v_mfma_f32_16x16x32_bf16 v[124:127], v[152:155], v[160:163], v[124:127]
	v_mfma_f32_16x16x32_bf16 v[100:103], v[140:143], v[168:171], v[100:103]
	v_mfma_f32_16x16x32_bf16 v[96:99], v[152:155], v[168:171], v[96:99]
	v_mfma_f32_16x16x32_bf16 v[84:87], v[140:143], v[176:179], v[84:87]
	v_mfma_f32_16x16x32_bf16 v[80:83], v[152:155], v[176:179], v[80:83]
	v_mfma_f32_16x16x32_bf16 v[68:71], v[140:143], v[204:207], v[68:71]
	v_mfma_f32_16x16x32_bf16 v[64:67], v[152:155], v[204:207], v[64:67]
	v_mfma_f32_16x16x32_bf16 v[128:131], v[148:151], v[164:167], v[128:131]
	v_mfma_f32_16x16x32_bf16 v[124:127], v[156:159], v[164:167], v[124:127]
	v_mfma_f32_16x16x32_bf16 v[100:103], v[148:151], v[172:175], v[100:103]
	v_mfma_f32_16x16x32_bf16 v[96:99], v[156:159], v[172:175], v[96:99]
	v_mfma_f32_16x16x32_bf16 v[84:87], v[148:151], v[200:203], v[84:87]
	v_mfma_f32_16x16x32_bf16 v[80:83], v[156:159], v[200:203], v[80:83]
	v_mfma_f32_16x16x32_bf16 v[68:71], v[148:151], v[208:211], v[68:71]
	v_mfma_f32_16x16x32_bf16 v[64:67], v[156:159], v[208:211], v[64:67]
	s_setprio 0
	s_barrier
; #define PG8_STAGE(bufoff, gbase, voff) do { _Pragma("unroll") for (int _i = 0; _i < 2; ++_i) \
;         __builtin_amdgcn_global_load_lds((const unsigned*)((const char*)(gbase) + (voff)[_i]), (PG8_LAS unsigned*)(lds + (bufoff) + ldsw + _i * 8192), 16, 0, 0); } while (0)
; #define PG8_LDA(dst, b, h) do { _Pragma("unroll") for (int m = 0; m < 4; ++m) _Pragma("unroll") for (int k = 0; k < 2; ++k) dst[m][k] = *(const PG8_LAS bf16x8*)(lds + PG8_SA(b, h) + aoff + m * 2048 + k * 1024); } while (0)
; #define PG8_MMA(ai, bj, At, Bt) do { __builtin_amdgcn_s_setprio(1); _Pragma("unroll") for (int m = 0; m < 4; ++m) _Pragma("unroll") for (int n = 0; n < 2; ++n) _Pragma("unroll") for (int k = 0; k < 2; ++k) \
;         acc[ai][bj][m][n] = __builtin_amdgcn_mfma_f32_16x16x32_bf16(Bt[n][k], At[m][k], acc[ai][bj][m][n], 0, 0, 0); __builtin_amdgcn_s_setprio(0); } while (0)
; #define PG8_WAIT_V(n) asm volatile("s_waitcnt vmcnt(" #n ")" ::: "memory")
; #define PG8_WAIT_L(n) asm volatile("s_waitcnt lgkmcnt(" #n ")" ::: "memory")
; #define PG8_BAR __builtin_amdgcn_s_barrier()
; #define PG8_SCHED __builtin_amdgcn_sched_barrier(0)
; template <class Epi, class Sched, bool ALIGN_EPI = false, bool SP2 = false>
; __device__ __forceinline__ void gemm_phase(PG8_LAS unsigned char* lds, const Gemm g, const Sched& S, const Epi& E) {
;     ...
;             PG8_LDA(At, 1, 1); PG8_STAGE(PG8_SB(1, 0), b3, voffB); PG8_STAGE(PG8_SB(1, 1), b3 + hstep, voffB); PG8_STAGE(PG8_SA(1, 0), a3, voffA);
;             PG8_WAIT_V(8); PG8_WAIT_L(0); PG8_BAR; PG8_MMA(1, 0, At, B0); PG8_MMA(1, 1, At, B1); PG8_BAR; PG8_SCHED;
	s_add_i32 s38, s60, s44
	v_lshl_add_u64 v[212:213], v[212:213], 0, s[78:79]
	s_mov_b32 m0, s38
	ds_read_b128 v[160:163], v227 offset:49152
	ds_read_b128 v[164:167], v227 offset:50176
	ds_read_b128 v[168:171], v227 offset:51200
	ds_read_b128 v[172:175], v227 offset:52224
	ds_read_b128 v[176:179], v227 offset:53248
	ds_read_b128 v[200:203], v227 offset:54272
	ds_read_b128 v[204:207], v227 offset:55296
	ds_read_b128 v[208:211], v227 offset:56320
	global_load_lds_dwordx4 v[212:213], off
	s_add_i32 m0, s38, 0x2000
	s_add_u32 s36, s36, 0x80080
	v_lshl_add_u64 v[212:213], v[214:215], 0, s[78:79]
	s_addc_u32 s37, s37, 0
	s_add_i32 s38, s61, s44
	global_load_lds_dwordx4 v[212:213], off
	v_lshl_add_u64 v[212:213], s[36:37], 0, v[188:189]
	s_mov_b32 m0, s38
	s_nop 0
	global_load_lds_dwordx4 v[212:213], off
	v_lshl_add_u64 v[212:213], s[36:37], 0, v[180:181]
	s_add_i32 m0, s38, 0x2000
	s_nop 0
	global_load_lds_dwordx4 v[212:213], off
	v_lshl_add_u64 v[212:213], v[216:217], 0, s[78:79]
	s_mov_b32 m0, s58
	s_nop 0
	global_load_lds_dwordx4 v[212:213], off
	v_lshl_add_u64 v[212:213], v[218:219], 0, s[78:79]
	s_mov_b32 m0, s62
	s_nop 0
	global_load_lds_dwordx4 v[212:213], off
	s_nop 0
	s_waitcnt vmcnt(8)
	s_waitcnt lgkmcnt(0)
	s_barrier
	s_setprio 1
	v_mfma_f32_16x16x32_bf16 v[60:63], v[112:115], v[160:163], v[60:63]
	v_mfma_f32_16x16x32_bf16 v[56:59], v[120:123], v[160:163], v[56:59]
	v_mfma_f32_16x16x32_bf16 v[44:47], v[112:115], v[168:171], v[44:47]
	v_mfma_f32_16x16x32_bf16 v[40:43], v[120:123], v[168:171], v[40:43]
	v_mfma_f32_16x16x32_bf16 v[28:31], v[112:115], v[176:179], v[28:31]
	v_mfma_f32_16x16x32_bf16 v[24:27], v[120:123], v[176:179], v[24:27]
	v_mfma_f32_16x16x32_bf16 v[12:15], v[112:115], v[204:207], v[12:15]
	v_mfma_f32_16x16x32_bf16 v[8:11], v[120:123], v[204:207], v[8:11]
	v_mfma_f32_16x16x32_bf16 v[60:63], v[116:119], v[164:167], v[60:63]
	v_mfma_f32_16x16x32_bf16 v[56:59], v[132:135], v[164:167], v[56:59]
	v_mfma_f32_16x16x32_bf16 v[44:47], v[116:119], v[172:175], v[44:47]
	v_mfma_f32_16x16x32_bf16 v[40:43], v[132:135], v[172:175], v[40:43]
	v_mfma_f32_16x16x32_bf16 v[28:31], v[116:119], v[200:203], v[28:31]
	v_mfma_f32_16x16x32_bf16 v[24:27], v[132:135], v[200:203], v[24:27]
	v_mfma_f32_16x16x32_bf16 v[12:15], v[116:119], v[208:211], v[12:15]
	v_mfma_f32_16x16x32_bf16 v[8:11], v[132:135], v[208:211], v[8:11]
	v_mfma_f32_16x16x32_bf16 v[52:55], v[140:143], v[160:163], v[52:55]
	v_mfma_f32_16x16x32_bf16 v[48:51], v[152:155], v[160:163], v[48:51]
	v_mfma_f32_16x16x32_bf16 v[36:39], v[140:143], v[168:171], v[36:39]
	v_mfma_f32_16x16x32_bf16 v[32:35], v[152:155], v[168:171], v[32:35]
	v_mfma_f32_16x16x32_bf16 v[20:23], v[140:143], v[176:179], v[20:23]
	v_mfma_f32_16x16x32_bf16 v[16:19], v[152:155], v[176:179], v[16:19]
	v_mfma_f32_16x16x32_bf16 v[4:7], v[140:143], v[204:207], v[4:7]
	v_mfma_f32_16x16x32_bf16 v[0:3], v[152:155], v[204:207], v[0:3]
	v_mfma_f32_16x16x32_bf16 v[52:55], v[148:151], v[164:167], v[52:55]
	v_mfma_f32_16x16x32_bf16 v[48:51], v[156:159], v[164:167], v[48:51]
	v_mfma_f32_16x16x32_bf16 v[36:39], v[148:151], v[172:175], v[36:39]
	v_mfma_f32_16x16x32_bf16 v[32:35], v[156:159], v[172:175], v[32:35]
	v_mfma_f32_16x16x32_bf16 v[20:23], v[148:151], v[200:203], v[20:23]
	v_mfma_f32_16x16x32_bf16 v[16:19], v[156:159], v[200:203], v[16:19]
	v_mfma_f32_16x16x32_bf16 v[4:7], v[148:151], v[208:211], v[4:7]
	v_mfma_f32_16x16x32_bf16 v[0:3], v[156:159], v[208:211], v[0:3]
	s_setprio 0
	s_barrier
	s_add_i32 s72, s72, 2
	s_add_u32 s34, s34, 0x100
	s_addc_u32 s35, s35, 0
	s_add_u32 s67, s67, 0x100
	s_addc_u32 s68, s68, 0
	s_cmp_gt_u32 s72, 29
	s_cbranch_scc0 .LBB0_872
	v_mov_b32_e32 v196, 0x2000
	s_and_b64 vcc, exec, s[18:19]
	s_cbranch_vccz .LBB0_875
	s_barrier
